# first 2 MFMAs of every MMA segment issued in front of its opening barrier (fills the matrix pipe across the hand-over); on top of v24
# baseline (speedup 1.0000x reference)
; #define PG8_STAGE(bufoff, gbase, voff) do { _Pragma("unroll") for (int _i = 0; _i < 2; ++_i) \
;         __builtin_amdgcn_global_load_lds((const unsigned*)((const char*)(gbase) + (voff)[_i]), (PG8_LAS unsigned*)(lds + (bufoff) + ldsw + _i * 8192), 16, 0, 0); } while (0)
; #define PG8_LDA(dst, b, h) do { _Pragma("unroll") for (int m = 0; m < 4; ++m) _Pragma("unroll") for (int k = 0; k < 2; ++k) dst[m][k] = *(const PG8_LAS bf16x8*)(lds + PG8_SA(b, h) + aoff + m * 2048 + k * 1024); } while (0)
; #define PG8_LDB(dst, b, h) do { _Pragma("unroll") for (int n = 0; n < 2; ++n) _Pragma("unroll") for (int k = 0; k < 2; ++k) dst[n][k] = *(const PG8_LAS bf16x8*)(lds + PG8_SB(b, h) + boff + n * 2048 + k * 1024); } while (0)
; #define PG8_MMA(ai, bj, At, Bt) do { __builtin_amdgcn_s_setprio(1); _Pragma("unroll") for (int m = 0; m < 4; ++m) _Pragma("unroll") for (int n = 0; n < 2; ++n) _Pragma("unroll") for (int k = 0; k < 2; ++k) \
;         acc[ai][bj][m][n] = __builtin_amdgcn_mfma_f32_16x16x32_bf16(Bt[n][k], At[m][k], acc[ai][bj][m][n], 0, 0, 0); __builtin_amdgcn_s_setprio(0); } while (0)
; #define PG8_WAIT_V(n) asm volatile("s_waitcnt vmcnt(" #n ")" ::: "memory")
; template <class Epi, class Sched, bool ALIGN_EPI = false, bool SP2 = false>
; __device__ __forceinline__ void gemm_phase(PG8_LAS unsigned char* lds, const Gemm g, const Sched& S, const Epi& E) {
;     ...
;         const char* nA = has_next ? (const char*)g.A + (size_t)nxt.pm * tstep : cA; const char* nB = has_next ? (const char*)g.Bt + (size_t)nxt.pn * tstep : cB;
;         for (int t = 0; t < nt; t += 2) {
;             const bool last = (t == nt - 2);
;             const char* a1 = cA + (size_t)(t + 1) * kstep;
;             const char* a2 = last ? nA : cA + (size_t)(t + 2) * kstep; const char* b2 = last ? nB : cB + (size_t)(t + 2) * kstep;
;             const char* a3 = a2 + kstep; const char* b3 = b2 + kstep;
;             if (last && has_next) S.a_ready(nxt);
;             if constexpr (SP2) {
;             PG8_LDB(B0, 0, 0); PG8_LDB(B1, 0, 1); PG8_SCHED; PG8_LDA(At, 0, 0); PG8_STAGE(PG8_SA(1, 1), a1 + hstep, voffA);
;             PG8_WAIT_V(8); PG8_WAIT_L(0); PG8_BAR; PG8_MMA(0, 0, At, B0); PG8_MMA(0, 1, At, B1); PG8_BAR; PG8_SCHED;
;             PG8_LDA(At, 0, 1); PG8_STAGE(PG8_SB(0, 0), b2, voffB); PG8_STAGE(PG8_SB(0, 1), b2 + hstep, voffB); PG8_STAGE(PG8_SA(0, 0), a2, voffA);
.LBB0_224:
	s_ashr_i32 s15, s14, 31
	s_lshl_b64 s[16:17], s[14:15], 19
	s_add_u32 s16, s34, s16
	s_addc_u32 s17, s35, s17
	s_and_b64 s[18:19], s[2:3], exec
	s_cselect_b32 s5, s17, s23
	s_cselect_b32 s15, s16, s22
	s_ashr_i32 s13, s12, 31
	s_lshl_b64 s[18:19], s[12:13], 19
	s_add_u32 s18, s38, s18
	s_addc_u32 s19, s39, s19
	s_and_b64 s[26:27], s[2:3], exec
	s_cselect_b32 s13, s19, s25
	s_cselect_b32 s21, s18, s24
	s_add_u32 s22, s22, 0x40080
	s_addc_u32 s23, s23, 0
	s_add_u32 s49, s24, 0x100
	s_addc_u32 s50, s25, 0
	s_mov_b32 s51, -2
	s_add_u32 s24, s22, 0xfffc0080
	s_addc_u32 s25, s23, -1
	s_add_i32 s52, 0, 0x10000
	s_cmp_eq_u32 s51, 12
	s_cselect_b32 s27, s5, s25
	s_cselect_b32 s26, s15, s24
	v_add_u32_e32 v138, s52, v149
	s_cselect_b32 s25, s13, s50
	s_cselect_b32 s24, s21, s49
	s_add_i32 s55, 0, 0x14000
	ds_read_b128 v[144:147], v138
	ds_read_b128 v[154:157], v138 offset:1024
	ds_read_b128 v[158:161], v138 offset:2048
	ds_read_b128 v[162:165], v138 offset:3072
	v_add_u32_e32 v138, s55, v149
	ds_read_b128 v[166:169], v138
	ds_read_b128 v[170:173], v138 offset:1024
	ds_read_b128 v[174:177], v138 offset:2048
	ds_read_b128 v[178:181], v138 offset:3072
	v_lshl_add_u64 v[138:139], s[22:23], 0, v[136:137]
	s_add_i32 m0, s41, 0xc000
	ds_read_b128 v[182:185], v152
	ds_read_b128 v[186:189], v152 offset:1024
	ds_read_b128 v[190:193], v152 offset:2048
	ds_read_b128 v[194:197], v152 offset:3072
	ds_read_b128 v[198:201], v152 offset:4096
	ds_read_b128 v[202:205], v152 offset:5120
	ds_read_b128 v[224:227], v152 offset:6144
	ds_read_b128 v[228:231], v152 offset:7168
	global_load_lds_dwordx4 v[138:139], off
	v_lshl_add_u64 v[138:139], s[22:23], 0, v[142:143]
	s_add_i32 m0, s41, 0xe000
	s_nop 0
	global_load_lds_dwordx4 v[138:139], off
	s_waitcnt vmcnt(8)
	s_waitcnt lgkmcnt(0)
	v_mfma_f32_16x16x32_bf16 v[126:129], v[144:147], v[182:185], 0
	v_mfma_f32_16x16x32_bf16 v[122:125], v[158:161], v[182:185], 0
	s_setprio 1
	s_barrier
	v_mfma_f32_16x16x32_bf16 v[110:113], v[144:147], v[190:193], 0
	v_mfma_f32_16x16x32_bf16 v[106:109], v[158:161], v[190:193], 0
	v_mfma_f32_16x16x32_bf16 v[94:97], v[144:147], v[198:201], 0
	v_mfma_f32_16x16x32_bf16 v[90:93], v[158:161], v[198:201], 0
	v_mfma_f32_16x16x32_bf16 v[78:81], v[144:147], v[224:227], 0
	v_mfma_f32_16x16x32_bf16 v[74:77], v[158:161], v[224:227], 0
	v_mfma_f32_16x16x32_bf16 v[126:129], v[154:157], v[186:189], v[126:129]
	v_mfma_f32_16x16x32_bf16 v[122:125], v[162:165], v[186:189], v[122:125]
	v_mfma_f32_16x16x32_bf16 v[110:113], v[154:157], v[194:197], v[110:113]
	v_mfma_f32_16x16x32_bf16 v[106:109], v[162:165], v[194:197], v[106:109]
	v_mfma_f32_16x16x32_bf16 v[94:97], v[154:157], v[202:205], v[94:97]
	v_mfma_f32_16x16x32_bf16 v[90:93], v[162:165], v[202:205], v[90:93]
	v_mfma_f32_16x16x32_bf16 v[78:81], v[154:157], v[228:231], v[78:81]
	v_mfma_f32_16x16x32_bf16 v[74:77], v[162:165], v[228:231], v[74:77]
	v_mfma_f32_16x16x32_bf16 v[118:121], v[166:169], v[182:185], 0
	v_mfma_f32_16x16x32_bf16 v[114:117], v[174:177], v[182:185], 0
	v_mfma_f32_16x16x32_bf16 v[102:105], v[166:169], v[190:193], 0
	v_mfma_f32_16x16x32_bf16 v[98:101], v[174:177], v[190:193], 0
	v_mfma_f32_16x16x32_bf16 v[86:89], v[166:169], v[198:201], 0
	v_mfma_f32_16x16x32_bf16 v[82:85], v[174:177], v[198:201], 0
	v_mfma_f32_16x16x32_bf16 v[70:73], v[166:169], v[224:227], 0
	v_mfma_f32_16x16x32_bf16 v[66:69], v[174:177], v[224:227], 0
	v_mfma_f32_16x16x32_bf16 v[118:121], v[170:173], v[186:189], v[118:121]
	v_mfma_f32_16x16x32_bf16 v[114:117], v[178:181], v[186:189], v[114:117]
	v_mfma_f32_16x16x32_bf16 v[102:105], v[170:173], v[194:197], v[102:105]
	v_mfma_f32_16x16x32_bf16 v[98:101], v[178:181], v[194:197], v[98:101]
	v_mfma_f32_16x16x32_bf16 v[86:89], v[170:173], v[202:205], v[86:89]
	v_mfma_f32_16x16x32_bf16 v[82:85], v[178:181], v[202:205], v[82:85]
	v_mfma_f32_16x16x32_bf16 v[70:73], v[170:173], v[228:231], v[70:73]
	v_mfma_f32_16x16x32_bf16 v[66:69], v[178:181], v[228:231], v[66:69]
	s_barrier
	s_setprio 0
	s_add_i32 s52, s52, s31
	v_lshl_add_u64 v[138:139], s[24:25], 0, v[0:1]
	s_mov_b32 m0, s52
	ds_read_b128 v[182:185], v152 offset:16384
	ds_read_b128 v[186:189], v152 offset:17408
	ds_read_b128 v[190:193], v152 offset:18432
	ds_read_b128 v[194:197], v152 offset:19456
	ds_read_b128 v[198:201], v152 offset:20480
	ds_read_b128 v[202:205], v152 offset:21504
	ds_read_b128 v[224:227], v152 offset:22528
	ds_read_b128 v[228:231], v152 offset:23552
	global_load_lds_dwordx4 v[138:139], off
	s_add_i32 m0, s52, 0x2000
	s_add_u32 s52, s24, 0x40000
	v_lshl_add_u64 v[140:141], s[24:25], 0, v[134:135]
	s_addc_u32 s53, s25, 0
	s_add_i32 s55, s55, s31
	global_load_lds_dwordx4 v[140:141], off
	v_lshl_add_u64 v[232:233], s[52:53], 0, v[0:1]
	s_mov_b32 m0, s55
	v_lshl_add_u64 v[234:235], s[26:27], 0, v[132:133]
	global_load_lds_dwordx4 v[232:233], off
	v_lshl_add_u64 v[232:233], s[52:53], 0, v[134:135]
	s_add_i32 m0, s55, 0x2000
	s_nop 0
	global_load_lds_dwordx4 v[232:233], off
	v_lshl_add_u64 v[232:233], s[26:27], 0, v[130:131]
	s_mov_b32 m0, s41
	s_nop 0
	global_load_lds_dwordx4 v[232:233], off
	s_mov_b32 m0, s42
	s_nop 0
	global_load_lds_dwordx4 v[234:235], off
	s_waitcnt vmcnt(8)
	s_waitcnt lgkmcnt(0)
	v_mfma_f32_16x16x32_bf16 v[62:65], v[144:147], v[182:185], 0
	v_mfma_f32_16x16x32_bf16 v[58:61], v[158:161], v[182:185], 0
	s_setprio 1
	s_barrier
; #define PG8_STAGE(bufoff, gbase, voff) do { _Pragma("unroll") for (int _i = 0; _i < 2; ++_i) \
;         __builtin_amdgcn_global_load_lds((const unsigned*)((const char*)(gbase) + (voff)[_i]), (PG8_LAS unsigned*)(lds + (bufoff) + ldsw + _i * 8192), 16, 0, 0); } while (0)
; #define PG8_LDA(dst, b, h) do { _Pragma("unroll") for (int m = 0; m < 4; ++m) _Pragma("unroll") for (int k = 0; k < 2; ++k) dst[m][k] = *(const PG8_LAS bf16x8*)(lds + PG8_SA(b, h) + aoff + m * 2048 + k * 1024); } while (0)
; #define PG8_LDB(dst, b, h) do { _Pragma("unroll") for (int n = 0; n < 2; ++n) _Pragma("unroll") for (int k = 0; k < 2; ++k) dst[n][k] = *(const PG8_LAS bf16x8*)(lds + PG8_SB(b, h) + boff + n * 2048 + k * 1024); } while (0)
; #define PG8_MMA(ai, bj, At, Bt) do { __builtin_amdgcn_s_setprio(1); _Pragma("unroll") for (int m = 0; m < 4; ++m) _Pragma("unroll") for (int n = 0; n < 2; ++n) _Pragma("unroll") for (int k = 0; k < 2; ++k) \
;         acc[ai][bj][m][n] = __builtin_amdgcn_mfma_f32_16x16x32_bf16(Bt[n][k], At[m][k], acc[ai][bj][m][n], 0, 0, 0); __builtin_amdgcn_s_setprio(0); } while (0)
; #define PG8_WAIT_V(n) asm volatile("s_waitcnt vmcnt(" #n ")" ::: "memory")
; #define PG8_WAIT_L(n) asm volatile("s_waitcnt lgkmcnt(" #n ")" ::: "memory")
; #define PG8_BAR __builtin_amdgcn_s_barrier()
; #define PG8_SCHED __builtin_amdgcn_sched_barrier(0)
; template <class Epi, class Sched, bool ALIGN_EPI = false, bool SP2 = false>
; __device__ __forceinline__ void gemm_phase(PG8_LAS unsigned char* lds, const Gemm g, const Sched& S, const Epi& E) {
;     ...
;             PG8_WAIT_V(8); PG8_WAIT_L(0); PG8_BAR; PG8_MMA(1, 0, At, B0); PG8_MMA(1, 1, At, B1); PG8_BAR; PG8_SCHED;
;             PG8_LDB(B0, 1, 0); PG8_LDB(B1, 1, 1); PG8_SCHED; PG8_LDA(At, 1, 0); PG8_STAGE(PG8_SA(0, 1), a2 + hstep, voffA);
;             PG8_WAIT_V(8); PG8_WAIT_L(0); PG8_BAR; PG8_MMA(0, 0, At, B0); PG8_MMA(0, 1, At, B1); PG8_BAR; PG8_SCHED;
	v_mfma_f32_16x16x32_bf16 v[46:49], v[144:147], v[190:193], 0
	v_mfma_f32_16x16x32_bf16 v[42:45], v[158:161], v[190:193], 0
	v_mfma_f32_16x16x32_bf16 v[30:33], v[144:147], v[198:201], 0
	v_mfma_f32_16x16x32_bf16 v[26:29], v[158:161], v[198:201], 0
	v_mfma_f32_16x16x32_bf16 v[14:17], v[144:147], v[224:227], 0
	v_mfma_f32_16x16x32_bf16 v[10:13], v[158:161], v[224:227], 0
	v_mfma_f32_16x16x32_bf16 v[62:65], v[154:157], v[186:189], v[62:65]
	v_mfma_f32_16x16x32_bf16 v[58:61], v[162:165], v[186:189], v[58:61]
	v_mfma_f32_16x16x32_bf16 v[46:49], v[154:157], v[194:197], v[46:49]
	v_mfma_f32_16x16x32_bf16 v[42:45], v[162:165], v[194:197], v[42:45]
	v_mfma_f32_16x16x32_bf16 v[30:33], v[154:157], v[202:205], v[30:33]
	v_mfma_f32_16x16x32_bf16 v[26:29], v[162:165], v[202:205], v[26:29]
	v_mfma_f32_16x16x32_bf16 v[14:17], v[154:157], v[228:231], v[14:17]
	v_mfma_f32_16x16x32_bf16 v[10:13], v[162:165], v[228:231], v[10:13]
	v_mfma_f32_16x16x32_bf16 v[54:57], v[166:169], v[182:185], 0
	v_mfma_f32_16x16x32_bf16 v[50:53], v[174:177], v[182:185], 0
	v_mfma_f32_16x16x32_bf16 v[38:41], v[166:169], v[190:193], 0
	v_mfma_f32_16x16x32_bf16 v[34:37], v[174:177], v[190:193], 0
	v_mfma_f32_16x16x32_bf16 v[22:25], v[166:169], v[198:201], 0
	v_mfma_f32_16x16x32_bf16 v[18:21], v[174:177], v[198:201], 0
	v_mfma_f32_16x16x32_bf16 v[6:9], v[166:169], v[224:227], 0
	v_mfma_f32_16x16x32_bf16 v[2:5], v[174:177], v[224:227], 0
	v_mfma_f32_16x16x32_bf16 v[54:57], v[170:173], v[186:189], v[54:57]
	v_mfma_f32_16x16x32_bf16 v[50:53], v[178:181], v[186:189], v[50:53]
	v_mfma_f32_16x16x32_bf16 v[38:41], v[170:173], v[194:197], v[38:41]
	v_mfma_f32_16x16x32_bf16 v[34:37], v[178:181], v[194:197], v[34:37]
	v_mfma_f32_16x16x32_bf16 v[22:25], v[170:173], v[202:205], v[22:25]
	v_mfma_f32_16x16x32_bf16 v[18:21], v[178:181], v[202:205], v[18:21]
	v_mfma_f32_16x16x32_bf16 v[6:9], v[170:173], v[228:231], v[6:9]
	v_mfma_f32_16x16x32_bf16 v[2:5], v[178:181], v[228:231], v[2:5]
	s_barrier
	s_setprio 0
	s_add_i32 s52, 0, 0x18000
	v_add_u32_e32 v153, s52, v149
	s_add_i32 s53, 0, 0x1c000
	ds_read_b128 v[144:147], v153
	ds_read_b128 v[154:157], v153 offset:1024
	ds_read_b128 v[158:161], v153 offset:2048
	ds_read_b128 v[162:165], v153 offset:3072
	v_add_u32_e32 v153, s53, v149
	ds_read_b128 v[166:169], v153
	ds_read_b128 v[170:173], v153 offset:1024
	ds_read_b128 v[174:177], v153 offset:2048
	ds_read_b128 v[178:181], v153 offset:3072
	s_add_u32 s26, s26, 0x40000
	s_addc_u32 s27, s27, 0
	s_mov_b32 m0, s43
	v_lshl_add_u64 v[236:237], s[26:27], 0, v[130:131]
	ds_read_b128 v[182:185], v152 offset:32768
	ds_read_b128 v[186:189], v152 offset:33792
	ds_read_b128 v[190:193], v152 offset:34816
	ds_read_b128 v[194:197], v152 offset:35840
	ds_read_b128 v[198:201], v152 offset:36864
	ds_read_b128 v[202:205], v152 offset:37888
	ds_read_b128 v[224:227], v152 offset:38912
	ds_read_b128 v[228:231], v152 offset:39936
	global_load_lds_dwordx4 v[236:237], off
	v_lshl_add_u64 v[236:237], s[26:27], 0, v[132:133]
	s_mov_b32 m0, s44
	s_nop 0
	global_load_lds_dwordx4 v[236:237], off
	s_waitcnt vmcnt(8)
	s_waitcnt lgkmcnt(0)
	v_mfma_f32_16x16x32_bf16 v[126:129], v[144:147], v[182:185], v[126:129]
	v_mfma_f32_16x16x32_bf16 v[122:125], v[158:161], v[182:185], v[122:125]
	s_setprio 1
	s_barrier
	v_mfma_f32_16x16x32_bf16 v[110:113], v[144:147], v[190:193], v[110:113]
	v_mfma_f32_16x16x32_bf16 v[106:109], v[158:161], v[190:193], v[106:109]
	v_mfma_f32_16x16x32_bf16 v[94:97], v[144:147], v[198:201], v[94:97]
	v_mfma_f32_16x16x32_bf16 v[90:93], v[158:161], v[198:201], v[90:93]
	v_mfma_f32_16x16x32_bf16 v[78:81], v[144:147], v[224:227], v[78:81]
	v_mfma_f32_16x16x32_bf16 v[74:77], v[158:161], v[224:227], v[74:77]
	v_mfma_f32_16x16x32_bf16 v[126:129], v[154:157], v[186:189], v[126:129]
	v_mfma_f32_16x16x32_bf16 v[122:125], v[162:165], v[186:189], v[122:125]
	v_mfma_f32_16x16x32_bf16 v[110:113], v[154:157], v[194:197], v[110:113]
	v_mfma_f32_16x16x32_bf16 v[106:109], v[162:165], v[194:197], v[106:109]
	v_mfma_f32_16x16x32_bf16 v[94:97], v[154:157], v[202:205], v[94:97]
	v_mfma_f32_16x16x32_bf16 v[90:93], v[162:165], v[202:205], v[90:93]
	v_mfma_f32_16x16x32_bf16 v[78:81], v[154:157], v[228:231], v[78:81]
	v_mfma_f32_16x16x32_bf16 v[74:77], v[162:165], v[228:231], v[74:77]
	v_mfma_f32_16x16x32_bf16 v[118:121], v[166:169], v[182:185], v[118:121]
	v_mfma_f32_16x16x32_bf16 v[114:117], v[174:177], v[182:185], v[114:117]
	v_mfma_f32_16x16x32_bf16 v[102:105], v[166:169], v[190:193], v[102:105]
	v_mfma_f32_16x16x32_bf16 v[98:101], v[174:177], v[190:193], v[98:101]
	v_mfma_f32_16x16x32_bf16 v[86:89], v[166:169], v[198:201], v[86:89]
	v_mfma_f32_16x16x32_bf16 v[82:85], v[174:177], v[198:201], v[82:85]
	v_mfma_f32_16x16x32_bf16 v[70:73], v[166:169], v[224:227], v[70:73]
	v_mfma_f32_16x16x32_bf16 v[66:69], v[174:177], v[224:227], v[66:69]
	v_mfma_f32_16x16x32_bf16 v[118:121], v[170:173], v[186:189], v[118:121]
	v_mfma_f32_16x16x32_bf16 v[114:117], v[178:181], v[186:189], v[114:117]
	v_mfma_f32_16x16x32_bf16 v[102:105], v[170:173], v[194:197], v[102:105]
	v_mfma_f32_16x16x32_bf16 v[98:101], v[178:181], v[194:197], v[98:101]
	v_mfma_f32_16x16x32_bf16 v[86:89], v[170:173], v[202:205], v[86:89]
	v_mfma_f32_16x16x32_bf16 v[82:85], v[178:181], v[202:205], v[82:85]
	v_mfma_f32_16x16x32_bf16 v[70:73], v[170:173], v[228:231], v[70:73]
	v_mfma_f32_16x16x32_bf16 v[66:69], v[178:181], v[228:231], v[66:69]
	s_barrier
; #define PG8_STAGE(bufoff, gbase, voff) do { _Pragma("unroll") for (int _i = 0; _i < 2; ++_i) \
;         __builtin_amdgcn_global_load_lds((const unsigned*)((const char*)(gbase) + (voff)[_i]), (PG8_LAS unsigned*)(lds + (bufoff) + ldsw + _i * 8192), 16, 0, 0); } while (0)
; #define PG8_LDA(dst, b, h) do { _Pragma("unroll") for (int m = 0; m < 4; ++m) _Pragma("unroll") for (int k = 0; k < 2; ++k) dst[m][k] = *(const PG8_LAS bf16x8*)(lds + PG8_SA(b, h) + aoff + m * 2048 + k * 1024); } while (0)
; #define PG8_LDB(dst, b, h) do { _Pragma("unroll") for (int n = 0; n < 2; ++n) _Pragma("unroll") for (int k = 0; k < 2; ++k) dst[n][k] = *(const PG8_LAS bf16x8*)(lds + PG8_SB(b, h) + boff + n * 2048 + k * 1024); } while (0)
; #define PG8_MMA(ai, bj, At, Bt) do { __builtin_amdgcn_s_setprio(1); _Pragma("unroll") for (int m = 0; m < 4; ++m) _Pragma("unroll") for (int n = 0; n < 2; ++n) _Pragma("unroll") for (int k = 0; k < 2; ++k) \
;         acc[ai][bj][m][n] = __builtin_amdgcn_mfma_f32_16x16x32_bf16(Bt[n][k], At[m][k], acc[ai][bj][m][n], 0, 0, 0); __builtin_amdgcn_s_setprio(0); } while (0)
; #define PG8_WAIT_V(n) asm volatile("s_waitcnt vmcnt(" #n ")" ::: "memory")
; #define PG8_BAR __builtin_amdgcn_s_barrier()
; template <class Epi, class Sched, bool ALIGN_EPI = false, bool SP2 = false>
; __device__ __forceinline__ void gemm_phase(PG8_LAS unsigned char* lds, const Gemm g, const Sched& S, const Epi& E) {
;     ...
;         for (int t = 0; t < nt; t += 2) {
;             const bool last = (t == nt - 2);
;             const char* a1 = cA + (size_t)(t + 1) * kstep;
;             const char* a2 = last ? nA : cA + (size_t)(t + 2) * kstep; const char* b2 = last ? nB : cB + (size_t)(t + 2) * kstep;
;             const char* a3 = a2 + kstep; const char* b3 = b2 + kstep;
;             if (last && has_next) S.a_ready(nxt);
;             if constexpr (SP2) {
;             PG8_LDB(B0, 0, 0); PG8_LDB(B1, 0, 1); PG8_SCHED; PG8_LDA(At, 0, 0); PG8_STAGE(PG8_SA(1, 1), a1 + hstep, voffA);
;             PG8_WAIT_V(8); PG8_WAIT_L(0); PG8_BAR; PG8_MMA(0, 0, At, B0); PG8_MMA(0, 1, At, B1); PG8_BAR; PG8_SCHED;
;     ...
;             PG8_LDA(At, 1, 1); PG8_STAGE(PG8_SB(1, 0), b3, voffB); PG8_STAGE(PG8_SB(1, 1), b3 + hstep, voffB); PG8_STAGE(PG8_SA(1, 0), a3, voffA);
;             PG8_WAIT_V(8); PG8_WAIT_L(0); PG8_BAR; PG8_MMA(1, 0, At, B0); PG8_MMA(1, 1, At, B1); PG8_BAR; PG8_SCHED;
	s_setprio 0
	s_add_i32 s26, s52, s31
	v_lshl_add_u64 v[138:139], v[138:139], 0, s[86:87]
	s_mov_b32 m0, s26
	ds_read_b128 v[182:185], v152 offset:49152
	ds_read_b128 v[186:189], v152 offset:50176
	ds_read_b128 v[190:193], v152 offset:51200
	ds_read_b128 v[194:197], v152 offset:52224
	ds_read_b128 v[198:201], v152 offset:53248
	ds_read_b128 v[202:205], v152 offset:54272
	ds_read_b128 v[224:227], v152 offset:55296
	ds_read_b128 v[228:231], v152 offset:56320
	global_load_lds_dwordx4 v[138:139], off
	s_add_i32 m0, s26, 0x2000
	s_add_u32 s24, s24, 0x40080
	v_lshl_add_u64 v[138:139], v[140:141], 0, s[86:87]
	s_addc_u32 s25, s25, 0
	s_add_i32 s26, s53, s31
	global_load_lds_dwordx4 v[138:139], off
	v_lshl_add_u64 v[138:139], s[24:25], 0, v[0:1]
	s_mov_b32 m0, s26
	s_nop 0
	global_load_lds_dwordx4 v[138:139], off
	v_lshl_add_u64 v[138:139], s[24:25], 0, v[134:135]
	s_add_i32 m0, s26, 0x2000
	s_nop 0
	global_load_lds_dwordx4 v[138:139], off
	v_lshl_add_u64 v[138:139], v[232:233], 0, s[86:87]
	s_mov_b32 m0, s45
	s_nop 0
	global_load_lds_dwordx4 v[138:139], off
	v_lshl_add_u64 v[138:139], v[234:235], 0, s[86:87]
	s_mov_b32 m0, s46
	s_nop 0
	global_load_lds_dwordx4 v[138:139], off
	s_waitcnt vmcnt(8)
	s_waitcnt lgkmcnt(0)
	v_mfma_f32_16x16x32_bf16 v[62:65], v[144:147], v[182:185], v[62:65]
	v_mfma_f32_16x16x32_bf16 v[58:61], v[158:161], v[182:185], v[58:61]
	s_setprio 1
	s_barrier
	v_mfma_f32_16x16x32_bf16 v[46:49], v[144:147], v[190:193], v[46:49]
	v_mfma_f32_16x16x32_bf16 v[42:45], v[158:161], v[190:193], v[42:45]
	v_mfma_f32_16x16x32_bf16 v[30:33], v[144:147], v[198:201], v[30:33]
	v_mfma_f32_16x16x32_bf16 v[26:29], v[158:161], v[198:201], v[26:29]
	v_mfma_f32_16x16x32_bf16 v[14:17], v[144:147], v[224:227], v[14:17]
	v_mfma_f32_16x16x32_bf16 v[10:13], v[158:161], v[224:227], v[10:13]
	v_mfma_f32_16x16x32_bf16 v[62:65], v[154:157], v[186:189], v[62:65]
	v_mfma_f32_16x16x32_bf16 v[58:61], v[162:165], v[186:189], v[58:61]
	v_mfma_f32_16x16x32_bf16 v[46:49], v[154:157], v[194:197], v[46:49]
	v_mfma_f32_16x16x32_bf16 v[42:45], v[162:165], v[194:197], v[42:45]
	v_mfma_f32_16x16x32_bf16 v[30:33], v[154:157], v[202:205], v[30:33]
	v_mfma_f32_16x16x32_bf16 v[26:29], v[162:165], v[202:205], v[26:29]
	v_mfma_f32_16x16x32_bf16 v[14:17], v[154:157], v[228:231], v[14:17]
	v_mfma_f32_16x16x32_bf16 v[10:13], v[162:165], v[228:231], v[10:13]
	v_mfma_f32_16x16x32_bf16 v[54:57], v[166:169], v[182:185], v[54:57]
	v_mfma_f32_16x16x32_bf16 v[50:53], v[174:177], v[182:185], v[50:53]
	v_mfma_f32_16x16x32_bf16 v[38:41], v[166:169], v[190:193], v[38:41]
	v_mfma_f32_16x16x32_bf16 v[34:37], v[174:177], v[190:193], v[34:37]
	v_mfma_f32_16x16x32_bf16 v[22:25], v[166:169], v[198:201], v[22:25]
	v_mfma_f32_16x16x32_bf16 v[18:21], v[174:177], v[198:201], v[18:21]
	v_mfma_f32_16x16x32_bf16 v[6:9], v[166:169], v[224:227], v[6:9]
	v_mfma_f32_16x16x32_bf16 v[2:5], v[174:177], v[224:227], v[2:5]
	v_mfma_f32_16x16x32_bf16 v[54:57], v[170:173], v[186:189], v[54:57]
	v_mfma_f32_16x16x32_bf16 v[50:53], v[178:181], v[186:189], v[50:53]
	v_mfma_f32_16x16x32_bf16 v[38:41], v[170:173], v[194:197], v[38:41]
	v_mfma_f32_16x16x32_bf16 v[34:37], v[178:181], v[194:197], v[34:37]
	v_mfma_f32_16x16x32_bf16 v[22:25], v[170:173], v[202:205], v[22:25]
	v_mfma_f32_16x16x32_bf16 v[18:21], v[178:181], v[202:205], v[18:21]
	v_mfma_f32_16x16x32_bf16 v[6:9], v[170:173], v[228:231], v[6:9]
	v_mfma_f32_16x16x32_bf16 v[2:5], v[178:181], v[228:231], v[2:5]
	s_barrier
	s_setprio 0
	s_add_i32 s51, s51, 2
	s_add_u32 s22, s22, 0x100
	s_addc_u32 s23, s23, 0
	s_add_u32 s49, s49, 0x100
	s_addc_u32 s50, s50, 0
	s_cmp_gt_u32 s51, 13
	s_cbranch_scc1 .Lpeel_exit_sw
.LBB0_225:
	s_add_u32 s24, s22, 0xfffc0080
	s_addc_u32 s25, s23, -1
	s_add_i32 s52, 0, 0x10000
	s_cmp_eq_u32 s51, 12
	s_cselect_b32 s27, s5, s25
	s_cselect_b32 s26, s15, s24
	v_add_u32_e32 v138, s52, v149
	s_cselect_b32 s25, s13, s50
	s_cselect_b32 s24, s21, s49
	s_add_i32 s55, 0, 0x14000
	ds_read_b128 v[144:147], v138
	ds_read_b128 v[154:157], v138 offset:1024
	ds_read_b128 v[158:161], v138 offset:2048
	ds_read_b128 v[162:165], v138 offset:3072
	v_add_u32_e32 v138, s55, v149
	ds_read_b128 v[166:169], v138
	ds_read_b128 v[170:173], v138 offset:1024
	ds_read_b128 v[174:177], v138 offset:2048
	ds_read_b128 v[178:181], v138 offset:3072
	v_lshl_add_u64 v[138:139], s[22:23], 0, v[136:137]
	s_add_i32 m0, s41, 0xc000
	ds_read_b128 v[182:185], v152
	ds_read_b128 v[186:189], v152 offset:1024
	ds_read_b128 v[190:193], v152 offset:2048
	ds_read_b128 v[194:197], v152 offset:3072
	ds_read_b128 v[198:201], v152 offset:4096
	ds_read_b128 v[202:205], v152 offset:5120
	ds_read_b128 v[224:227], v152 offset:6144
	ds_read_b128 v[228:231], v152 offset:7168
	global_load_lds_dwordx4 v[138:139], off
	v_lshl_add_u64 v[138:139], s[22:23], 0, v[142:143]
	s_add_i32 m0, s41, 0xe000
	s_nop 0
	global_load_lds_dwordx4 v[138:139], off
	s_waitcnt vmcnt(8)
	s_waitcnt lgkmcnt(0)
	v_mfma_f32_16x16x32_bf16 v[126:129], v[144:147], v[182:185], v[126:129]
	v_mfma_f32_16x16x32_bf16 v[122:125], v[158:161], v[182:185], v[122:125]
	s_setprio 1
	s_barrier
; #define PG8_STAGE(bufoff, gbase, voff) do { _Pragma("unroll") for (int _i = 0; _i < 2; ++_i) \
;         __builtin_amdgcn_global_load_lds((const unsigned*)((const char*)(gbase) + (voff)[_i]), (PG8_LAS unsigned*)(lds + (bufoff) + ldsw + _i * 8192), 16, 0, 0); } while (0)
; #define PG8_LDA(dst, b, h) do { _Pragma("unroll") for (int m = 0; m < 4; ++m) _Pragma("unroll") for (int k = 0; k < 2; ++k) dst[m][k] = *(const PG8_LAS bf16x8*)(lds + PG8_SA(b, h) + aoff + m * 2048 + k * 1024); } while (0)
; #define PG8_MMA(ai, bj, At, Bt) do { __builtin_amdgcn_s_setprio(1); _Pragma("unroll") for (int m = 0; m < 4; ++m) _Pragma("unroll") for (int n = 0; n < 2; ++n) _Pragma("unroll") for (int k = 0; k < 2; ++k) \
;         acc[ai][bj][m][n] = __builtin_amdgcn_mfma_f32_16x16x32_bf16(Bt[n][k], At[m][k], acc[ai][bj][m][n], 0, 0, 0); __builtin_amdgcn_s_setprio(0); } while (0)
; #define PG8_WAIT_V(n) asm volatile("s_waitcnt vmcnt(" #n ")" ::: "memory")
; #define PG8_WAIT_L(n) asm volatile("s_waitcnt lgkmcnt(" #n ")" ::: "memory")
; #define PG8_BAR __builtin_amdgcn_s_barrier()
; #define PG8_SCHED __builtin_amdgcn_sched_barrier(0)
; template <class Epi, class Sched, bool ALIGN_EPI = false, bool SP2 = false>
; __device__ __forceinline__ void gemm_phase(PG8_LAS unsigned char* lds, const Gemm g, const Sched& S, const Epi& E) {
;     ...
;             PG8_WAIT_V(8); PG8_WAIT_L(0); PG8_BAR; PG8_MMA(0, 0, At, B0); PG8_MMA(0, 1, At, B1); PG8_BAR; PG8_SCHED;
;             PG8_LDA(At, 0, 1); PG8_STAGE(PG8_SB(0, 0), b2, voffB); PG8_STAGE(PG8_SB(0, 1), b2 + hstep, voffB); PG8_STAGE(PG8_SA(0, 0), a2, voffA);
;             PG8_WAIT_V(8); PG8_WAIT_L(0); PG8_BAR; PG8_MMA(1, 0, At, B0); PG8_MMA(1, 1, At, B1); PG8_BAR; PG8_SCHED;
	v_mfma_f32_16x16x32_bf16 v[110:113], v[144:147], v[190:193], v[110:113]
	v_mfma_f32_16x16x32_bf16 v[106:109], v[158:161], v[190:193], v[106:109]
	v_mfma_f32_16x16x32_bf16 v[94:97], v[144:147], v[198:201], v[94:97]
	v_mfma_f32_16x16x32_bf16 v[90:93], v[158:161], v[198:201], v[90:93]
	v_mfma_f32_16x16x32_bf16 v[78:81], v[144:147], v[224:227], v[78:81]
	v_mfma_f32_16x16x32_bf16 v[74:77], v[158:161], v[224:227], v[74:77]
	v_mfma_f32_16x16x32_bf16 v[126:129], v[154:157], v[186:189], v[126:129]
	v_mfma_f32_16x16x32_bf16 v[122:125], v[162:165], v[186:189], v[122:125]
	v_mfma_f32_16x16x32_bf16 v[110:113], v[154:157], v[194:197], v[110:113]
	v_mfma_f32_16x16x32_bf16 v[106:109], v[162:165], v[194:197], v[106:109]
	v_mfma_f32_16x16x32_bf16 v[94:97], v[154:157], v[202:205], v[94:97]
	v_mfma_f32_16x16x32_bf16 v[90:93], v[162:165], v[202:205], v[90:93]
	v_mfma_f32_16x16x32_bf16 v[78:81], v[154:157], v[228:231], v[78:81]
	v_mfma_f32_16x16x32_bf16 v[74:77], v[162:165], v[228:231], v[74:77]
	v_mfma_f32_16x16x32_bf16 v[118:121], v[166:169], v[182:185], v[118:121]
	v_mfma_f32_16x16x32_bf16 v[114:117], v[174:177], v[182:185], v[114:117]
	v_mfma_f32_16x16x32_bf16 v[102:105], v[166:169], v[190:193], v[102:105]
	v_mfma_f32_16x16x32_bf16 v[98:101], v[174:177], v[190:193], v[98:101]
	v_mfma_f32_16x16x32_bf16 v[86:89], v[166:169], v[198:201], v[86:89]
	v_mfma_f32_16x16x32_bf16 v[82:85], v[174:177], v[198:201], v[82:85]
	v_mfma_f32_16x16x32_bf16 v[70:73], v[166:169], v[224:227], v[70:73]
	v_mfma_f32_16x16x32_bf16 v[66:69], v[174:177], v[224:227], v[66:69]
	v_mfma_f32_16x16x32_bf16 v[118:121], v[170:173], v[186:189], v[118:121]
	v_mfma_f32_16x16x32_bf16 v[114:117], v[178:181], v[186:189], v[114:117]
	v_mfma_f32_16x16x32_bf16 v[102:105], v[170:173], v[194:197], v[102:105]
	v_mfma_f32_16x16x32_bf16 v[98:101], v[178:181], v[194:197], v[98:101]
	v_mfma_f32_16x16x32_bf16 v[86:89], v[170:173], v[202:205], v[86:89]
	v_mfma_f32_16x16x32_bf16 v[82:85], v[178:181], v[202:205], v[82:85]
	v_mfma_f32_16x16x32_bf16 v[70:73], v[170:173], v[228:231], v[70:73]
	v_mfma_f32_16x16x32_bf16 v[66:69], v[178:181], v[228:231], v[66:69]
	s_barrier
	s_setprio 0
	s_add_i32 s52, s52, s31
	v_lshl_add_u64 v[138:139], s[24:25], 0, v[0:1]
	s_mov_b32 m0, s52
	ds_read_b128 v[182:185], v152 offset:16384
	ds_read_b128 v[186:189], v152 offset:17408
	ds_read_b128 v[190:193], v152 offset:18432
	ds_read_b128 v[194:197], v152 offset:19456
	ds_read_b128 v[198:201], v152 offset:20480
	ds_read_b128 v[202:205], v152 offset:21504
	ds_read_b128 v[224:227], v152 offset:22528
	ds_read_b128 v[228:231], v152 offset:23552
	global_load_lds_dwordx4 v[138:139], off
	s_add_i32 m0, s52, 0x2000
	s_add_u32 s52, s24, 0x40000
	v_lshl_add_u64 v[140:141], s[24:25], 0, v[134:135]
	s_addc_u32 s53, s25, 0
	s_add_i32 s55, s55, s31
	global_load_lds_dwordx4 v[140:141], off
	v_lshl_add_u64 v[232:233], s[52:53], 0, v[0:1]
	s_mov_b32 m0, s55
	v_lshl_add_u64 v[234:235], s[26:27], 0, v[132:133]
	global_load_lds_dwordx4 v[232:233], off
	v_lshl_add_u64 v[232:233], s[52:53], 0, v[134:135]
	s_add_i32 m0, s55, 0x2000
	s_nop 0
	global_load_lds_dwordx4 v[232:233], off
	v_lshl_add_u64 v[232:233], s[26:27], 0, v[130:131]
	s_mov_b32 m0, s41
	s_nop 0
	global_load_lds_dwordx4 v[232:233], off
	s_mov_b32 m0, s42
	s_nop 0
	global_load_lds_dwordx4 v[234:235], off
	s_waitcnt vmcnt(8)
	s_waitcnt lgkmcnt(0)
	v_mfma_f32_16x16x32_bf16 v[62:65], v[144:147], v[182:185], v[62:65]
	v_mfma_f32_16x16x32_bf16 v[58:61], v[158:161], v[182:185], v[58:61]
	s_setprio 1
	s_barrier
	v_mfma_f32_16x16x32_bf16 v[46:49], v[144:147], v[190:193], v[46:49]
	v_mfma_f32_16x16x32_bf16 v[42:45], v[158:161], v[190:193], v[42:45]
	v_mfma_f32_16x16x32_bf16 v[30:33], v[144:147], v[198:201], v[30:33]
	v_mfma_f32_16x16x32_bf16 v[26:29], v[158:161], v[198:201], v[26:29]
	v_mfma_f32_16x16x32_bf16 v[14:17], v[144:147], v[224:227], v[14:17]
	v_mfma_f32_16x16x32_bf16 v[10:13], v[158:161], v[224:227], v[10:13]
	v_mfma_f32_16x16x32_bf16 v[62:65], v[154:157], v[186:189], v[62:65]
	v_mfma_f32_16x16x32_bf16 v[58:61], v[162:165], v[186:189], v[58:61]
	v_mfma_f32_16x16x32_bf16 v[46:49], v[154:157], v[194:197], v[46:49]
	v_mfma_f32_16x16x32_bf16 v[42:45], v[162:165], v[194:197], v[42:45]
	v_mfma_f32_16x16x32_bf16 v[30:33], v[154:157], v[202:205], v[30:33]
	v_mfma_f32_16x16x32_bf16 v[26:29], v[162:165], v[202:205], v[26:29]
	v_mfma_f32_16x16x32_bf16 v[14:17], v[154:157], v[228:231], v[14:17]
	v_mfma_f32_16x16x32_bf16 v[10:13], v[162:165], v[228:231], v[10:13]
	v_mfma_f32_16x16x32_bf16 v[54:57], v[166:169], v[182:185], v[54:57]
	v_mfma_f32_16x16x32_bf16 v[50:53], v[174:177], v[182:185], v[50:53]
	v_mfma_f32_16x16x32_bf16 v[38:41], v[166:169], v[190:193], v[38:41]
	v_mfma_f32_16x16x32_bf16 v[34:37], v[174:177], v[190:193], v[34:37]
	v_mfma_f32_16x16x32_bf16 v[22:25], v[166:169], v[198:201], v[22:25]
	v_mfma_f32_16x16x32_bf16 v[18:21], v[174:177], v[198:201], v[18:21]
	v_mfma_f32_16x16x32_bf16 v[6:9], v[166:169], v[224:227], v[6:9]
	v_mfma_f32_16x16x32_bf16 v[2:5], v[174:177], v[224:227], v[2:5]
	v_mfma_f32_16x16x32_bf16 v[54:57], v[170:173], v[186:189], v[54:57]
	v_mfma_f32_16x16x32_bf16 v[50:53], v[178:181], v[186:189], v[50:53]
	v_mfma_f32_16x16x32_bf16 v[38:41], v[170:173], v[194:197], v[38:41]
	v_mfma_f32_16x16x32_bf16 v[34:37], v[178:181], v[194:197], v[34:37]
	v_mfma_f32_16x16x32_bf16 v[22:25], v[170:173], v[202:205], v[22:25]
	v_mfma_f32_16x16x32_bf16 v[18:21], v[178:181], v[202:205], v[18:21]
	v_mfma_f32_16x16x32_bf16 v[6:9], v[170:173], v[228:231], v[6:9]
	v_mfma_f32_16x16x32_bf16 v[2:5], v[178:181], v[228:231], v[2:5]
	s_barrier
; #define PG8_STAGE(bufoff, gbase, voff) do { _Pragma("unroll") for (int _i = 0; _i < 2; ++_i) \
;         __builtin_amdgcn_global_load_lds((const unsigned*)((const char*)(gbase) + (voff)[_i]), (PG8_LAS unsigned*)(lds + (bufoff) + ldsw + _i * 8192), 16, 0, 0); } while (0)
; #define PG8_LDA(dst, b, h) do { _Pragma("unroll") for (int m = 0; m < 4; ++m) _Pragma("unroll") for (int k = 0; k < 2; ++k) dst[m][k] = *(const PG8_LAS bf16x8*)(lds + PG8_SA(b, h) + aoff + m * 2048 + k * 1024); } while (0)
; #define PG8_LDB(dst, b, h) do { _Pragma("unroll") for (int n = 0; n < 2; ++n) _Pragma("unroll") for (int k = 0; k < 2; ++k) dst[n][k] = *(const PG8_LAS bf16x8*)(lds + PG8_SB(b, h) + boff + n * 2048 + k * 1024); } while (0)
; #define PG8_MMA(ai, bj, At, Bt) do { __builtin_amdgcn_s_setprio(1); _Pragma("unroll") for (int m = 0; m < 4; ++m) _Pragma("unroll") for (int n = 0; n < 2; ++n) _Pragma("unroll") for (int k = 0; k < 2; ++k) \
;         acc[ai][bj][m][n] = __builtin_amdgcn_mfma_f32_16x16x32_bf16(Bt[n][k], At[m][k], acc[ai][bj][m][n], 0, 0, 0); __builtin_amdgcn_s_setprio(0); } while (0)
; #define PG8_WAIT_V(n) asm volatile("s_waitcnt vmcnt(" #n ")" ::: "memory")
; #define PG8_WAIT_L(n) asm volatile("s_waitcnt lgkmcnt(" #n ")" ::: "memory")
; #define PG8_BAR __builtin_amdgcn_s_barrier()
; #define PG8_SCHED __builtin_amdgcn_sched_barrier(0)
; template <class Epi, class Sched, bool ALIGN_EPI = false, bool SP2 = false>
; __device__ __forceinline__ void gemm_phase(PG8_LAS unsigned char* lds, const Gemm g, const Sched& S, const Epi& E) {
;     ...
;             PG8_LDB(B0, 1, 0); PG8_LDB(B1, 1, 1); PG8_SCHED; PG8_LDA(At, 1, 0); PG8_STAGE(PG8_SA(0, 1), a2 + hstep, voffA);
;             PG8_WAIT_V(8); PG8_WAIT_L(0); PG8_BAR; PG8_MMA(0, 0, At, B0); PG8_MMA(0, 1, At, B1); PG8_BAR; PG8_SCHED;
	s_setprio 0
	s_add_i32 s52, 0, 0x18000
	v_add_u32_e32 v153, s52, v149
	s_add_i32 s53, 0, 0x1c000
	ds_read_b128 v[144:147], v153
	ds_read_b128 v[154:157], v153 offset:1024
	ds_read_b128 v[158:161], v153 offset:2048
	ds_read_b128 v[162:165], v153 offset:3072
	v_add_u32_e32 v153, s53, v149
	ds_read_b128 v[166:169], v153
	ds_read_b128 v[170:173], v153 offset:1024
	ds_read_b128 v[174:177], v153 offset:2048
	ds_read_b128 v[178:181], v153 offset:3072
	s_add_u32 s26, s26, 0x40000
	s_addc_u32 s27, s27, 0
	s_mov_b32 m0, s43
	v_lshl_add_u64 v[236:237], s[26:27], 0, v[130:131]
	ds_read_b128 v[182:185], v152 offset:32768
	ds_read_b128 v[186:189], v152 offset:33792
	ds_read_b128 v[190:193], v152 offset:34816
	ds_read_b128 v[194:197], v152 offset:35840
	ds_read_b128 v[198:201], v152 offset:36864
	ds_read_b128 v[202:205], v152 offset:37888
	ds_read_b128 v[224:227], v152 offset:38912
	ds_read_b128 v[228:231], v152 offset:39936
	global_load_lds_dwordx4 v[236:237], off
	v_lshl_add_u64 v[236:237], s[26:27], 0, v[132:133]
	s_mov_b32 m0, s44
	s_nop 0
	global_load_lds_dwordx4 v[236:237], off
	s_waitcnt vmcnt(8)
	s_waitcnt lgkmcnt(0)
	v_mfma_f32_16x16x32_bf16 v[126:129], v[144:147], v[182:185], v[126:129]
	v_mfma_f32_16x16x32_bf16 v[122:125], v[158:161], v[182:185], v[122:125]
	s_setprio 1
	s_barrier
	v_mfma_f32_16x16x32_bf16 v[110:113], v[144:147], v[190:193], v[110:113]
	v_mfma_f32_16x16x32_bf16 v[106:109], v[158:161], v[190:193], v[106:109]
	v_mfma_f32_16x16x32_bf16 v[94:97], v[144:147], v[198:201], v[94:97]
	v_mfma_f32_16x16x32_bf16 v[90:93], v[158:161], v[198:201], v[90:93]
	v_mfma_f32_16x16x32_bf16 v[78:81], v[144:147], v[224:227], v[78:81]
	v_mfma_f32_16x16x32_bf16 v[74:77], v[158:161], v[224:227], v[74:77]
	v_mfma_f32_16x16x32_bf16 v[126:129], v[154:157], v[186:189], v[126:129]
	v_mfma_f32_16x16x32_bf16 v[122:125], v[162:165], v[186:189], v[122:125]
	v_mfma_f32_16x16x32_bf16 v[110:113], v[154:157], v[194:197], v[110:113]
	v_mfma_f32_16x16x32_bf16 v[106:109], v[162:165], v[194:197], v[106:109]
	v_mfma_f32_16x16x32_bf16 v[94:97], v[154:157], v[202:205], v[94:97]
	v_mfma_f32_16x16x32_bf16 v[90:93], v[162:165], v[202:205], v[90:93]
	v_mfma_f32_16x16x32_bf16 v[78:81], v[154:157], v[228:231], v[78:81]
	v_mfma_f32_16x16x32_bf16 v[74:77], v[162:165], v[228:231], v[74:77]
	v_mfma_f32_16x16x32_bf16 v[118:121], v[166:169], v[182:185], v[118:121]
	v_mfma_f32_16x16x32_bf16 v[114:117], v[174:177], v[182:185], v[114:117]
	v_mfma_f32_16x16x32_bf16 v[102:105], v[166:169], v[190:193], v[102:105]
	v_mfma_f32_16x16x32_bf16 v[98:101], v[174:177], v[190:193], v[98:101]
	v_mfma_f32_16x16x32_bf16 v[86:89], v[166:169], v[198:201], v[86:89]
	v_mfma_f32_16x16x32_bf16 v[82:85], v[174:177], v[198:201], v[82:85]
	v_mfma_f32_16x16x32_bf16 v[70:73], v[166:169], v[224:227], v[70:73]
	v_mfma_f32_16x16x32_bf16 v[66:69], v[174:177], v[224:227], v[66:69]
	v_mfma_f32_16x16x32_bf16 v[118:121], v[170:173], v[186:189], v[118:121]
	v_mfma_f32_16x16x32_bf16 v[114:117], v[178:181], v[186:189], v[114:117]
	v_mfma_f32_16x16x32_bf16 v[102:105], v[170:173], v[194:197], v[102:105]
	v_mfma_f32_16x16x32_bf16 v[98:101], v[178:181], v[194:197], v[98:101]
	v_mfma_f32_16x16x32_bf16 v[86:89], v[170:173], v[202:205], v[86:89]
	v_mfma_f32_16x16x32_bf16 v[82:85], v[178:181], v[202:205], v[82:85]
	v_mfma_f32_16x16x32_bf16 v[70:73], v[170:173], v[228:231], v[70:73]
	v_mfma_f32_16x16x32_bf16 v[66:69], v[178:181], v[228:231], v[66:69]
	s_barrier
; #define PG8_STAGE(bufoff, gbase, voff) do { _Pragma("unroll") for (int _i = 0; _i < 2; ++_i) \
;         __builtin_amdgcn_global_load_lds((const unsigned*)((const char*)(gbase) + (voff)[_i]), (PG8_LAS unsigned*)(lds + (bufoff) + ldsw + _i * 8192), 16, 0, 0); } while (0)
; #define PG8_LDA(dst, b, h) do { _Pragma("unroll") for (int m = 0; m < 4; ++m) _Pragma("unroll") for (int k = 0; k < 2; ++k) dst[m][k] = *(const PG8_LAS bf16x8*)(lds + PG8_SA(b, h) + aoff + m * 2048 + k * 1024); } while (0)
; #define PG8_MMA(ai, bj, At, Bt) do { __builtin_amdgcn_s_setprio(1); _Pragma("unroll") for (int m = 0; m < 4; ++m) _Pragma("unroll") for (int n = 0; n < 2; ++n) _Pragma("unroll") for (int k = 0; k < 2; ++k) \
;         acc[ai][bj][m][n] = __builtin_amdgcn_mfma_f32_16x16x32_bf16(Bt[n][k], At[m][k], acc[ai][bj][m][n], 0, 0, 0); __builtin_amdgcn_s_setprio(0); } while (0)
; #define PG8_WAIT_V(n) asm volatile("s_waitcnt vmcnt(" #n ")" ::: "memory")
; #define PG8_WAIT_L(n) asm volatile("s_waitcnt lgkmcnt(" #n ")" ::: "memory")
; #define PG8_BAR __builtin_amdgcn_s_barrier()
; #define PG8_SCHED __builtin_amdgcn_sched_barrier(0)
; template <class Epi, class Sched, bool ALIGN_EPI = false, bool SP2 = false>
; __device__ __forceinline__ void gemm_phase(PG8_LAS unsigned char* lds, const Gemm g, const Sched& S, const Epi& E) {
;     ...
;             PG8_LDA(At, 1, 1); PG8_STAGE(PG8_SB(1, 0), b3, voffB); PG8_STAGE(PG8_SB(1, 1), b3 + hstep, voffB); PG8_STAGE(PG8_SA(1, 0), a3, voffA);
;             PG8_WAIT_V(8); PG8_WAIT_L(0); PG8_BAR; PG8_MMA(1, 0, At, B0); PG8_MMA(1, 1, At, B1); PG8_BAR; PG8_SCHED;
	s_setprio 0
	s_add_i32 s26, s52, s31
	v_lshl_add_u64 v[138:139], v[138:139], 0, s[86:87]
	s_mov_b32 m0, s26
	ds_read_b128 v[182:185], v152 offset:49152
	ds_read_b128 v[186:189], v152 offset:50176
	ds_read_b128 v[190:193], v152 offset:51200
	ds_read_b128 v[194:197], v152 offset:52224
	ds_read_b128 v[198:201], v152 offset:53248
	ds_read_b128 v[202:205], v152 offset:54272
	ds_read_b128 v[224:227], v152 offset:55296
	ds_read_b128 v[228:231], v152 offset:56320
	global_load_lds_dwordx4 v[138:139], off
	s_add_i32 m0, s26, 0x2000
	s_add_u32 s24, s24, 0x40080
	v_lshl_add_u64 v[138:139], v[140:141], 0, s[86:87]
	s_addc_u32 s25, s25, 0
	s_add_i32 s26, s53, s31
	global_load_lds_dwordx4 v[138:139], off
	v_lshl_add_u64 v[138:139], s[24:25], 0, v[0:1]
	s_mov_b32 m0, s26
	s_nop 0
	global_load_lds_dwordx4 v[138:139], off
	v_lshl_add_u64 v[138:139], s[24:25], 0, v[134:135]
	s_add_i32 m0, s26, 0x2000
	s_nop 0
	global_load_lds_dwordx4 v[138:139], off
	v_lshl_add_u64 v[138:139], v[232:233], 0, s[86:87]
	s_mov_b32 m0, s45
	s_nop 0
	global_load_lds_dwordx4 v[138:139], off
	v_lshl_add_u64 v[138:139], v[234:235], 0, s[86:87]
	s_mov_b32 m0, s46
	s_nop 0
	global_load_lds_dwordx4 v[138:139], off
	s_waitcnt vmcnt(8)
	s_waitcnt lgkmcnt(0)
	v_mfma_f32_16x16x32_bf16 v[62:65], v[144:147], v[182:185], v[62:65]
	v_mfma_f32_16x16x32_bf16 v[58:61], v[158:161], v[182:185], v[58:61]
	s_setprio 1
	s_barrier
	v_mfma_f32_16x16x32_bf16 v[46:49], v[144:147], v[190:193], v[46:49]
	v_mfma_f32_16x16x32_bf16 v[42:45], v[158:161], v[190:193], v[42:45]
	v_mfma_f32_16x16x32_bf16 v[30:33], v[144:147], v[198:201], v[30:33]
	v_mfma_f32_16x16x32_bf16 v[26:29], v[158:161], v[198:201], v[26:29]
	v_mfma_f32_16x16x32_bf16 v[14:17], v[144:147], v[224:227], v[14:17]
	v_mfma_f32_16x16x32_bf16 v[10:13], v[158:161], v[224:227], v[10:13]
	v_mfma_f32_16x16x32_bf16 v[62:65], v[154:157], v[186:189], v[62:65]
	v_mfma_f32_16x16x32_bf16 v[58:61], v[162:165], v[186:189], v[58:61]
	v_mfma_f32_16x16x32_bf16 v[46:49], v[154:157], v[194:197], v[46:49]
	v_mfma_f32_16x16x32_bf16 v[42:45], v[162:165], v[194:197], v[42:45]
	v_mfma_f32_16x16x32_bf16 v[30:33], v[154:157], v[202:205], v[30:33]
	v_mfma_f32_16x16x32_bf16 v[26:29], v[162:165], v[202:205], v[26:29]
	v_mfma_f32_16x16x32_bf16 v[14:17], v[154:157], v[228:231], v[14:17]
	v_mfma_f32_16x16x32_bf16 v[10:13], v[162:165], v[228:231], v[10:13]
	v_mfma_f32_16x16x32_bf16 v[54:57], v[166:169], v[182:185], v[54:57]
	v_mfma_f32_16x16x32_bf16 v[50:53], v[174:177], v[182:185], v[50:53]
	v_mfma_f32_16x16x32_bf16 v[38:41], v[166:169], v[190:193], v[38:41]
	v_mfma_f32_16x16x32_bf16 v[34:37], v[174:177], v[190:193], v[34:37]
	v_mfma_f32_16x16x32_bf16 v[22:25], v[166:169], v[198:201], v[22:25]
	v_mfma_f32_16x16x32_bf16 v[18:21], v[174:177], v[198:201], v[18:21]
	v_mfma_f32_16x16x32_bf16 v[6:9], v[166:169], v[224:227], v[6:9]
	v_mfma_f32_16x16x32_bf16 v[2:5], v[174:177], v[224:227], v[2:5]
	v_mfma_f32_16x16x32_bf16 v[54:57], v[170:173], v[186:189], v[54:57]
	v_mfma_f32_16x16x32_bf16 v[50:53], v[178:181], v[186:189], v[50:53]
	v_mfma_f32_16x16x32_bf16 v[38:41], v[170:173], v[194:197], v[38:41]
	v_mfma_f32_16x16x32_bf16 v[34:37], v[178:181], v[194:197], v[34:37]
	v_mfma_f32_16x16x32_bf16 v[22:25], v[170:173], v[202:205], v[22:25]
	v_mfma_f32_16x16x32_bf16 v[18:21], v[178:181], v[202:205], v[18:21]
	v_mfma_f32_16x16x32_bf16 v[6:9], v[170:173], v[228:231], v[6:9]
	v_mfma_f32_16x16x32_bf16 v[2:5], v[178:181], v[228:231], v[2:5]
	s_barrier
	s_setprio 0
	s_add_i32 s51, s51, 2
	s_add_u32 s22, s22, 0x100
	s_addc_u32 s23, s23, 0
	s_add_u32 s49, s49, 0x100
	s_addc_u32 s50, s50, 0
	s_cmp_gt_u32 s51, 13
	s_cbranch_scc0 .LBB0_225

; #define PG8_STAGE(bufoff, gbase, voff) do { _Pragma("unroll") for (int _i = 0; _i < 2; ++_i) \
;         __builtin_amdgcn_global_load_lds((const unsigned*)((const char*)(gbase) + (voff)[_i]), (PG8_LAS unsigned*)(lds + (bufoff) + ldsw + _i * 8192), 16, 0, 0); } while (0)
; #define PG8_LDA(dst, b, h) do { _Pragma("unroll") for (int m = 0; m < 4; ++m) _Pragma("unroll") for (int k = 0; k < 2; ++k) dst[m][k] = *(const PG8_LAS bf16x8*)(lds + PG8_SA(b, h) + aoff + m * 2048 + k * 1024); } while (0)
; #define PG8_LDB(dst, b, h) do { _Pragma("unroll") for (int n = 0; n < 2; ++n) _Pragma("unroll") for (int k = 0; k < 2; ++k) dst[n][k] = *(const PG8_LAS bf16x8*)(lds + PG8_SB(b, h) + boff + n * 2048 + k * 1024); } while (0)
; #define PG8_MMA(ai, bj, At, Bt) do { __builtin_amdgcn_s_setprio(1); _Pragma("unroll") for (int m = 0; m < 4; ++m) _Pragma("unroll") for (int n = 0; n < 2; ++n) _Pragma("unroll") for (int k = 0; k < 2; ++k) \
;         acc[ai][bj][m][n] = __builtin_amdgcn_mfma_f32_16x16x32_bf16(Bt[n][k], At[m][k], acc[ai][bj][m][n], 0, 0, 0); __builtin_amdgcn_s_setprio(0); } while (0)
; #define PG8_WAIT_V(n) asm volatile("s_waitcnt vmcnt(" #n ")" ::: "memory")
; #define PG8_WAIT_L(n) asm volatile("s_waitcnt lgkmcnt(" #n ")" ::: "memory")
; #define PG8_BAR __builtin_amdgcn_s_barrier()
; #define PG8_SCHED __builtin_amdgcn_sched_barrier(0)
; template <class Epi, class Sched, bool ALIGN_EPI = false, bool SP2 = false>
; __device__ __forceinline__ void gemm_phase(PG8_LAS unsigned char* lds, const Gemm g, const Sched& S, const Epi& E) {
;     ...
;         for (int t = 0; t < nt; t += 2) {
;             const bool last = (t == nt - 2);
;             const char* a1 = cA + (size_t)(t + 1) * kstep;
;             const char* a2 = last ? nA : cA + (size_t)(t + 2) * kstep; const char* b2 = last ? nB : cB + (size_t)(t + 2) * kstep;
;             const char* a3 = a2 + kstep; const char* b3 = b2 + kstep;
;             if (last && has_next) S.a_ready(nxt);
;             if constexpr (SP2) {
;             PG8_LDB(B0, 0, 0); PG8_LDB(B1, 0, 1); PG8_SCHED; PG8_LDA(At, 0, 0); PG8_STAGE(PG8_SA(1, 1), a1 + hstep, voffA);
;             PG8_WAIT_V(8); PG8_WAIT_L(0); PG8_BAR; PG8_MMA(0, 0, At, B0); PG8_MMA(0, 1, At, B1); PG8_BAR; PG8_SCHED;
;             PG8_LDA(At, 0, 1); PG8_STAGE(PG8_SB(0, 0), b2, voffB); PG8_STAGE(PG8_SB(0, 1), b2 + hstep, voffB); PG8_STAGE(PG8_SA(0, 0), a2, voffA);
.LBB0_362:
	s_add_u32 s16, s14, 0x100
	s_addc_u32 s17, s15, 0
	s_add_i32 s50, 0, 0x10000
	s_cmp_eq_u32 s49, 40
	s_cselect_b32 s21, s7, s17
	s_cselect_b32 s20, s6, s16
	v_add_u32_e32 v138, s50, v149
	s_cselect_b32 s19, s13, s48
	s_cselect_b32 s18, s12, s47
	s_add_i32 s51, 0, 0x14000
	ds_read_b128 v[144:147], v138
	ds_read_b128 v[152:155], v138 offset:1024
	ds_read_b128 v[156:159], v138 offset:2048
	ds_read_b128 v[160:163], v138 offset:3072
	v_add_u32_e32 v138, s51, v149
	ds_read_b128 v[164:167], v138
	ds_read_b128 v[168:171], v138 offset:1024
	ds_read_b128 v[172:175], v138 offset:2048
	ds_read_b128 v[176:179], v138 offset:3072
	v_lshl_add_u64 v[138:139], s[14:15], 0, v[136:137]
	s_add_i32 m0, s26, 0xc000
	ds_read_b128 v[180:183], v151
	ds_read_b128 v[184:187], v151 offset:1024
	ds_read_b128 v[188:191], v151 offset:2048
	ds_read_b128 v[192:195], v151 offset:3072
	ds_read_b128 v[196:199], v151 offset:4096
	ds_read_b128 v[200:203], v151 offset:5120
	ds_read_b128 v[224:227], v151 offset:6144
	ds_read_b128 v[228:231], v151 offset:7168
	global_load_lds_dwordx4 v[138:139], off
	v_lshl_add_u64 v[138:139], s[14:15], 0, v[142:143]
	s_add_i32 m0, s26, 0xe000
	s_nop 0
	global_load_lds_dwordx4 v[138:139], off
	s_waitcnt vmcnt(8)
	s_waitcnt lgkmcnt(0)
	v_mfma_f32_16x16x32_bf16 v[126:129], v[144:147], v[180:183], v[126:129]
	v_mfma_f32_16x16x32_bf16 v[122:125], v[156:159], v[180:183], v[122:125]
	s_setprio 1
	s_barrier
	v_mfma_f32_16x16x32_bf16 v[110:113], v[144:147], v[188:191], v[110:113]
	v_mfma_f32_16x16x32_bf16 v[106:109], v[156:159], v[188:191], v[106:109]
	v_mfma_f32_16x16x32_bf16 v[94:97], v[144:147], v[196:199], v[94:97]
	v_mfma_f32_16x16x32_bf16 v[90:93], v[156:159], v[196:199], v[90:93]
	v_mfma_f32_16x16x32_bf16 v[78:81], v[144:147], v[224:227], v[78:81]
	v_mfma_f32_16x16x32_bf16 v[74:77], v[156:159], v[224:227], v[74:77]
	v_mfma_f32_16x16x32_bf16 v[126:129], v[152:155], v[184:187], v[126:129]
	v_mfma_f32_16x16x32_bf16 v[122:125], v[160:163], v[184:187], v[122:125]
	v_mfma_f32_16x16x32_bf16 v[110:113], v[152:155], v[192:195], v[110:113]
	v_mfma_f32_16x16x32_bf16 v[106:109], v[160:163], v[192:195], v[106:109]
	v_mfma_f32_16x16x32_bf16 v[94:97], v[152:155], v[200:203], v[94:97]
	v_mfma_f32_16x16x32_bf16 v[90:93], v[160:163], v[200:203], v[90:93]
	v_mfma_f32_16x16x32_bf16 v[78:81], v[152:155], v[228:231], v[78:81]
	v_mfma_f32_16x16x32_bf16 v[74:77], v[160:163], v[228:231], v[74:77]
	v_mfma_f32_16x16x32_bf16 v[118:121], v[164:167], v[180:183], v[118:121]
	v_mfma_f32_16x16x32_bf16 v[114:117], v[172:175], v[180:183], v[114:117]
	v_mfma_f32_16x16x32_bf16 v[102:105], v[164:167], v[188:191], v[102:105]
	v_mfma_f32_16x16x32_bf16 v[98:101], v[172:175], v[188:191], v[98:101]
	v_mfma_f32_16x16x32_bf16 v[86:89], v[164:167], v[196:199], v[86:89]
	v_mfma_f32_16x16x32_bf16 v[82:85], v[172:175], v[196:199], v[82:85]
	v_mfma_f32_16x16x32_bf16 v[70:73], v[164:167], v[224:227], v[70:73]
	v_mfma_f32_16x16x32_bf16 v[66:69], v[172:175], v[224:227], v[66:69]
	v_mfma_f32_16x16x32_bf16 v[118:121], v[168:171], v[184:187], v[118:121]
	v_mfma_f32_16x16x32_bf16 v[114:117], v[176:179], v[184:187], v[114:117]
	v_mfma_f32_16x16x32_bf16 v[102:105], v[168:171], v[192:195], v[102:105]
	v_mfma_f32_16x16x32_bf16 v[98:101], v[176:179], v[192:195], v[98:101]
	v_mfma_f32_16x16x32_bf16 v[86:89], v[168:171], v[200:203], v[86:89]
	v_mfma_f32_16x16x32_bf16 v[82:85], v[176:179], v[200:203], v[82:85]
	v_mfma_f32_16x16x32_bf16 v[70:73], v[168:171], v[228:231], v[70:73]
	v_mfma_f32_16x16x32_bf16 v[66:69], v[176:179], v[228:231], v[66:69]
	s_barrier
	s_setprio 0
	s_add_i32 s14, s50, s23
	v_lshl_add_u64 v[138:139], s[18:19], 0, v[0:1]
	s_mov_b32 m0, s14
	ds_read_b128 v[180:183], v151 offset:16384
	ds_read_b128 v[184:187], v151 offset:17408
	ds_read_b128 v[188:191], v151 offset:18432
	ds_read_b128 v[192:195], v151 offset:19456
	ds_read_b128 v[196:199], v151 offset:20480
	ds_read_b128 v[200:203], v151 offset:21504
	ds_read_b128 v[224:227], v151 offset:22528
	ds_read_b128 v[228:231], v151 offset:23552
	global_load_lds_dwordx4 v[138:139], off
	s_add_i32 m0, s14, 0x2000
	s_add_u32 s14, s18, 0xb0000
	v_lshl_add_u64 v[140:141], s[18:19], 0, v[134:135]
	s_addc_u32 s15, s19, 0
	s_add_i32 s50, s51, s23
	global_load_lds_dwordx4 v[140:141], off
	v_lshl_add_u64 v[204:205], s[14:15], 0, v[0:1]
	s_mov_b32 m0, s50
	v_lshl_add_u64 v[232:233], s[20:21], 0, v[132:133]
	global_load_lds_dwordx4 v[204:205], off
	v_lshl_add_u64 v[204:205], s[14:15], 0, v[134:135]
	s_add_i32 m0, s50, 0x2000
	s_nop 0
	global_load_lds_dwordx4 v[204:205], off
	v_lshl_add_u64 v[204:205], s[20:21], 0, v[130:131]
	s_mov_b32 m0, s26
	s_nop 0
	global_load_lds_dwordx4 v[204:205], off
	s_mov_b32 m0, s27
	s_nop 0
	global_load_lds_dwordx4 v[232:233], off
	s_waitcnt vmcnt(8)
	s_waitcnt lgkmcnt(0)
	v_mfma_f32_16x16x32_bf16 v[62:65], v[144:147], v[180:183], v[62:65]
	v_mfma_f32_16x16x32_bf16 v[58:61], v[156:159], v[180:183], v[58:61]
	s_setprio 1
	s_barrier
; #define PG8_STAGE(bufoff, gbase, voff) do { _Pragma("unroll") for (int _i = 0; _i < 2; ++_i) \
;         __builtin_amdgcn_global_load_lds((const unsigned*)((const char*)(gbase) + (voff)[_i]), (PG8_LAS unsigned*)(lds + (bufoff) + ldsw + _i * 8192), 16, 0, 0); } while (0)
; #define PG8_LDA(dst, b, h) do { _Pragma("unroll") for (int m = 0; m < 4; ++m) _Pragma("unroll") for (int k = 0; k < 2; ++k) dst[m][k] = *(const PG8_LAS bf16x8*)(lds + PG8_SA(b, h) + aoff + m * 2048 + k * 1024); } while (0)
; #define PG8_LDB(dst, b, h) do { _Pragma("unroll") for (int n = 0; n < 2; ++n) _Pragma("unroll") for (int k = 0; k < 2; ++k) dst[n][k] = *(const PG8_LAS bf16x8*)(lds + PG8_SB(b, h) + boff + n * 2048 + k * 1024); } while (0)
; #define PG8_MMA(ai, bj, At, Bt) do { __builtin_amdgcn_s_setprio(1); _Pragma("unroll") for (int m = 0; m < 4; ++m) _Pragma("unroll") for (int n = 0; n < 2; ++n) _Pragma("unroll") for (int k = 0; k < 2; ++k) \
;         acc[ai][bj][m][n] = __builtin_amdgcn_mfma_f32_16x16x32_bf16(Bt[n][k], At[m][k], acc[ai][bj][m][n], 0, 0, 0); __builtin_amdgcn_s_setprio(0); } while (0)
; #define PG8_WAIT_V(n) asm volatile("s_waitcnt vmcnt(" #n ")" ::: "memory")
; #define PG8_WAIT_L(n) asm volatile("s_waitcnt lgkmcnt(" #n ")" ::: "memory")
; #define PG8_BAR __builtin_amdgcn_s_barrier()
; #define PG8_SCHED __builtin_amdgcn_sched_barrier(0)
; template <class Epi, class Sched, bool ALIGN_EPI = false, bool SP2 = false>
; __device__ __forceinline__ void gemm_phase(PG8_LAS unsigned char* lds, const Gemm g, const Sched& S, const Epi& E) {
;     ...
;             PG8_WAIT_V(8); PG8_WAIT_L(0); PG8_BAR; PG8_MMA(1, 0, At, B0); PG8_MMA(1, 1, At, B1); PG8_BAR; PG8_SCHED;
;             PG8_LDB(B0, 1, 0); PG8_LDB(B1, 1, 1); PG8_SCHED; PG8_LDA(At, 1, 0); PG8_STAGE(PG8_SA(0, 1), a2 + hstep, voffA);
;             PG8_WAIT_V(8); PG8_WAIT_L(0); PG8_BAR; PG8_MMA(0, 0, At, B0); PG8_MMA(0, 1, At, B1); PG8_BAR; PG8_SCHED;
	v_mfma_f32_16x16x32_bf16 v[46:49], v[144:147], v[188:191], v[46:49]
	v_mfma_f32_16x16x32_bf16 v[42:45], v[156:159], v[188:191], v[42:45]
	v_mfma_f32_16x16x32_bf16 v[30:33], v[144:147], v[196:199], v[30:33]
	v_mfma_f32_16x16x32_bf16 v[26:29], v[156:159], v[196:199], v[26:29]
	v_mfma_f32_16x16x32_bf16 v[14:17], v[144:147], v[224:227], v[14:17]
	v_mfma_f32_16x16x32_bf16 v[10:13], v[156:159], v[224:227], v[10:13]
	v_mfma_f32_16x16x32_bf16 v[62:65], v[152:155], v[184:187], v[62:65]
	v_mfma_f32_16x16x32_bf16 v[58:61], v[160:163], v[184:187], v[58:61]
	v_mfma_f32_16x16x32_bf16 v[46:49], v[152:155], v[192:195], v[46:49]
	v_mfma_f32_16x16x32_bf16 v[42:45], v[160:163], v[192:195], v[42:45]
	v_mfma_f32_16x16x32_bf16 v[30:33], v[152:155], v[200:203], v[30:33]
	v_mfma_f32_16x16x32_bf16 v[26:29], v[160:163], v[200:203], v[26:29]
	v_mfma_f32_16x16x32_bf16 v[14:17], v[152:155], v[228:231], v[14:17]
	v_mfma_f32_16x16x32_bf16 v[10:13], v[160:163], v[228:231], v[10:13]
	v_mfma_f32_16x16x32_bf16 v[54:57], v[164:167], v[180:183], v[54:57]
	v_mfma_f32_16x16x32_bf16 v[50:53], v[172:175], v[180:183], v[50:53]
	v_mfma_f32_16x16x32_bf16 v[38:41], v[164:167], v[188:191], v[38:41]
	v_mfma_f32_16x16x32_bf16 v[34:37], v[172:175], v[188:191], v[34:37]
	v_mfma_f32_16x16x32_bf16 v[22:25], v[164:167], v[196:199], v[22:25]
	v_mfma_f32_16x16x32_bf16 v[18:21], v[172:175], v[196:199], v[18:21]
	v_mfma_f32_16x16x32_bf16 v[6:9], v[164:167], v[224:227], v[6:9]
	v_mfma_f32_16x16x32_bf16 v[2:5], v[172:175], v[224:227], v[2:5]
	v_mfma_f32_16x16x32_bf16 v[54:57], v[168:171], v[184:187], v[54:57]
	v_mfma_f32_16x16x32_bf16 v[50:53], v[176:179], v[184:187], v[50:53]
	v_mfma_f32_16x16x32_bf16 v[38:41], v[168:171], v[192:195], v[38:41]
	v_mfma_f32_16x16x32_bf16 v[34:37], v[176:179], v[192:195], v[34:37]
	v_mfma_f32_16x16x32_bf16 v[22:25], v[168:171], v[200:203], v[22:25]
	v_mfma_f32_16x16x32_bf16 v[18:21], v[176:179], v[200:203], v[18:21]
	v_mfma_f32_16x16x32_bf16 v[6:9], v[168:171], v[228:231], v[6:9]
	v_mfma_f32_16x16x32_bf16 v[2:5], v[176:179], v[228:231], v[2:5]
	s_barrier
	s_setprio 0
	s_add_i32 s50, 0, 0x18000
	s_add_i32 s51, 0, 0x1c000
	v_add_u32_e32 v160, s50, v149
	v_add_u32_e32 v176, s51, v149
	ds_read_b128 v[144:147], v160
	ds_read_b128 v[152:155], v160 offset:1024
	ds_read_b128 v[156:159], v160 offset:2048
	ds_read_b128 v[160:163], v160 offset:3072
	ds_read_b128 v[164:167], v176
	ds_read_b128 v[168:171], v176 offset:1024
	ds_read_b128 v[172:175], v176 offset:2048
	ds_read_b128 v[176:179], v176 offset:3072
	s_add_u32 s14, s20, 0xb0000
	s_addc_u32 s15, s21, 0
	s_mov_b32 m0, s29
	v_lshl_add_u64 v[234:235], s[14:15], 0, v[130:131]
	ds_read_b128 v[180:183], v151 offset:32768
	ds_read_b128 v[184:187], v151 offset:33792
	ds_read_b128 v[188:191], v151 offset:34816
	ds_read_b128 v[192:195], v151 offset:35840
	ds_read_b128 v[196:199], v151 offset:36864
	ds_read_b128 v[200:203], v151 offset:37888
	ds_read_b128 v[224:227], v151 offset:38912
	ds_read_b128 v[228:231], v151 offset:39936
	global_load_lds_dwordx4 v[234:235], off
	v_lshl_add_u64 v[234:235], s[14:15], 0, v[132:133]
	s_mov_b32 m0, s30
	s_nop 0
	global_load_lds_dwordx4 v[234:235], off
	s_waitcnt vmcnt(8)
	s_waitcnt lgkmcnt(0)
	v_mfma_f32_16x16x32_bf16 v[126:129], v[144:147], v[180:183], v[126:129]
	v_mfma_f32_16x16x32_bf16 v[122:125], v[156:159], v[180:183], v[122:125]
	s_setprio 1
	s_barrier
	v_mfma_f32_16x16x32_bf16 v[110:113], v[144:147], v[188:191], v[110:113]
	v_mfma_f32_16x16x32_bf16 v[106:109], v[156:159], v[188:191], v[106:109]
	v_mfma_f32_16x16x32_bf16 v[94:97], v[144:147], v[196:199], v[94:97]
	v_mfma_f32_16x16x32_bf16 v[90:93], v[156:159], v[196:199], v[90:93]
	v_mfma_f32_16x16x32_bf16 v[78:81], v[144:147], v[224:227], v[78:81]
	v_mfma_f32_16x16x32_bf16 v[74:77], v[156:159], v[224:227], v[74:77]
	v_mfma_f32_16x16x32_bf16 v[126:129], v[152:155], v[184:187], v[126:129]
	v_mfma_f32_16x16x32_bf16 v[122:125], v[160:163], v[184:187], v[122:125]
	v_mfma_f32_16x16x32_bf16 v[110:113], v[152:155], v[192:195], v[110:113]
	v_mfma_f32_16x16x32_bf16 v[106:109], v[160:163], v[192:195], v[106:109]
	v_mfma_f32_16x16x32_bf16 v[94:97], v[152:155], v[200:203], v[94:97]
	v_mfma_f32_16x16x32_bf16 v[90:93], v[160:163], v[200:203], v[90:93]
	v_mfma_f32_16x16x32_bf16 v[78:81], v[152:155], v[228:231], v[78:81]
	v_mfma_f32_16x16x32_bf16 v[74:77], v[160:163], v[228:231], v[74:77]
	v_mfma_f32_16x16x32_bf16 v[118:121], v[164:167], v[180:183], v[118:121]
	v_mfma_f32_16x16x32_bf16 v[114:117], v[172:175], v[180:183], v[114:117]
	v_mfma_f32_16x16x32_bf16 v[102:105], v[164:167], v[188:191], v[102:105]
	v_mfma_f32_16x16x32_bf16 v[98:101], v[172:175], v[188:191], v[98:101]
	v_mfma_f32_16x16x32_bf16 v[86:89], v[164:167], v[196:199], v[86:89]
	v_mfma_f32_16x16x32_bf16 v[82:85], v[172:175], v[196:199], v[82:85]
	v_mfma_f32_16x16x32_bf16 v[70:73], v[164:167], v[224:227], v[70:73]
	v_mfma_f32_16x16x32_bf16 v[66:69], v[172:175], v[224:227], v[66:69]
	v_mfma_f32_16x16x32_bf16 v[118:121], v[168:171], v[184:187], v[118:121]
	v_mfma_f32_16x16x32_bf16 v[114:117], v[176:179], v[184:187], v[114:117]
	v_mfma_f32_16x16x32_bf16 v[102:105], v[168:171], v[192:195], v[102:105]
	v_mfma_f32_16x16x32_bf16 v[98:101], v[176:179], v[192:195], v[98:101]
	v_mfma_f32_16x16x32_bf16 v[86:89], v[168:171], v[200:203], v[86:89]
	v_mfma_f32_16x16x32_bf16 v[82:85], v[176:179], v[200:203], v[82:85]
	v_mfma_f32_16x16x32_bf16 v[70:73], v[168:171], v[228:231], v[70:73]
	v_mfma_f32_16x16x32_bf16 v[66:69], v[176:179], v[228:231], v[66:69]
	s_barrier
; #define PG8_STAGE(bufoff, gbase, voff) do { _Pragma("unroll") for (int _i = 0; _i < 2; ++_i) \
;         __builtin_amdgcn_global_load_lds((const unsigned*)((const char*)(gbase) + (voff)[_i]), (PG8_LAS unsigned*)(lds + (bufoff) + ldsw + _i * 8192), 16, 0, 0); } while (0)
; #define PG8_LDA(dst, b, h) do { _Pragma("unroll") for (int m = 0; m < 4; ++m) _Pragma("unroll") for (int k = 0; k < 2; ++k) dst[m][k] = *(const PG8_LAS bf16x8*)(lds + PG8_SA(b, h) + aoff + m * 2048 + k * 1024); } while (0)
; #define PG8_MMA(ai, bj, At, Bt) do { __builtin_amdgcn_s_setprio(1); _Pragma("unroll") for (int m = 0; m < 4; ++m) _Pragma("unroll") for (int n = 0; n < 2; ++n) _Pragma("unroll") for (int k = 0; k < 2; ++k) \
;         acc[ai][bj][m][n] = __builtin_amdgcn_mfma_f32_16x16x32_bf16(Bt[n][k], At[m][k], acc[ai][bj][m][n], 0, 0, 0); __builtin_amdgcn_s_setprio(0); } while (0)
; #define PG8_WAIT_V(n) asm volatile("s_waitcnt vmcnt(" #n ")" ::: "memory")
; #define PG8_WAIT_L(n) asm volatile("s_waitcnt lgkmcnt(" #n ")" ::: "memory")
; #define PG8_BAR __builtin_amdgcn_s_barrier()
; #define PG8_SCHED __builtin_amdgcn_sched_barrier(0)
; template <class Epi, class Sched, bool ALIGN_EPI = false, bool SP2 = false>
; __device__ __forceinline__ void gemm_phase(PG8_LAS unsigned char* lds, const Gemm g, const Sched& S, const Epi& E) {
;     ...
;             PG8_LDA(At, 1, 1); PG8_STAGE(PG8_SB(1, 0), b3, voffB); PG8_STAGE(PG8_SB(1, 1), b3 + hstep, voffB); PG8_STAGE(PG8_SA(1, 0), a3, voffA);
;             PG8_WAIT_V(8); PG8_WAIT_L(0); PG8_BAR; PG8_MMA(1, 0, At, B0); PG8_MMA(1, 1, At, B1); PG8_BAR; PG8_SCHED;
;     __device__ __forceinline__ void operator()(const f32x4 (&acc)[2][2][4][2], const Unit& u, int wr, int wc, int fr, int fq) const {
;     ...
;                 const int row = row0 + ai * 128 + m * 16; float p = 0.f;
; #pragma unroll
;                 for (int bj = 0; bj < 2; ++bj) {
;                     const size_t off = (size_t)row * D + col0 + bj * 128;
;                     const u32x4 xx = *(const u32x4*)(xb + off);
	s_setprio 0
	s_add_i32 s14, s50, s23
	v_lshl_add_u64 v[138:139], v[138:139], 0, s[86:87]
	s_mov_b32 m0, s14
	ds_read_b128 v[180:183], v151 offset:49152
	ds_read_b128 v[184:187], v151 offset:50176
	ds_read_b128 v[188:191], v151 offset:51200
	ds_read_b128 v[192:195], v151 offset:52224
	ds_read_b128 v[196:199], v151 offset:53248
	ds_read_b128 v[200:203], v151 offset:54272
	ds_read_b128 v[224:227], v151 offset:55296
	ds_read_b128 v[228:231], v151 offset:56320
	global_load_lds_dwordx4 v[138:139], off
	s_add_i32 m0, s14, 0x2000
	s_add_u32 s14, s18, 0xb0080
	v_lshl_add_u64 v[138:139], v[140:141], 0, s[86:87]
	s_addc_u32 s15, s19, 0
	s_add_i32 s18, s51, s23
	global_load_lds_dwordx4 v[138:139], off
	v_lshl_add_u64 v[138:139], s[14:15], 0, v[0:1]
	s_mov_b32 m0, s18
	s_nop 0
	global_load_lds_dwordx4 v[138:139], off
	v_lshl_add_u64 v[138:139], s[14:15], 0, v[134:135]
	s_add_i32 m0, s18, 0x2000
	s_nop 0
	global_load_lds_dwordx4 v[138:139], off
	v_lshl_add_u64 v[138:139], v[204:205], 0, s[86:87]
	s_mov_b32 m0, s38
	s_nop 0
	global_load_lds_dwordx4 v[138:139], off
	v_lshl_add_u64 v[138:139], v[232:233], 0, s[86:87]
	s_mov_b32 m0, s39
	s_nop 0
	global_load_lds_dwordx4 v[138:139], off
	s_waitcnt vmcnt(8)
	s_waitcnt lgkmcnt(0)
	v_mfma_f32_16x16x32_bf16 v[62:65], v[144:147], v[180:183], v[62:65]
	v_mfma_f32_16x16x32_bf16 v[58:61], v[156:159], v[180:183], v[58:61]
	s_setprio 1
	s_barrier
	v_mfma_f32_16x16x32_bf16 v[46:49], v[144:147], v[188:191], v[46:49]
	v_mfma_f32_16x16x32_bf16 v[42:45], v[156:159], v[188:191], v[42:45]
	v_mfma_f32_16x16x32_bf16 v[30:33], v[144:147], v[196:199], v[30:33]
	v_mfma_f32_16x16x32_bf16 v[26:29], v[156:159], v[196:199], v[26:29]
	v_mfma_f32_16x16x32_bf16 v[14:17], v[144:147], v[224:227], v[14:17]
	v_mfma_f32_16x16x32_bf16 v[10:13], v[156:159], v[224:227], v[10:13]
	v_mfma_f32_16x16x32_bf16 v[62:65], v[152:155], v[184:187], v[62:65]
	v_mfma_f32_16x16x32_bf16 v[58:61], v[160:163], v[184:187], v[58:61]
	v_mfma_f32_16x16x32_bf16 v[46:49], v[152:155], v[192:195], v[46:49]
	v_mfma_f32_16x16x32_bf16 v[42:45], v[160:163], v[192:195], v[42:45]
	v_mfma_f32_16x16x32_bf16 v[30:33], v[152:155], v[200:203], v[30:33]
	v_mfma_f32_16x16x32_bf16 v[26:29], v[160:163], v[200:203], v[26:29]
	v_mfma_f32_16x16x32_bf16 v[14:17], v[152:155], v[228:231], v[14:17]
	v_mfma_f32_16x16x32_bf16 v[10:13], v[160:163], v[228:231], v[10:13]
	v_mfma_f32_16x16x32_bf16 v[54:57], v[164:167], v[180:183], v[54:57]
	v_mfma_f32_16x16x32_bf16 v[50:53], v[172:175], v[180:183], v[50:53]
	v_mfma_f32_16x16x32_bf16 v[38:41], v[164:167], v[188:191], v[38:41]
	v_mfma_f32_16x16x32_bf16 v[34:37], v[172:175], v[188:191], v[34:37]
	v_mfma_f32_16x16x32_bf16 v[22:25], v[164:167], v[196:199], v[22:25]
	v_mfma_f32_16x16x32_bf16 v[18:21], v[172:175], v[196:199], v[18:21]
	v_mfma_f32_16x16x32_bf16 v[6:9], v[164:167], v[224:227], v[6:9]
	v_mfma_f32_16x16x32_bf16 v[2:5], v[172:175], v[224:227], v[2:5]
	v_mfma_f32_16x16x32_bf16 v[54:57], v[168:171], v[184:187], v[54:57]
	v_mfma_f32_16x16x32_bf16 v[50:53], v[176:179], v[184:187], v[50:53]
	v_mfma_f32_16x16x32_bf16 v[38:41], v[168:171], v[192:195], v[38:41]
	v_mfma_f32_16x16x32_bf16 v[34:37], v[176:179], v[192:195], v[34:37]
	v_mfma_f32_16x16x32_bf16 v[22:25], v[168:171], v[200:203], v[22:25]
	v_mfma_f32_16x16x32_bf16 v[18:21], v[176:179], v[200:203], v[18:21]
	v_mfma_f32_16x16x32_bf16 v[6:9], v[168:171], v[228:231], v[6:9]
	v_mfma_f32_16x16x32_bf16 v[2:5], v[176:179], v[228:231], v[2:5]
	s_barrier
	s_setprio 0
	s_add_i32 s49, s49, 2
	s_add_u32 s47, s47, 0x100
	s_addc_u32 s48, s48, 0
	s_cmp_gt_u32 s49, 41
	s_mov_b64 s[14:15], s[16:17]
	s_cbranch_scc0 .LBB0_362
	v_lshl_add_u32 v138, s46, 8, v148
	v_lshl_or_b32 v139, s45, 8, v150
	v_lshlrev_b32_e32 v138, 11, v138
	v_lshl_add_u32 v138, v139, 1, v138
	global_load_dwordx4 v[152:155], v138, s[34:35]
	global_load_dwordx4 v[156:159], v138, s[34:35] offset:256
	v_add_u32_e32 v139, 0x8000, v138
	global_load_dwordx4 v[160:163], v139, s[34:35]
	global_load_dwordx4 v[164:167], v139, s[34:35] offset:256
	v_add_u32_e32 v139, 0x10000, v138
	global_load_dwordx4 v[168:171], v139, s[34:35]
	global_load_dwordx4 v[172:175], v139, s[34:35] offset:256
	v_add_u32_e32 v139, 0x18000, v138
	global_load_dwordx4 v[176:179], v139, s[34:35]
	global_load_dwordx4 v[180:183], v139, s[34:35] offset:256
	v_add_u32_e32 v139, 0x40000, v138
	global_load_dwordx4 v[184:187], v139, s[34:35]
	global_load_dwordx4 v[188:191], v139, s[34:35] offset:256
	v_add_u32_e32 v139, 0x48000, v138
	global_load_dwordx4 v[192:195], v139, s[34:35]
	global_load_dwordx4 v[196:199], v139, s[34:35] offset:256
	v_add_u32_e32 v139, 0x50000, v138
	global_load_dwordx4 v[200:203], v139, s[34:35]
	global_load_dwordx4 v[224:227], v139, s[34:35] offset:256
	v_add_u32_e32 v139, 0x58000, v138
	global_load_dwordx4 v[228:231], v139, s[34:35]
	global_load_dwordx4 v[232:235], v139, s[34:35] offset:256
	s_and_b64 vcc, exec, s[10:11]
	s_cbranch_vccz .LBB0_365
	s_barrier

; #define PG8_STAGE(bufoff, gbase, voff) do { _Pragma("unroll") for (int _i = 0; _i < 2; ++_i) \
;         __builtin_amdgcn_global_load_lds((const unsigned*)((const char*)(gbase) + (voff)[_i]), (PG8_LAS unsigned*)(lds + (bufoff) + ldsw + _i * 8192), 16, 0, 0); } while (0)
; #define PG8_LDA(dst, b, h) do { _Pragma("unroll") for (int m = 0; m < 4; ++m) _Pragma("unroll") for (int k = 0; k < 2; ++k) dst[m][k] = *(const PG8_LAS bf16x8*)(lds + PG8_SA(b, h) + aoff + m * 2048 + k * 1024); } while (0)
; #define PG8_LDB(dst, b, h) do { _Pragma("unroll") for (int n = 0; n < 2; ++n) _Pragma("unroll") for (int k = 0; k < 2; ++k) dst[n][k] = *(const PG8_LAS bf16x8*)(lds + PG8_SB(b, h) + boff + n * 2048 + k * 1024); } while (0)
; #define PG8_MMA(ai, bj, At, Bt) do { __builtin_amdgcn_s_setprio(1); _Pragma("unroll") for (int m = 0; m < 4; ++m) _Pragma("unroll") for (int n = 0; n < 2; ++n) _Pragma("unroll") for (int k = 0; k < 2; ++k) \
;         acc[ai][bj][m][n] = __builtin_amdgcn_mfma_f32_16x16x32_bf16(Bt[n][k], At[m][k], acc[ai][bj][m][n], 0, 0, 0); __builtin_amdgcn_s_setprio(0); } while (0)
; #define PG8_WAIT_V(n) asm volatile("s_waitcnt vmcnt(" #n ")" ::: "memory")
; template <class Epi, class Sched, bool ALIGN_EPI = false, bool SP2 = false>
; __device__ __forceinline__ void gemm_phase(PG8_LAS unsigned char* lds, const Gemm g, const Sched& S, const Epi& E) {
;     ...
;         const char* nA = has_next ? (const char*)g.A + (size_t)nxt.pm * tstep : cA; const char* nB = has_next ? (const char*)g.Bt + (size_t)nxt.pn * tstep : cB;
;         for (int t = 0; t < nt; t += 2) {
;             const bool last = (t == nt - 2);
;             const char* a1 = cA + (size_t)(t + 1) * kstep;
;             const char* a2 = last ? nA : cA + (size_t)(t + 2) * kstep; const char* b2 = last ? nB : cB + (size_t)(t + 2) * kstep;
;             const char* a3 = a2 + kstep; const char* b3 = b2 + kstep;
;             if (last && has_next) S.a_ready(nxt);
;             if constexpr (SP2) {
;             PG8_LDB(B0, 0, 0); PG8_LDB(B1, 0, 1); PG8_SCHED; PG8_LDA(At, 0, 0); PG8_STAGE(PG8_SA(1, 1), a1 + hstep, voffA);
;             PG8_WAIT_V(8); PG8_WAIT_L(0); PG8_BAR; PG8_MMA(0, 0, At, B0); PG8_MMA(0, 1, At, B1); PG8_BAR; PG8_SCHED;
;             PG8_LDA(At, 0, 1); PG8_STAGE(PG8_SB(0, 0), b2, voffB); PG8_STAGE(PG8_SB(0, 1), b2 + hstep, voffB); PG8_STAGE(PG8_SA(0, 0), a2, voffA);
.LBB0_491:
	s_ashr_i32 s15, s14, 31
	s_lshl_b64 s[16:17], s[14:15], 19
	s_add_u32 s16, s34, s16
	s_addc_u32 s17, s35, s17
	s_and_b64 s[18:19], s[2:3], exec
	s_cselect_b32 s5, s17, s9
	s_cselect_b32 s7, s16, s8
	s_ashr_i32 s13, s12, 31
	s_lshl_b64 s[18:19], s[12:13], 19
	s_add_u32 s18, s27, s18
	s_addc_u32 s19, s29, s19
	s_and_b64 s[22:23], s[2:3], exec
	s_cselect_b32 s13, s19, s21
	s_cselect_b32 s15, s18, s20
	s_add_u32 s8, s8, 0x40080
	s_addc_u32 s9, s9, 0
	s_add_u32 s45, s20, 0x100
	s_addc_u32 s46, s21, 0
	s_mov_b32 s47, -2
	s_add_u32 s20, s8, 0xfffc0080
	s_addc_u32 s21, s9, -1
	s_add_i32 s48, 0, 0x10000
	s_cmp_eq_u32 s47, 12
	s_cselect_b32 s23, s5, s21
	s_cselect_b32 s22, s7, s20
	v_add_u32_e32 v138, s48, v161
	s_cselect_b32 s21, s13, s46
	s_cselect_b32 s20, s15, s45
	s_add_i32 s50, 0, 0x14000
	ds_read_b128 v[144:147], v138
	ds_read_b128 v[148:151], v138 offset:1024
	ds_read_b128 v[152:155], v138 offset:2048
	ds_read_b128 v[156:159], v138 offset:3072
	v_add_u32_e32 v138, s50, v161
	ds_read_b128 v[166:169], v138
	ds_read_b128 v[170:173], v138 offset:1024
	ds_read_b128 v[174:177], v138 offset:2048
	ds_read_b128 v[178:181], v138 offset:3072
	v_lshl_add_u64 v[138:139], s[8:9], 0, v[136:137]
	s_add_i32 m0, s30, 0xc000
	ds_read_b128 v[182:185], v164
	ds_read_b128 v[186:189], v164 offset:1024
	ds_read_b128 v[190:193], v164 offset:2048
	ds_read_b128 v[194:197], v164 offset:3072
	ds_read_b128 v[198:201], v164 offset:4096
	ds_read_b128 v[202:205], v164 offset:5120
	ds_read_b128 v[224:227], v164 offset:6144
	ds_read_b128 v[228:231], v164 offset:7168
	global_load_lds_dwordx4 v[138:139], off
	v_lshl_add_u64 v[138:139], s[8:9], 0, v[142:143]
	s_add_i32 m0, s30, 0xe000
	s_nop 0
	global_load_lds_dwordx4 v[138:139], off
	s_waitcnt vmcnt(8)
	s_waitcnt lgkmcnt(0)
	v_mfma_f32_16x16x32_bf16 v[126:129], v[144:147], v[182:185], 0
	v_mfma_f32_16x16x32_bf16 v[122:125], v[152:155], v[182:185], 0
	s_setprio 1
	s_barrier
	v_mfma_f32_16x16x32_bf16 v[110:113], v[144:147], v[190:193], 0
	v_mfma_f32_16x16x32_bf16 v[106:109], v[152:155], v[190:193], 0
	v_mfma_f32_16x16x32_bf16 v[94:97], v[144:147], v[198:201], 0
	v_mfma_f32_16x16x32_bf16 v[90:93], v[152:155], v[198:201], 0
	v_mfma_f32_16x16x32_bf16 v[78:81], v[144:147], v[224:227], 0
	v_mfma_f32_16x16x32_bf16 v[74:77], v[152:155], v[224:227], 0
	v_mfma_f32_16x16x32_bf16 v[126:129], v[148:151], v[186:189], v[126:129]
	v_mfma_f32_16x16x32_bf16 v[122:125], v[156:159], v[186:189], v[122:125]
	v_mfma_f32_16x16x32_bf16 v[110:113], v[148:151], v[194:197], v[110:113]
	v_mfma_f32_16x16x32_bf16 v[106:109], v[156:159], v[194:197], v[106:109]
	v_mfma_f32_16x16x32_bf16 v[94:97], v[148:151], v[202:205], v[94:97]
	v_mfma_f32_16x16x32_bf16 v[90:93], v[156:159], v[202:205], v[90:93]
	v_mfma_f32_16x16x32_bf16 v[78:81], v[148:151], v[228:231], v[78:81]
	v_mfma_f32_16x16x32_bf16 v[74:77], v[156:159], v[228:231], v[74:77]
	v_mfma_f32_16x16x32_bf16 v[118:121], v[166:169], v[182:185], 0
	v_mfma_f32_16x16x32_bf16 v[114:117], v[174:177], v[182:185], 0
	v_mfma_f32_16x16x32_bf16 v[102:105], v[166:169], v[190:193], 0
	v_mfma_f32_16x16x32_bf16 v[98:101], v[174:177], v[190:193], 0
	v_mfma_f32_16x16x32_bf16 v[86:89], v[166:169], v[198:201], 0
	v_mfma_f32_16x16x32_bf16 v[82:85], v[174:177], v[198:201], 0
	v_mfma_f32_16x16x32_bf16 v[70:73], v[166:169], v[224:227], 0
	v_mfma_f32_16x16x32_bf16 v[66:69], v[174:177], v[224:227], 0
	v_mfma_f32_16x16x32_bf16 v[118:121], v[170:173], v[186:189], v[118:121]
	v_mfma_f32_16x16x32_bf16 v[114:117], v[178:181], v[186:189], v[114:117]
	v_mfma_f32_16x16x32_bf16 v[102:105], v[170:173], v[194:197], v[102:105]
	v_mfma_f32_16x16x32_bf16 v[98:101], v[178:181], v[194:197], v[98:101]
	v_mfma_f32_16x16x32_bf16 v[86:89], v[170:173], v[202:205], v[86:89]
	v_mfma_f32_16x16x32_bf16 v[82:85], v[178:181], v[202:205], v[82:85]
	v_mfma_f32_16x16x32_bf16 v[70:73], v[170:173], v[228:231], v[70:73]
	v_mfma_f32_16x16x32_bf16 v[66:69], v[178:181], v[228:231], v[66:69]
	s_barrier
	s_setprio 0
	s_add_i32 s48, s48, s26
	v_lshl_add_u64 v[138:139], s[20:21], 0, v[0:1]
	s_mov_b32 m0, s48
	ds_read_b128 v[182:185], v164 offset:16384
	ds_read_b128 v[186:189], v164 offset:17408
	ds_read_b128 v[190:193], v164 offset:18432
	ds_read_b128 v[194:197], v164 offset:19456
	ds_read_b128 v[198:201], v164 offset:20480
	ds_read_b128 v[202:205], v164 offset:21504
	ds_read_b128 v[224:227], v164 offset:22528
	ds_read_b128 v[228:231], v164 offset:23552
	global_load_lds_dwordx4 v[138:139], off
	s_add_i32 m0, s48, 0x2000
	s_add_u32 s48, s20, 0x40000
	v_lshl_add_u64 v[140:141], s[20:21], 0, v[134:135]
	s_addc_u32 s49, s21, 0
	s_add_i32 s50, s50, s26
	global_load_lds_dwordx4 v[140:141], off
	v_lshl_add_u64 v[232:233], s[48:49], 0, v[0:1]
	s_mov_b32 m0, s50
	v_lshl_add_u64 v[234:235], s[22:23], 0, v[132:133]
	global_load_lds_dwordx4 v[232:233], off
	v_lshl_add_u64 v[232:233], s[48:49], 0, v[134:135]
	s_add_i32 m0, s50, 0x2000
	s_nop 0
	global_load_lds_dwordx4 v[232:233], off
	v_lshl_add_u64 v[232:233], s[22:23], 0, v[130:131]
	s_mov_b32 m0, s30
	s_nop 0
	global_load_lds_dwordx4 v[232:233], off
	s_mov_b32 m0, s31
	s_nop 0
	global_load_lds_dwordx4 v[234:235], off
	s_waitcnt vmcnt(8)
	s_waitcnt lgkmcnt(0)
	v_mfma_f32_16x16x32_bf16 v[62:65], v[144:147], v[182:185], 0
	v_mfma_f32_16x16x32_bf16 v[58:61], v[152:155], v[182:185], 0
	s_setprio 1
	s_barrier
; #define PG8_STAGE(bufoff, gbase, voff) do { _Pragma("unroll") for (int _i = 0; _i < 2; ++_i) \
;         __builtin_amdgcn_global_load_lds((const unsigned*)((const char*)(gbase) + (voff)[_i]), (PG8_LAS unsigned*)(lds + (bufoff) + ldsw + _i * 8192), 16, 0, 0); } while (0)
; #define PG8_LDA(dst, b, h) do { _Pragma("unroll") for (int m = 0; m < 4; ++m) _Pragma("unroll") for (int k = 0; k < 2; ++k) dst[m][k] = *(const PG8_LAS bf16x8*)(lds + PG8_SA(b, h) + aoff + m * 2048 + k * 1024); } while (0)
; #define PG8_LDB(dst, b, h) do { _Pragma("unroll") for (int n = 0; n < 2; ++n) _Pragma("unroll") for (int k = 0; k < 2; ++k) dst[n][k] = *(const PG8_LAS bf16x8*)(lds + PG8_SB(b, h) + boff + n * 2048 + k * 1024); } while (0)
; #define PG8_MMA(ai, bj, At, Bt) do { __builtin_amdgcn_s_setprio(1); _Pragma("unroll") for (int m = 0; m < 4; ++m) _Pragma("unroll") for (int n = 0; n < 2; ++n) _Pragma("unroll") for (int k = 0; k < 2; ++k) \
;         acc[ai][bj][m][n] = __builtin_amdgcn_mfma_f32_16x16x32_bf16(Bt[n][k], At[m][k], acc[ai][bj][m][n], 0, 0, 0); __builtin_amdgcn_s_setprio(0); } while (0)
; #define PG8_WAIT_V(n) asm volatile("s_waitcnt vmcnt(" #n ")" ::: "memory")
; #define PG8_WAIT_L(n) asm volatile("s_waitcnt lgkmcnt(" #n ")" ::: "memory")
; #define PG8_BAR __builtin_amdgcn_s_barrier()
; #define PG8_SCHED __builtin_amdgcn_sched_barrier(0)
; template <class Epi, class Sched, bool ALIGN_EPI = false, bool SP2 = false>
; __device__ __forceinline__ void gemm_phase(PG8_LAS unsigned char* lds, const Gemm g, const Sched& S, const Epi& E) {
;     ...
;             PG8_WAIT_V(8); PG8_WAIT_L(0); PG8_BAR; PG8_MMA(1, 0, At, B0); PG8_MMA(1, 1, At, B1); PG8_BAR; PG8_SCHED;
;             PG8_LDB(B0, 1, 0); PG8_LDB(B1, 1, 1); PG8_SCHED; PG8_LDA(At, 1, 0); PG8_STAGE(PG8_SA(0, 1), a2 + hstep, voffA);
;             PG8_WAIT_V(8); PG8_WAIT_L(0); PG8_BAR; PG8_MMA(0, 0, At, B0); PG8_MMA(0, 1, At, B1); PG8_BAR; PG8_SCHED;
	v_mfma_f32_16x16x32_bf16 v[46:49], v[144:147], v[190:193], 0
	v_mfma_f32_16x16x32_bf16 v[42:45], v[152:155], v[190:193], 0
	v_mfma_f32_16x16x32_bf16 v[30:33], v[144:147], v[198:201], 0
	v_mfma_f32_16x16x32_bf16 v[26:29], v[152:155], v[198:201], 0
	v_mfma_f32_16x16x32_bf16 v[14:17], v[144:147], v[224:227], 0
	v_mfma_f32_16x16x32_bf16 v[10:13], v[152:155], v[224:227], 0
	v_mfma_f32_16x16x32_bf16 v[62:65], v[148:151], v[186:189], v[62:65]
	v_mfma_f32_16x16x32_bf16 v[58:61], v[156:159], v[186:189], v[58:61]
	v_mfma_f32_16x16x32_bf16 v[46:49], v[148:151], v[194:197], v[46:49]
	v_mfma_f32_16x16x32_bf16 v[42:45], v[156:159], v[194:197], v[42:45]
	v_mfma_f32_16x16x32_bf16 v[30:33], v[148:151], v[202:205], v[30:33]
	v_mfma_f32_16x16x32_bf16 v[26:29], v[156:159], v[202:205], v[26:29]
	v_mfma_f32_16x16x32_bf16 v[14:17], v[148:151], v[228:231], v[14:17]
	v_mfma_f32_16x16x32_bf16 v[10:13], v[156:159], v[228:231], v[10:13]
	v_mfma_f32_16x16x32_bf16 v[54:57], v[166:169], v[182:185], 0
	v_mfma_f32_16x16x32_bf16 v[50:53], v[174:177], v[182:185], 0
	v_mfma_f32_16x16x32_bf16 v[38:41], v[166:169], v[190:193], 0
	v_mfma_f32_16x16x32_bf16 v[34:37], v[174:177], v[190:193], 0
	v_mfma_f32_16x16x32_bf16 v[22:25], v[166:169], v[198:201], 0
	v_mfma_f32_16x16x32_bf16 v[18:21], v[174:177], v[198:201], 0
	v_mfma_f32_16x16x32_bf16 v[6:9], v[166:169], v[224:227], 0
	v_mfma_f32_16x16x32_bf16 v[2:5], v[174:177], v[224:227], 0
	v_mfma_f32_16x16x32_bf16 v[54:57], v[170:173], v[186:189], v[54:57]
	v_mfma_f32_16x16x32_bf16 v[50:53], v[178:181], v[186:189], v[50:53]
	v_mfma_f32_16x16x32_bf16 v[38:41], v[170:173], v[194:197], v[38:41]
	v_mfma_f32_16x16x32_bf16 v[34:37], v[178:181], v[194:197], v[34:37]
	v_mfma_f32_16x16x32_bf16 v[22:25], v[170:173], v[202:205], v[22:25]
	v_mfma_f32_16x16x32_bf16 v[18:21], v[178:181], v[202:205], v[18:21]
	v_mfma_f32_16x16x32_bf16 v[6:9], v[170:173], v[228:231], v[6:9]
	v_mfma_f32_16x16x32_bf16 v[2:5], v[178:181], v[228:231], v[2:5]
	s_barrier
	s_setprio 0
	s_add_i32 s48, 0, 0x18000
	s_add_i32 s49, 0, 0x1c000
	v_add_u32_e32 v156, s48, v161
	v_add_u32_e32 v165, s49, v161
	ds_read_b128 v[144:147], v156
	ds_read_b128 v[148:151], v156 offset:1024
	ds_read_b128 v[152:155], v156 offset:2048
	ds_read_b128 v[156:159], v156 offset:3072
	ds_read_b128 v[166:169], v165
	ds_read_b128 v[170:173], v165 offset:1024
	ds_read_b128 v[174:177], v165 offset:2048
	ds_read_b128 v[178:181], v165 offset:3072
	s_add_u32 s22, s22, 0x40000
	s_addc_u32 s23, s23, 0
	s_mov_b32 m0, s38
	v_lshl_add_u64 v[236:237], s[22:23], 0, v[130:131]
	ds_read_b128 v[182:185], v164 offset:32768
	ds_read_b128 v[186:189], v164 offset:33792
	ds_read_b128 v[190:193], v164 offset:34816
	ds_read_b128 v[194:197], v164 offset:35840
	ds_read_b128 v[198:201], v164 offset:36864
	ds_read_b128 v[202:205], v164 offset:37888
	ds_read_b128 v[224:227], v164 offset:38912
	ds_read_b128 v[228:231], v164 offset:39936
	global_load_lds_dwordx4 v[236:237], off
	v_lshl_add_u64 v[236:237], s[22:23], 0, v[132:133]
	s_mov_b32 m0, s39
	s_nop 0
	global_load_lds_dwordx4 v[236:237], off
	s_waitcnt vmcnt(8)
	s_waitcnt lgkmcnt(0)
	v_mfma_f32_16x16x32_bf16 v[126:129], v[144:147], v[182:185], v[126:129]
	v_mfma_f32_16x16x32_bf16 v[122:125], v[152:155], v[182:185], v[122:125]
	s_setprio 1
	s_barrier
	v_mfma_f32_16x16x32_bf16 v[110:113], v[144:147], v[190:193], v[110:113]
	v_mfma_f32_16x16x32_bf16 v[106:109], v[152:155], v[190:193], v[106:109]
	v_mfma_f32_16x16x32_bf16 v[94:97], v[144:147], v[198:201], v[94:97]
	v_mfma_f32_16x16x32_bf16 v[90:93], v[152:155], v[198:201], v[90:93]
	v_mfma_f32_16x16x32_bf16 v[78:81], v[144:147], v[224:227], v[78:81]
	v_mfma_f32_16x16x32_bf16 v[74:77], v[152:155], v[224:227], v[74:77]
	v_mfma_f32_16x16x32_bf16 v[126:129], v[148:151], v[186:189], v[126:129]
	v_mfma_f32_16x16x32_bf16 v[122:125], v[156:159], v[186:189], v[122:125]
	v_mfma_f32_16x16x32_bf16 v[110:113], v[148:151], v[194:197], v[110:113]
	v_mfma_f32_16x16x32_bf16 v[106:109], v[156:159], v[194:197], v[106:109]
	v_mfma_f32_16x16x32_bf16 v[94:97], v[148:151], v[202:205], v[94:97]
	v_mfma_f32_16x16x32_bf16 v[90:93], v[156:159], v[202:205], v[90:93]
	v_mfma_f32_16x16x32_bf16 v[78:81], v[148:151], v[228:231], v[78:81]
	v_mfma_f32_16x16x32_bf16 v[74:77], v[156:159], v[228:231], v[74:77]
	v_mfma_f32_16x16x32_bf16 v[118:121], v[166:169], v[182:185], v[118:121]
	v_mfma_f32_16x16x32_bf16 v[114:117], v[174:177], v[182:185], v[114:117]
	v_mfma_f32_16x16x32_bf16 v[102:105], v[166:169], v[190:193], v[102:105]
	v_mfma_f32_16x16x32_bf16 v[98:101], v[174:177], v[190:193], v[98:101]
	v_mfma_f32_16x16x32_bf16 v[86:89], v[166:169], v[198:201], v[86:89]
	v_mfma_f32_16x16x32_bf16 v[82:85], v[174:177], v[198:201], v[82:85]
	v_mfma_f32_16x16x32_bf16 v[70:73], v[166:169], v[224:227], v[70:73]
	v_mfma_f32_16x16x32_bf16 v[66:69], v[174:177], v[224:227], v[66:69]
	v_mfma_f32_16x16x32_bf16 v[118:121], v[170:173], v[186:189], v[118:121]
	v_mfma_f32_16x16x32_bf16 v[114:117], v[178:181], v[186:189], v[114:117]
	v_mfma_f32_16x16x32_bf16 v[102:105], v[170:173], v[194:197], v[102:105]
	v_mfma_f32_16x16x32_bf16 v[98:101], v[178:181], v[194:197], v[98:101]
	v_mfma_f32_16x16x32_bf16 v[86:89], v[170:173], v[202:205], v[86:89]
	v_mfma_f32_16x16x32_bf16 v[82:85], v[178:181], v[202:205], v[82:85]
	v_mfma_f32_16x16x32_bf16 v[70:73], v[170:173], v[228:231], v[70:73]
	v_mfma_f32_16x16x32_bf16 v[66:69], v[178:181], v[228:231], v[66:69]
	s_barrier
; #define PG8_STAGE(bufoff, gbase, voff) do { _Pragma("unroll") for (int _i = 0; _i < 2; ++_i) \
;         __builtin_amdgcn_global_load_lds((const unsigned*)((const char*)(gbase) + (voff)[_i]), (PG8_LAS unsigned*)(lds + (bufoff) + ldsw + _i * 8192), 16, 0, 0); } while (0)
; #define PG8_LDA(dst, b, h) do { _Pragma("unroll") for (int m = 0; m < 4; ++m) _Pragma("unroll") for (int k = 0; k < 2; ++k) dst[m][k] = *(const PG8_LAS bf16x8*)(lds + PG8_SA(b, h) + aoff + m * 2048 + k * 1024); } while (0)
; #define PG8_LDB(dst, b, h) do { _Pragma("unroll") for (int n = 0; n < 2; ++n) _Pragma("unroll") for (int k = 0; k < 2; ++k) dst[n][k] = *(const PG8_LAS bf16x8*)(lds + PG8_SB(b, h) + boff + n * 2048 + k * 1024); } while (0)
; #define PG8_MMA(ai, bj, At, Bt) do { __builtin_amdgcn_s_setprio(1); _Pragma("unroll") for (int m = 0; m < 4; ++m) _Pragma("unroll") for (int n = 0; n < 2; ++n) _Pragma("unroll") for (int k = 0; k < 2; ++k) \
;         acc[ai][bj][m][n] = __builtin_amdgcn_mfma_f32_16x16x32_bf16(Bt[n][k], At[m][k], acc[ai][bj][m][n], 0, 0, 0); __builtin_amdgcn_s_setprio(0); } while (0)
; #define PG8_WAIT_V(n) asm volatile("s_waitcnt vmcnt(" #n ")" ::: "memory")
; #define PG8_BAR __builtin_amdgcn_s_barrier()
; template <class Epi, class Sched, bool ALIGN_EPI = false, bool SP2 = false>
; __device__ __forceinline__ void gemm_phase(PG8_LAS unsigned char* lds, const Gemm g, const Sched& S, const Epi& E) {
;     ...
;         for (int t = 0; t < nt; t += 2) {
;             const bool last = (t == nt - 2);
;             const char* a1 = cA + (size_t)(t + 1) * kstep;
;             const char* a2 = last ? nA : cA + (size_t)(t + 2) * kstep; const char* b2 = last ? nB : cB + (size_t)(t + 2) * kstep;
;             const char* a3 = a2 + kstep; const char* b3 = b2 + kstep;
;             if (last && has_next) S.a_ready(nxt);
;             if constexpr (SP2) {
;             PG8_LDB(B0, 0, 0); PG8_LDB(B1, 0, 1); PG8_SCHED; PG8_LDA(At, 0, 0); PG8_STAGE(PG8_SA(1, 1), a1 + hstep, voffA);
;             PG8_WAIT_V(8); PG8_WAIT_L(0); PG8_BAR; PG8_MMA(0, 0, At, B0); PG8_MMA(0, 1, At, B1); PG8_BAR; PG8_SCHED;
;     ...
;             PG8_LDA(At, 1, 1); PG8_STAGE(PG8_SB(1, 0), b3, voffB); PG8_STAGE(PG8_SB(1, 1), b3 + hstep, voffB); PG8_STAGE(PG8_SA(1, 0), a3, voffA);
;             PG8_WAIT_V(8); PG8_WAIT_L(0); PG8_BAR; PG8_MMA(1, 0, At, B0); PG8_MMA(1, 1, At, B1); PG8_BAR; PG8_SCHED;
	s_setprio 0
	s_add_i32 s22, s48, s26
	v_lshl_add_u64 v[138:139], v[138:139], 0, s[86:87]
	s_mov_b32 m0, s22
	ds_read_b128 v[182:185], v164 offset:49152
	ds_read_b128 v[186:189], v164 offset:50176
	ds_read_b128 v[190:193], v164 offset:51200
	ds_read_b128 v[194:197], v164 offset:52224
	ds_read_b128 v[198:201], v164 offset:53248
	ds_read_b128 v[202:205], v164 offset:54272
	ds_read_b128 v[224:227], v164 offset:55296
	ds_read_b128 v[228:231], v164 offset:56320
	global_load_lds_dwordx4 v[138:139], off
	s_add_i32 m0, s22, 0x2000
	s_add_u32 s20, s20, 0x40080
	v_lshl_add_u64 v[138:139], v[140:141], 0, s[86:87]
	s_addc_u32 s21, s21, 0
	s_add_i32 s22, s49, s26
	global_load_lds_dwordx4 v[138:139], off
	v_lshl_add_u64 v[138:139], s[20:21], 0, v[0:1]
	s_mov_b32 m0, s22
	s_nop 0
	global_load_lds_dwordx4 v[138:139], off
	v_lshl_add_u64 v[138:139], s[20:21], 0, v[134:135]
	s_add_i32 m0, s22, 0x2000
	s_nop 0
	global_load_lds_dwordx4 v[138:139], off
	v_lshl_add_u64 v[138:139], v[232:233], 0, s[86:87]
	s_mov_b32 m0, s41
	s_nop 0
	global_load_lds_dwordx4 v[138:139], off
	v_lshl_add_u64 v[138:139], v[234:235], 0, s[86:87]
	s_mov_b32 m0, s42
	s_nop 0
	global_load_lds_dwordx4 v[138:139], off
	s_waitcnt vmcnt(8)
	s_waitcnt lgkmcnt(0)
	v_mfma_f32_16x16x32_bf16 v[62:65], v[144:147], v[182:185], v[62:65]
	v_mfma_f32_16x16x32_bf16 v[58:61], v[152:155], v[182:185], v[58:61]
	s_setprio 1
	s_barrier
	v_mfma_f32_16x16x32_bf16 v[46:49], v[144:147], v[190:193], v[46:49]
	v_mfma_f32_16x16x32_bf16 v[42:45], v[152:155], v[190:193], v[42:45]
	v_mfma_f32_16x16x32_bf16 v[30:33], v[144:147], v[198:201], v[30:33]
	v_mfma_f32_16x16x32_bf16 v[26:29], v[152:155], v[198:201], v[26:29]
	v_mfma_f32_16x16x32_bf16 v[14:17], v[144:147], v[224:227], v[14:17]
	v_mfma_f32_16x16x32_bf16 v[10:13], v[152:155], v[224:227], v[10:13]
	v_mfma_f32_16x16x32_bf16 v[62:65], v[148:151], v[186:189], v[62:65]
	v_mfma_f32_16x16x32_bf16 v[58:61], v[156:159], v[186:189], v[58:61]
	v_mfma_f32_16x16x32_bf16 v[46:49], v[148:151], v[194:197], v[46:49]
	v_mfma_f32_16x16x32_bf16 v[42:45], v[156:159], v[194:197], v[42:45]
	v_mfma_f32_16x16x32_bf16 v[30:33], v[148:151], v[202:205], v[30:33]
	v_mfma_f32_16x16x32_bf16 v[26:29], v[156:159], v[202:205], v[26:29]
	v_mfma_f32_16x16x32_bf16 v[14:17], v[148:151], v[228:231], v[14:17]
	v_mfma_f32_16x16x32_bf16 v[10:13], v[156:159], v[228:231], v[10:13]
	v_mfma_f32_16x16x32_bf16 v[54:57], v[166:169], v[182:185], v[54:57]
	v_mfma_f32_16x16x32_bf16 v[50:53], v[174:177], v[182:185], v[50:53]
	v_mfma_f32_16x16x32_bf16 v[38:41], v[166:169], v[190:193], v[38:41]
	v_mfma_f32_16x16x32_bf16 v[34:37], v[174:177], v[190:193], v[34:37]
	v_mfma_f32_16x16x32_bf16 v[22:25], v[166:169], v[198:201], v[22:25]
	v_mfma_f32_16x16x32_bf16 v[18:21], v[174:177], v[198:201], v[18:21]
	v_mfma_f32_16x16x32_bf16 v[6:9], v[166:169], v[224:227], v[6:9]
	v_mfma_f32_16x16x32_bf16 v[2:5], v[174:177], v[224:227], v[2:5]
	v_mfma_f32_16x16x32_bf16 v[54:57], v[170:173], v[186:189], v[54:57]
	v_mfma_f32_16x16x32_bf16 v[50:53], v[178:181], v[186:189], v[50:53]
	v_mfma_f32_16x16x32_bf16 v[38:41], v[170:173], v[194:197], v[38:41]
	v_mfma_f32_16x16x32_bf16 v[34:37], v[178:181], v[194:197], v[34:37]
	v_mfma_f32_16x16x32_bf16 v[22:25], v[170:173], v[202:205], v[22:25]
	v_mfma_f32_16x16x32_bf16 v[18:21], v[178:181], v[202:205], v[18:21]
	v_mfma_f32_16x16x32_bf16 v[6:9], v[170:173], v[228:231], v[6:9]
	v_mfma_f32_16x16x32_bf16 v[2:5], v[178:181], v[228:231], v[2:5]
	s_barrier
	s_setprio 0
	s_add_i32 s47, s47, 2
	s_add_u32 s8, s8, 0x100
	s_addc_u32 s9, s9, 0
	s_add_u32 s45, s45, 0x100
	s_addc_u32 s46, s46, 0
	s_cmp_gt_u32 s47, 13
	s_cbranch_scc1 .Lpeel_exit_pj
.LBB0_492:
	s_add_u32 s20, s8, 0xfffc0080
	s_addc_u32 s21, s9, -1
	s_add_i32 s48, 0, 0x10000
	s_cmp_eq_u32 s47, 12
	s_cselect_b32 s23, s5, s21
	s_cselect_b32 s22, s7, s20
	v_add_u32_e32 v138, s48, v161
	s_cselect_b32 s21, s13, s46
	s_cselect_b32 s20, s15, s45
	s_add_i32 s50, 0, 0x14000
	ds_read_b128 v[144:147], v138
	ds_read_b128 v[148:151], v138 offset:1024
	ds_read_b128 v[152:155], v138 offset:2048
	ds_read_b128 v[156:159], v138 offset:3072
	v_add_u32_e32 v138, s50, v161
	ds_read_b128 v[166:169], v138
	ds_read_b128 v[170:173], v138 offset:1024
	ds_read_b128 v[174:177], v138 offset:2048
	ds_read_b128 v[178:181], v138 offset:3072
	v_lshl_add_u64 v[138:139], s[8:9], 0, v[136:137]
	s_add_i32 m0, s30, 0xc000
	ds_read_b128 v[182:185], v164
	ds_read_b128 v[186:189], v164 offset:1024
	ds_read_b128 v[190:193], v164 offset:2048
	ds_read_b128 v[194:197], v164 offset:3072
	ds_read_b128 v[198:201], v164 offset:4096
	ds_read_b128 v[202:205], v164 offset:5120
	ds_read_b128 v[224:227], v164 offset:6144
	ds_read_b128 v[228:231], v164 offset:7168
	global_load_lds_dwordx4 v[138:139], off
	v_lshl_add_u64 v[138:139], s[8:9], 0, v[142:143]
	s_add_i32 m0, s30, 0xe000
	s_nop 0
	global_load_lds_dwordx4 v[138:139], off
	s_waitcnt vmcnt(8)
	s_waitcnt lgkmcnt(0)
	v_mfma_f32_16x16x32_bf16 v[126:129], v[144:147], v[182:185], v[126:129]
	v_mfma_f32_16x16x32_bf16 v[122:125], v[152:155], v[182:185], v[122:125]
	s_setprio 1
	s_barrier
; #define PG8_STAGE(bufoff, gbase, voff) do { _Pragma("unroll") for (int _i = 0; _i < 2; ++_i) \
;         __builtin_amdgcn_global_load_lds((const unsigned*)((const char*)(gbase) + (voff)[_i]), (PG8_LAS unsigned*)(lds + (bufoff) + ldsw + _i * 8192), 16, 0, 0); } while (0)
; #define PG8_LDA(dst, b, h) do { _Pragma("unroll") for (int m = 0; m < 4; ++m) _Pragma("unroll") for (int k = 0; k < 2; ++k) dst[m][k] = *(const PG8_LAS bf16x8*)(lds + PG8_SA(b, h) + aoff + m * 2048 + k * 1024); } while (0)
; #define PG8_LDB(dst, b, h) do { _Pragma("unroll") for (int n = 0; n < 2; ++n) _Pragma("unroll") for (int k = 0; k < 2; ++k) dst[n][k] = *(const PG8_LAS bf16x8*)(lds + PG8_SB(b, h) + boff + n * 2048 + k * 1024); } while (0)
; #define PG8_MMA(ai, bj, At, Bt) do { __builtin_amdgcn_s_setprio(1); _Pragma("unroll") for (int m = 0; m < 4; ++m) _Pragma("unroll") for (int n = 0; n < 2; ++n) _Pragma("unroll") for (int k = 0; k < 2; ++k) \
;         acc[ai][bj][m][n] = __builtin_amdgcn_mfma_f32_16x16x32_bf16(Bt[n][k], At[m][k], acc[ai][bj][m][n], 0, 0, 0); __builtin_amdgcn_s_setprio(0); } while (0)
; #define PG8_WAIT_V(n) asm volatile("s_waitcnt vmcnt(" #n ")" ::: "memory")
; #define PG8_WAIT_L(n) asm volatile("s_waitcnt lgkmcnt(" #n ")" ::: "memory")
; #define PG8_BAR __builtin_amdgcn_s_barrier()
; #define PG8_SCHED __builtin_amdgcn_sched_barrier(0)
; template <class Epi, class Sched, bool ALIGN_EPI = false, bool SP2 = false>
; __device__ __forceinline__ void gemm_phase(PG8_LAS unsigned char* lds, const Gemm g, const Sched& S, const Epi& E) {
;     ...
;             PG8_LDB(B0, 0, 0); PG8_LDB(B1, 0, 1); PG8_SCHED; PG8_LDA(At, 0, 0); PG8_STAGE(PG8_SA(1, 1), a1 + hstep, voffA);
;             PG8_WAIT_V(8); PG8_WAIT_L(0); PG8_BAR; PG8_MMA(0, 0, At, B0); PG8_MMA(0, 1, At, B1); PG8_BAR; PG8_SCHED;
;             PG8_LDA(At, 0, 1); PG8_STAGE(PG8_SB(0, 0), b2, voffB); PG8_STAGE(PG8_SB(0, 1), b2 + hstep, voffB); PG8_STAGE(PG8_SA(0, 0), a2, voffA);
;             PG8_WAIT_V(8); PG8_WAIT_L(0); PG8_BAR; PG8_MMA(1, 0, At, B0); PG8_MMA(1, 1, At, B1); PG8_BAR; PG8_SCHED;
;             PG8_LDB(B0, 1, 0); PG8_LDB(B1, 1, 1); PG8_SCHED; PG8_LDA(At, 1, 0); PG8_STAGE(PG8_SA(0, 1), a2 + hstep, voffA);
;             PG8_WAIT_V(8); PG8_WAIT_L(0); PG8_BAR; PG8_MMA(0, 0, At, B0); PG8_MMA(0, 1, At, B1); PG8_BAR; PG8_SCHED;
	v_mfma_f32_16x16x32_bf16 v[110:113], v[144:147], v[190:193], v[110:113]
	v_mfma_f32_16x16x32_bf16 v[106:109], v[152:155], v[190:193], v[106:109]
	v_mfma_f32_16x16x32_bf16 v[94:97], v[144:147], v[198:201], v[94:97]
	v_mfma_f32_16x16x32_bf16 v[90:93], v[152:155], v[198:201], v[90:93]
	v_mfma_f32_16x16x32_bf16 v[78:81], v[144:147], v[224:227], v[78:81]
	v_mfma_f32_16x16x32_bf16 v[74:77], v[152:155], v[224:227], v[74:77]
	v_mfma_f32_16x16x32_bf16 v[126:129], v[148:151], v[186:189], v[126:129]
	v_mfma_f32_16x16x32_bf16 v[122:125], v[156:159], v[186:189], v[122:125]
	v_mfma_f32_16x16x32_bf16 v[110:113], v[148:151], v[194:197], v[110:113]
	v_mfma_f32_16x16x32_bf16 v[106:109], v[156:159], v[194:197], v[106:109]
	v_mfma_f32_16x16x32_bf16 v[94:97], v[148:151], v[202:205], v[94:97]
	v_mfma_f32_16x16x32_bf16 v[90:93], v[156:159], v[202:205], v[90:93]
	v_mfma_f32_16x16x32_bf16 v[78:81], v[148:151], v[228:231], v[78:81]
	v_mfma_f32_16x16x32_bf16 v[74:77], v[156:159], v[228:231], v[74:77]
	v_mfma_f32_16x16x32_bf16 v[118:121], v[166:169], v[182:185], v[118:121]
	v_mfma_f32_16x16x32_bf16 v[114:117], v[174:177], v[182:185], v[114:117]
	v_mfma_f32_16x16x32_bf16 v[102:105], v[166:169], v[190:193], v[102:105]
	v_mfma_f32_16x16x32_bf16 v[98:101], v[174:177], v[190:193], v[98:101]
	v_mfma_f32_16x16x32_bf16 v[86:89], v[166:169], v[198:201], v[86:89]
	v_mfma_f32_16x16x32_bf16 v[82:85], v[174:177], v[198:201], v[82:85]
	v_mfma_f32_16x16x32_bf16 v[70:73], v[166:169], v[224:227], v[70:73]
	v_mfma_f32_16x16x32_bf16 v[66:69], v[174:177], v[224:227], v[66:69]
	v_mfma_f32_16x16x32_bf16 v[118:121], v[170:173], v[186:189], v[118:121]
	v_mfma_f32_16x16x32_bf16 v[114:117], v[178:181], v[186:189], v[114:117]
	v_mfma_f32_16x16x32_bf16 v[102:105], v[170:173], v[194:197], v[102:105]
	v_mfma_f32_16x16x32_bf16 v[98:101], v[178:181], v[194:197], v[98:101]
	v_mfma_f32_16x16x32_bf16 v[86:89], v[170:173], v[202:205], v[86:89]
	v_mfma_f32_16x16x32_bf16 v[82:85], v[178:181], v[202:205], v[82:85]
	v_mfma_f32_16x16x32_bf16 v[70:73], v[170:173], v[228:231], v[70:73]
	v_mfma_f32_16x16x32_bf16 v[66:69], v[178:181], v[228:231], v[66:69]
	s_barrier
	s_setprio 0
	s_add_i32 s48, s48, s26
	v_lshl_add_u64 v[138:139], s[20:21], 0, v[0:1]
	s_mov_b32 m0, s48
	ds_read_b128 v[182:185], v164 offset:16384
	ds_read_b128 v[186:189], v164 offset:17408
	ds_read_b128 v[190:193], v164 offset:18432
	ds_read_b128 v[194:197], v164 offset:19456
	ds_read_b128 v[198:201], v164 offset:20480
	ds_read_b128 v[202:205], v164 offset:21504
	ds_read_b128 v[224:227], v164 offset:22528
	ds_read_b128 v[228:231], v164 offset:23552
	global_load_lds_dwordx4 v[138:139], off
	s_add_i32 m0, s48, 0x2000
	s_add_u32 s48, s20, 0x40000
	v_lshl_add_u64 v[140:141], s[20:21], 0, v[134:135]
	s_addc_u32 s49, s21, 0
	s_add_i32 s50, s50, s26
	global_load_lds_dwordx4 v[140:141], off
	v_lshl_add_u64 v[232:233], s[48:49], 0, v[0:1]
	s_mov_b32 m0, s50
	v_lshl_add_u64 v[234:235], s[22:23], 0, v[132:133]
	global_load_lds_dwordx4 v[232:233], off
	v_lshl_add_u64 v[232:233], s[48:49], 0, v[134:135]
	s_add_i32 m0, s50, 0x2000
	s_nop 0
	global_load_lds_dwordx4 v[232:233], off
	v_lshl_add_u64 v[232:233], s[22:23], 0, v[130:131]
	s_mov_b32 m0, s30
	s_nop 0
	global_load_lds_dwordx4 v[232:233], off
	s_mov_b32 m0, s31
	s_nop 0
	global_load_lds_dwordx4 v[234:235], off
	s_waitcnt vmcnt(8)
	s_waitcnt lgkmcnt(0)
	v_mfma_f32_16x16x32_bf16 v[62:65], v[144:147], v[182:185], v[62:65]
	v_mfma_f32_16x16x32_bf16 v[58:61], v[152:155], v[182:185], v[58:61]
	s_setprio 1
	s_barrier
	v_mfma_f32_16x16x32_bf16 v[46:49], v[144:147], v[190:193], v[46:49]
	v_mfma_f32_16x16x32_bf16 v[42:45], v[152:155], v[190:193], v[42:45]
	v_mfma_f32_16x16x32_bf16 v[30:33], v[144:147], v[198:201], v[30:33]
	v_mfma_f32_16x16x32_bf16 v[26:29], v[152:155], v[198:201], v[26:29]
	v_mfma_f32_16x16x32_bf16 v[14:17], v[144:147], v[224:227], v[14:17]
	v_mfma_f32_16x16x32_bf16 v[10:13], v[152:155], v[224:227], v[10:13]
	v_mfma_f32_16x16x32_bf16 v[62:65], v[148:151], v[186:189], v[62:65]
	v_mfma_f32_16x16x32_bf16 v[58:61], v[156:159], v[186:189], v[58:61]
	v_mfma_f32_16x16x32_bf16 v[46:49], v[148:151], v[194:197], v[46:49]
	v_mfma_f32_16x16x32_bf16 v[42:45], v[156:159], v[194:197], v[42:45]
	v_mfma_f32_16x16x32_bf16 v[30:33], v[148:151], v[202:205], v[30:33]
	v_mfma_f32_16x16x32_bf16 v[26:29], v[156:159], v[202:205], v[26:29]
	v_mfma_f32_16x16x32_bf16 v[14:17], v[148:151], v[228:231], v[14:17]
	v_mfma_f32_16x16x32_bf16 v[10:13], v[156:159], v[228:231], v[10:13]
	v_mfma_f32_16x16x32_bf16 v[54:57], v[166:169], v[182:185], v[54:57]
	v_mfma_f32_16x16x32_bf16 v[50:53], v[174:177], v[182:185], v[50:53]
	v_mfma_f32_16x16x32_bf16 v[38:41], v[166:169], v[190:193], v[38:41]
	v_mfma_f32_16x16x32_bf16 v[34:37], v[174:177], v[190:193], v[34:37]
	v_mfma_f32_16x16x32_bf16 v[22:25], v[166:169], v[198:201], v[22:25]
	v_mfma_f32_16x16x32_bf16 v[18:21], v[174:177], v[198:201], v[18:21]
	v_mfma_f32_16x16x32_bf16 v[6:9], v[166:169], v[224:227], v[6:9]
	v_mfma_f32_16x16x32_bf16 v[2:5], v[174:177], v[224:227], v[2:5]
	v_mfma_f32_16x16x32_bf16 v[54:57], v[170:173], v[186:189], v[54:57]
	v_mfma_f32_16x16x32_bf16 v[50:53], v[178:181], v[186:189], v[50:53]
	v_mfma_f32_16x16x32_bf16 v[38:41], v[170:173], v[194:197], v[38:41]
	v_mfma_f32_16x16x32_bf16 v[34:37], v[178:181], v[194:197], v[34:37]
	v_mfma_f32_16x16x32_bf16 v[22:25], v[170:173], v[202:205], v[22:25]
	v_mfma_f32_16x16x32_bf16 v[18:21], v[178:181], v[202:205], v[18:21]
	v_mfma_f32_16x16x32_bf16 v[6:9], v[170:173], v[228:231], v[6:9]
	v_mfma_f32_16x16x32_bf16 v[2:5], v[178:181], v[228:231], v[2:5]
	s_barrier
; #define PG8_STAGE(bufoff, gbase, voff) do { _Pragma("unroll") for (int _i = 0; _i < 2; ++_i) \
;         __builtin_amdgcn_global_load_lds((const unsigned*)((const char*)(gbase) + (voff)[_i]), (PG8_LAS unsigned*)(lds + (bufoff) + ldsw + _i * 8192), 16, 0, 0); } while (0)
; #define PG8_LDA(dst, b, h) do { _Pragma("unroll") for (int m = 0; m < 4; ++m) _Pragma("unroll") for (int k = 0; k < 2; ++k) dst[m][k] = *(const PG8_LAS bf16x8*)(lds + PG8_SA(b, h) + aoff + m * 2048 + k * 1024); } while (0)
; #define PG8_LDB(dst, b, h) do { _Pragma("unroll") for (int n = 0; n < 2; ++n) _Pragma("unroll") for (int k = 0; k < 2; ++k) dst[n][k] = *(const PG8_LAS bf16x8*)(lds + PG8_SB(b, h) + boff + n * 2048 + k * 1024); } while (0)
; #define PG8_MMA(ai, bj, At, Bt) do { __builtin_amdgcn_s_setprio(1); _Pragma("unroll") for (int m = 0; m < 4; ++m) _Pragma("unroll") for (int n = 0; n < 2; ++n) _Pragma("unroll") for (int k = 0; k < 2; ++k) \
;         acc[ai][bj][m][n] = __builtin_amdgcn_mfma_f32_16x16x32_bf16(Bt[n][k], At[m][k], acc[ai][bj][m][n], 0, 0, 0); __builtin_amdgcn_s_setprio(0); } while (0)
; #define PG8_WAIT_V(n) asm volatile("s_waitcnt vmcnt(" #n ")" ::: "memory")
; #define PG8_WAIT_L(n) asm volatile("s_waitcnt lgkmcnt(" #n ")" ::: "memory")
; #define PG8_BAR __builtin_amdgcn_s_barrier()
; #define PG8_SCHED __builtin_amdgcn_sched_barrier(0)
; template <class Epi, class Sched, bool ALIGN_EPI = false, bool SP2 = false>
; __device__ __forceinline__ void gemm_phase(PG8_LAS unsigned char* lds, const Gemm g, const Sched& S, const Epi& E) {
;     ...
;             PG8_LDB(B0, 1, 0); PG8_LDB(B1, 1, 1); PG8_SCHED; PG8_LDA(At, 1, 0); PG8_STAGE(PG8_SA(0, 1), a2 + hstep, voffA);
;             PG8_WAIT_V(8); PG8_WAIT_L(0); PG8_BAR; PG8_MMA(0, 0, At, B0); PG8_MMA(0, 1, At, B1); PG8_BAR; PG8_SCHED;
	s_setprio 0
	s_add_i32 s48, 0, 0x18000
	s_add_i32 s49, 0, 0x1c000
	v_add_u32_e32 v156, s48, v161
	v_add_u32_e32 v165, s49, v161
	ds_read_b128 v[144:147], v156
	ds_read_b128 v[148:151], v156 offset:1024
	ds_read_b128 v[152:155], v156 offset:2048
	ds_read_b128 v[156:159], v156 offset:3072
	ds_read_b128 v[166:169], v165
	ds_read_b128 v[170:173], v165 offset:1024
	ds_read_b128 v[174:177], v165 offset:2048
	ds_read_b128 v[178:181], v165 offset:3072
	s_add_u32 s22, s22, 0x40000
	s_addc_u32 s23, s23, 0
	s_mov_b32 m0, s38
	v_lshl_add_u64 v[236:237], s[22:23], 0, v[130:131]
	ds_read_b128 v[182:185], v164 offset:32768
	ds_read_b128 v[186:189], v164 offset:33792
	ds_read_b128 v[190:193], v164 offset:34816
	ds_read_b128 v[194:197], v164 offset:35840
	ds_read_b128 v[198:201], v164 offset:36864
	ds_read_b128 v[202:205], v164 offset:37888
	ds_read_b128 v[224:227], v164 offset:38912
	ds_read_b128 v[228:231], v164 offset:39936
	global_load_lds_dwordx4 v[236:237], off
	v_lshl_add_u64 v[236:237], s[22:23], 0, v[132:133]
	s_mov_b32 m0, s39
	s_nop 0
	global_load_lds_dwordx4 v[236:237], off
	s_waitcnt vmcnt(8)
	s_waitcnt lgkmcnt(0)
	v_mfma_f32_16x16x32_bf16 v[126:129], v[144:147], v[182:185], v[126:129]
	v_mfma_f32_16x16x32_bf16 v[122:125], v[152:155], v[182:185], v[122:125]
	s_setprio 1
	s_barrier
	v_mfma_f32_16x16x32_bf16 v[110:113], v[144:147], v[190:193], v[110:113]
	v_mfma_f32_16x16x32_bf16 v[106:109], v[152:155], v[190:193], v[106:109]
	v_mfma_f32_16x16x32_bf16 v[94:97], v[144:147], v[198:201], v[94:97]
	v_mfma_f32_16x16x32_bf16 v[90:93], v[152:155], v[198:201], v[90:93]
	v_mfma_f32_16x16x32_bf16 v[78:81], v[144:147], v[224:227], v[78:81]
	v_mfma_f32_16x16x32_bf16 v[74:77], v[152:155], v[224:227], v[74:77]
	v_mfma_f32_16x16x32_bf16 v[126:129], v[148:151], v[186:189], v[126:129]
	v_mfma_f32_16x16x32_bf16 v[122:125], v[156:159], v[186:189], v[122:125]
	v_mfma_f32_16x16x32_bf16 v[110:113], v[148:151], v[194:197], v[110:113]
	v_mfma_f32_16x16x32_bf16 v[106:109], v[156:159], v[194:197], v[106:109]
	v_mfma_f32_16x16x32_bf16 v[94:97], v[148:151], v[202:205], v[94:97]
	v_mfma_f32_16x16x32_bf16 v[90:93], v[156:159], v[202:205], v[90:93]
	v_mfma_f32_16x16x32_bf16 v[78:81], v[148:151], v[228:231], v[78:81]
	v_mfma_f32_16x16x32_bf16 v[74:77], v[156:159], v[228:231], v[74:77]
	v_mfma_f32_16x16x32_bf16 v[118:121], v[166:169], v[182:185], v[118:121]
	v_mfma_f32_16x16x32_bf16 v[114:117], v[174:177], v[182:185], v[114:117]
	v_mfma_f32_16x16x32_bf16 v[102:105], v[166:169], v[190:193], v[102:105]
	v_mfma_f32_16x16x32_bf16 v[98:101], v[174:177], v[190:193], v[98:101]
	v_mfma_f32_16x16x32_bf16 v[86:89], v[166:169], v[198:201], v[86:89]
	v_mfma_f32_16x16x32_bf16 v[82:85], v[174:177], v[198:201], v[82:85]
	v_mfma_f32_16x16x32_bf16 v[70:73], v[166:169], v[224:227], v[70:73]
	v_mfma_f32_16x16x32_bf16 v[66:69], v[174:177], v[224:227], v[66:69]
	v_mfma_f32_16x16x32_bf16 v[118:121], v[170:173], v[186:189], v[118:121]
	v_mfma_f32_16x16x32_bf16 v[114:117], v[178:181], v[186:189], v[114:117]
	v_mfma_f32_16x16x32_bf16 v[102:105], v[170:173], v[194:197], v[102:105]
	v_mfma_f32_16x16x32_bf16 v[98:101], v[178:181], v[194:197], v[98:101]
	v_mfma_f32_16x16x32_bf16 v[86:89], v[170:173], v[202:205], v[86:89]
	v_mfma_f32_16x16x32_bf16 v[82:85], v[178:181], v[202:205], v[82:85]
	v_mfma_f32_16x16x32_bf16 v[70:73], v[170:173], v[228:231], v[70:73]
	v_mfma_f32_16x16x32_bf16 v[66:69], v[178:181], v[228:231], v[66:69]
	s_barrier
; #define PG8_STAGE(bufoff, gbase, voff) do { _Pragma("unroll") for (int _i = 0; _i < 2; ++_i) \
;         __builtin_amdgcn_global_load_lds((const unsigned*)((const char*)(gbase) + (voff)[_i]), (PG8_LAS unsigned*)(lds + (bufoff) + ldsw + _i * 8192), 16, 0, 0); } while (0)
; #define PG8_LDA(dst, b, h) do { _Pragma("unroll") for (int m = 0; m < 4; ++m) _Pragma("unroll") for (int k = 0; k < 2; ++k) dst[m][k] = *(const PG8_LAS bf16x8*)(lds + PG8_SA(b, h) + aoff + m * 2048 + k * 1024); } while (0)
; #define PG8_MMA(ai, bj, At, Bt) do { __builtin_amdgcn_s_setprio(1); _Pragma("unroll") for (int m = 0; m < 4; ++m) _Pragma("unroll") for (int n = 0; n < 2; ++n) _Pragma("unroll") for (int k = 0; k < 2; ++k) \
;         acc[ai][bj][m][n] = __builtin_amdgcn_mfma_f32_16x16x32_bf16(Bt[n][k], At[m][k], acc[ai][bj][m][n], 0, 0, 0); __builtin_amdgcn_s_setprio(0); } while (0)
; #define PG8_WAIT_V(n) asm volatile("s_waitcnt vmcnt(" #n ")" ::: "memory")
; #define PG8_WAIT_L(n) asm volatile("s_waitcnt lgkmcnt(" #n ")" ::: "memory")
; #define PG8_BAR __builtin_amdgcn_s_barrier()
; #define PG8_SCHED __builtin_amdgcn_sched_barrier(0)
; template <class Epi, class Sched, bool ALIGN_EPI = false, bool SP2 = false>
; __device__ __forceinline__ void gemm_phase(PG8_LAS unsigned char* lds, const Gemm g, const Sched& S, const Epi& E) {
;     ...
;         for (int t = 0; t < nt; t += 2) {
;     ...
;             PG8_LDA(At, 1, 1); PG8_STAGE(PG8_SB(1, 0), b3, voffB); PG8_STAGE(PG8_SB(1, 1), b3 + hstep, voffB); PG8_STAGE(PG8_SA(1, 0), a3, voffA);
;             PG8_WAIT_V(8); PG8_WAIT_L(0); PG8_BAR; PG8_MMA(1, 0, At, B0); PG8_MMA(1, 1, At, B1); PG8_BAR; PG8_SCHED;
	s_setprio 0
	s_add_i32 s22, s48, s26
	v_lshl_add_u64 v[138:139], v[138:139], 0, s[86:87]
	s_mov_b32 m0, s22
	ds_read_b128 v[182:185], v164 offset:49152
	ds_read_b128 v[186:189], v164 offset:50176
	ds_read_b128 v[190:193], v164 offset:51200
	ds_read_b128 v[194:197], v164 offset:52224
	ds_read_b128 v[198:201], v164 offset:53248
	ds_read_b128 v[202:205], v164 offset:54272
	ds_read_b128 v[224:227], v164 offset:55296
	ds_read_b128 v[228:231], v164 offset:56320
	global_load_lds_dwordx4 v[138:139], off
	s_add_i32 m0, s22, 0x2000
	s_add_u32 s20, s20, 0x40080
	v_lshl_add_u64 v[138:139], v[140:141], 0, s[86:87]
	s_addc_u32 s21, s21, 0
	s_add_i32 s22, s49, s26
	global_load_lds_dwordx4 v[138:139], off
	v_lshl_add_u64 v[138:139], s[20:21], 0, v[0:1]
	s_mov_b32 m0, s22
	s_nop 0
	global_load_lds_dwordx4 v[138:139], off
	v_lshl_add_u64 v[138:139], s[20:21], 0, v[134:135]
	s_add_i32 m0, s22, 0x2000
	s_nop 0
	global_load_lds_dwordx4 v[138:139], off
	v_lshl_add_u64 v[138:139], v[232:233], 0, s[86:87]
	s_mov_b32 m0, s41
	s_nop 0
	global_load_lds_dwordx4 v[138:139], off
	v_lshl_add_u64 v[138:139], v[234:235], 0, s[86:87]
	s_mov_b32 m0, s42
	s_nop 0
	global_load_lds_dwordx4 v[138:139], off
	s_waitcnt vmcnt(8)
	s_waitcnt lgkmcnt(0)
	v_mfma_f32_16x16x32_bf16 v[62:65], v[144:147], v[182:185], v[62:65]
	v_mfma_f32_16x16x32_bf16 v[58:61], v[152:155], v[182:185], v[58:61]
	s_setprio 1
	s_barrier
	v_mfma_f32_16x16x32_bf16 v[46:49], v[144:147], v[190:193], v[46:49]
	v_mfma_f32_16x16x32_bf16 v[42:45], v[152:155], v[190:193], v[42:45]
	v_mfma_f32_16x16x32_bf16 v[30:33], v[144:147], v[198:201], v[30:33]
	v_mfma_f32_16x16x32_bf16 v[26:29], v[152:155], v[198:201], v[26:29]
	v_mfma_f32_16x16x32_bf16 v[14:17], v[144:147], v[224:227], v[14:17]
	v_mfma_f32_16x16x32_bf16 v[10:13], v[152:155], v[224:227], v[10:13]
	v_mfma_f32_16x16x32_bf16 v[62:65], v[148:151], v[186:189], v[62:65]
	v_mfma_f32_16x16x32_bf16 v[58:61], v[156:159], v[186:189], v[58:61]
	v_mfma_f32_16x16x32_bf16 v[46:49], v[148:151], v[194:197], v[46:49]
	v_mfma_f32_16x16x32_bf16 v[42:45], v[156:159], v[194:197], v[42:45]
	v_mfma_f32_16x16x32_bf16 v[30:33], v[148:151], v[202:205], v[30:33]
	v_mfma_f32_16x16x32_bf16 v[26:29], v[156:159], v[202:205], v[26:29]
	v_mfma_f32_16x16x32_bf16 v[14:17], v[148:151], v[228:231], v[14:17]
	v_mfma_f32_16x16x32_bf16 v[10:13], v[156:159], v[228:231], v[10:13]
	v_mfma_f32_16x16x32_bf16 v[54:57], v[166:169], v[182:185], v[54:57]
	v_mfma_f32_16x16x32_bf16 v[50:53], v[174:177], v[182:185], v[50:53]
	v_mfma_f32_16x16x32_bf16 v[38:41], v[166:169], v[190:193], v[38:41]
	v_mfma_f32_16x16x32_bf16 v[34:37], v[174:177], v[190:193], v[34:37]
	v_mfma_f32_16x16x32_bf16 v[22:25], v[166:169], v[198:201], v[22:25]
	v_mfma_f32_16x16x32_bf16 v[18:21], v[174:177], v[198:201], v[18:21]
	v_mfma_f32_16x16x32_bf16 v[6:9], v[166:169], v[224:227], v[6:9]
	v_mfma_f32_16x16x32_bf16 v[2:5], v[174:177], v[224:227], v[2:5]
	v_mfma_f32_16x16x32_bf16 v[54:57], v[170:173], v[186:189], v[54:57]
	v_mfma_f32_16x16x32_bf16 v[50:53], v[178:181], v[186:189], v[50:53]
	v_mfma_f32_16x16x32_bf16 v[38:41], v[170:173], v[194:197], v[38:41]
	v_mfma_f32_16x16x32_bf16 v[34:37], v[178:181], v[194:197], v[34:37]
	v_mfma_f32_16x16x32_bf16 v[22:25], v[170:173], v[202:205], v[22:25]
	v_mfma_f32_16x16x32_bf16 v[18:21], v[178:181], v[202:205], v[18:21]
	v_mfma_f32_16x16x32_bf16 v[6:9], v[170:173], v[228:231], v[6:9]
	v_mfma_f32_16x16x32_bf16 v[2:5], v[178:181], v[228:231], v[2:5]
	s_barrier
	s_setprio 0
	s_add_i32 s47, s47, 2
	s_add_u32 s8, s8, 0x100
	s_addc_u32 s9, s9, 0
	s_add_u32 s45, s45, 0x100
	s_addc_u32 s46, s46, 0
	s_cmp_gt_u32 s47, 13
	s_cbranch_scc0 .LBB0_492

; #define PG8_STAGE(bufoff, gbase, voff) do { _Pragma("unroll") for (int _i = 0; _i < 2; ++_i) \
;         __builtin_amdgcn_global_load_lds((const unsigned*)((const char*)(gbase) + (voff)[_i]), (PG8_LAS unsigned*)(lds + (bufoff) + ldsw + _i * 8192), 16, 0, 0); } while (0)
; #define PG8_LDA(dst, b, h) do { _Pragma("unroll") for (int m = 0; m < 4; ++m) _Pragma("unroll") for (int k = 0; k < 2; ++k) dst[m][k] = *(const PG8_LAS bf16x8*)(lds + PG8_SA(b, h) + aoff + m * 2048 + k * 1024); } while (0)
; #define PG8_LDB(dst, b, h) do { _Pragma("unroll") for (int n = 0; n < 2; ++n) _Pragma("unroll") for (int k = 0; k < 2; ++k) dst[n][k] = *(const PG8_LAS bf16x8*)(lds + PG8_SB(b, h) + boff + n * 2048 + k * 1024); } while (0)
; #define PG8_MMA(ai, bj, At, Bt) do { __builtin_amdgcn_s_setprio(1); _Pragma("unroll") for (int m = 0; m < 4; ++m) _Pragma("unroll") for (int n = 0; n < 2; ++n) _Pragma("unroll") for (int k = 0; k < 2; ++k) \
;         acc[ai][bj][m][n] = __builtin_amdgcn_mfma_f32_16x16x32_bf16(Bt[n][k], At[m][k], acc[ai][bj][m][n], 0, 0, 0); __builtin_amdgcn_s_setprio(0); } while (0)
; #define PG8_WAIT_V(n) asm volatile("s_waitcnt vmcnt(" #n ")" ::: "memory")
; #define PG8_WAIT_L(n) asm volatile("s_waitcnt lgkmcnt(" #n ")" ::: "memory")
; #define PG8_BAR __builtin_amdgcn_s_barrier()
; #define PG8_SCHED __builtin_amdgcn_sched_barrier(0)
; template <class Epi, class Sched, bool ALIGN_EPI = false, bool SP2 = false>
; __device__ __forceinline__ void gemm_phase(PG8_LAS unsigned char* lds, const Gemm g, const Sched& S, const Epi& E) {
;     ...
;             PG8_LDB(B0, 0, 0); PG8_LDB(B1, 0, 1); PG8_SCHED; PG8_LDA(At, 0, 0); PG8_STAGE(PG8_SA(1, 1), a1 + hstep, voffA);
;             PG8_WAIT_V(8); PG8_WAIT_L(0); PG8_BAR; PG8_MMA(0, 0, At, B0); PG8_MMA(0, 1, At, B1); PG8_BAR; PG8_SCHED;
;             PG8_LDA(At, 0, 1); PG8_STAGE(PG8_SB(0, 0), b2, voffB); PG8_STAGE(PG8_SB(0, 1), b2 + hstep, voffB); PG8_STAGE(PG8_SA(0, 0), a2, voffA);
;             PG8_WAIT_V(8); PG8_WAIT_L(0); PG8_BAR; PG8_MMA(1, 0, At, B0); PG8_MMA(1, 1, At, B1); PG8_BAR; PG8_SCHED;
.LBB0_891:
	s_add_u32 s18, s16, 0xfffe0080
	s_addc_u32 s19, s17, -1
	s_add_i32 s46, 0, 0x10000
	s_cmp_eq_u32 s45, 4
	s_cselect_b32 s21, s9, s19
	s_cselect_b32 s20, s41, s18
	v_add_u32_e32 v148, s46, v151
	s_cselect_b32 s19, s7, s44
	s_cselect_b32 s18, s42, s43
	s_add_i32 s48, 0, 0x14000
	ds_read_b128 v[138:141], v148
	ds_read_b128 v[144:147], v148 offset:1024
	ds_read_b128 v[154:157], v148 offset:2048
	ds_read_b128 v[158:161], v148 offset:3072
	v_add_u32_e32 v148, s48, v151
	ds_read_b128 v[162:165], v148
	ds_read_b128 v[166:169], v148 offset:1024
	ds_read_b128 v[170:173], v148 offset:2048
	ds_read_b128 v[174:177], v148 offset:3072
	v_lshl_add_u64 v[148:149], s[16:17], 0, v[136:137]
	s_add_i32 m0, s27, 0xc000
	ds_read_b128 v[178:181], v153
	ds_read_b128 v[182:185], v153 offset:1024
	ds_read_b128 v[186:189], v153 offset:2048
	ds_read_b128 v[190:193], v153 offset:3072
	ds_read_b128 v[194:197], v153 offset:4096
	ds_read_b128 v[198:201], v153 offset:5120
	ds_read_b128 v[202:205], v153 offset:6144
	ds_read_b128 v[224:227], v153 offset:7168
	global_load_lds_dwordx4 v[148:149], off
	v_lshl_add_u64 v[148:149], s[16:17], 0, v[142:143]
	s_add_i32 m0, s27, 0xe000
	s_nop 0
	global_load_lds_dwordx4 v[148:149], off
	s_waitcnt vmcnt(8)
	s_waitcnt lgkmcnt(0)
	v_mfma_f32_16x16x32_bf16 v[126:129], v[138:141], v[178:181], v[126:129]
	v_mfma_f32_16x16x32_bf16 v[122:125], v[154:157], v[178:181], v[122:125]
	s_setprio 1
	s_barrier
	v_mfma_f32_16x16x32_bf16 v[110:113], v[138:141], v[186:189], v[110:113]
	v_mfma_f32_16x16x32_bf16 v[106:109], v[154:157], v[186:189], v[106:109]
	v_mfma_f32_16x16x32_bf16 v[94:97], v[138:141], v[194:197], v[94:97]
	v_mfma_f32_16x16x32_bf16 v[90:93], v[154:157], v[194:197], v[90:93]
	v_mfma_f32_16x16x32_bf16 v[78:81], v[138:141], v[202:205], v[78:81]
	v_mfma_f32_16x16x32_bf16 v[74:77], v[154:157], v[202:205], v[74:77]
	v_mfma_f32_16x16x32_bf16 v[126:129], v[144:147], v[182:185], v[126:129]
	v_mfma_f32_16x16x32_bf16 v[122:125], v[158:161], v[182:185], v[122:125]
	v_mfma_f32_16x16x32_bf16 v[110:113], v[144:147], v[190:193], v[110:113]
	v_mfma_f32_16x16x32_bf16 v[106:109], v[158:161], v[190:193], v[106:109]
	v_mfma_f32_16x16x32_bf16 v[94:97], v[144:147], v[198:201], v[94:97]
	v_mfma_f32_16x16x32_bf16 v[90:93], v[158:161], v[198:201], v[90:93]
	v_mfma_f32_16x16x32_bf16 v[78:81], v[144:147], v[224:227], v[78:81]
	v_mfma_f32_16x16x32_bf16 v[74:77], v[158:161], v[224:227], v[74:77]
	v_mfma_f32_16x16x32_bf16 v[118:121], v[162:165], v[178:181], v[118:121]
	v_mfma_f32_16x16x32_bf16 v[114:117], v[170:173], v[178:181], v[114:117]
	v_mfma_f32_16x16x32_bf16 v[102:105], v[162:165], v[186:189], v[102:105]
	v_mfma_f32_16x16x32_bf16 v[98:101], v[170:173], v[186:189], v[98:101]
	v_mfma_f32_16x16x32_bf16 v[86:89], v[162:165], v[194:197], v[86:89]
	v_mfma_f32_16x16x32_bf16 v[82:85], v[170:173], v[194:197], v[82:85]
	v_mfma_f32_16x16x32_bf16 v[70:73], v[162:165], v[202:205], v[70:73]
	v_mfma_f32_16x16x32_bf16 v[66:69], v[170:173], v[202:205], v[66:69]
	v_mfma_f32_16x16x32_bf16 v[118:121], v[166:169], v[182:185], v[118:121]
	v_mfma_f32_16x16x32_bf16 v[114:117], v[174:177], v[182:185], v[114:117]
	v_mfma_f32_16x16x32_bf16 v[102:105], v[166:169], v[190:193], v[102:105]
	v_mfma_f32_16x16x32_bf16 v[98:101], v[174:177], v[190:193], v[98:101]
	v_mfma_f32_16x16x32_bf16 v[86:89], v[166:169], v[198:201], v[86:89]
	v_mfma_f32_16x16x32_bf16 v[82:85], v[174:177], v[198:201], v[82:85]
	v_mfma_f32_16x16x32_bf16 v[70:73], v[166:169], v[224:227], v[70:73]
	v_mfma_f32_16x16x32_bf16 v[66:69], v[174:177], v[224:227], v[66:69]
	s_barrier
	s_setprio 0
	s_add_i32 s46, s46, s26
	v_lshl_add_u64 v[148:149], s[18:19], 0, v[0:1]
	s_mov_b32 m0, s46
	ds_read_b128 v[178:181], v153 offset:16384
	ds_read_b128 v[182:185], v153 offset:17408
	ds_read_b128 v[186:189], v153 offset:18432
	ds_read_b128 v[190:193], v153 offset:19456
	ds_read_b128 v[194:197], v153 offset:20480
	ds_read_b128 v[198:201], v153 offset:21504
	ds_read_b128 v[202:205], v153 offset:22528
	ds_read_b128 v[224:227], v153 offset:23552
	global_load_lds_dwordx4 v[148:149], off
	s_add_i32 m0, s46, 0x2000
	s_add_u32 s46, s18, 0x20000
	v_lshl_add_u64 v[228:229], s[18:19], 0, v[134:135]
	s_addc_u32 s47, s19, 0
	s_add_i32 s48, s48, s26
	global_load_lds_dwordx4 v[228:229], off
	v_lshl_add_u64 v[230:231], s[46:47], 0, v[0:1]
	s_mov_b32 m0, s48
	v_lshl_add_u64 v[232:233], s[20:21], 0, v[132:133]
	global_load_lds_dwordx4 v[230:231], off
	v_lshl_add_u64 v[230:231], s[46:47], 0, v[134:135]
	s_add_i32 m0, s48, 0x2000
	s_nop 0
	global_load_lds_dwordx4 v[230:231], off
	v_lshl_add_u64 v[230:231], s[20:21], 0, v[130:131]
	s_mov_b32 m0, s27
	s_nop 0
	global_load_lds_dwordx4 v[230:231], off
	s_mov_b32 m0, s28
	s_nop 0
	global_load_lds_dwordx4 v[232:233], off
	s_waitcnt vmcnt(8)
	s_waitcnt lgkmcnt(0)
	v_mfma_f32_16x16x32_bf16 v[62:65], v[138:141], v[178:181], v[62:65]
	v_mfma_f32_16x16x32_bf16 v[58:61], v[154:157], v[178:181], v[58:61]
	s_setprio 1
	s_barrier
; #define PG8_STAGE(bufoff, gbase, voff) do { _Pragma("unroll") for (int _i = 0; _i < 2; ++_i) \
;         __builtin_amdgcn_global_load_lds((const unsigned*)((const char*)(gbase) + (voff)[_i]), (PG8_LAS unsigned*)(lds + (bufoff) + ldsw + _i * 8192), 16, 0, 0); } while (0)
; #define PG8_LDA(dst, b, h) do { _Pragma("unroll") for (int m = 0; m < 4; ++m) _Pragma("unroll") for (int k = 0; k < 2; ++k) dst[m][k] = *(const PG8_LAS bf16x8*)(lds + PG8_SA(b, h) + aoff + m * 2048 + k * 1024); } while (0)
; #define PG8_LDB(dst, b, h) do { _Pragma("unroll") for (int n = 0; n < 2; ++n) _Pragma("unroll") for (int k = 0; k < 2; ++k) dst[n][k] = *(const PG8_LAS bf16x8*)(lds + PG8_SB(b, h) + boff + n * 2048 + k * 1024); } while (0)
; #define PG8_MMA(ai, bj, At, Bt) do { __builtin_amdgcn_s_setprio(1); _Pragma("unroll") for (int m = 0; m < 4; ++m) _Pragma("unroll") for (int n = 0; n < 2; ++n) _Pragma("unroll") for (int k = 0; k < 2; ++k) \
;         acc[ai][bj][m][n] = __builtin_amdgcn_mfma_f32_16x16x32_bf16(Bt[n][k], At[m][k], acc[ai][bj][m][n], 0, 0, 0); __builtin_amdgcn_s_setprio(0); } while (0)
; #define PG8_WAIT_V(n) asm volatile("s_waitcnt vmcnt(" #n ")" ::: "memory")
; #define PG8_WAIT_L(n) asm volatile("s_waitcnt lgkmcnt(" #n ")" ::: "memory")
; #define PG8_BAR __builtin_amdgcn_s_barrier()
; #define PG8_SCHED __builtin_amdgcn_sched_barrier(0)
; template <class Epi, class Sched, bool ALIGN_EPI = false, bool SP2 = false>
; __device__ __forceinline__ void gemm_phase(PG8_LAS unsigned char* lds, const Gemm g, const Sched& S, const Epi& E) {
;     ...
;             PG8_WAIT_V(8); PG8_WAIT_L(0); PG8_BAR; PG8_MMA(1, 0, At, B0); PG8_MMA(1, 1, At, B1); PG8_BAR; PG8_SCHED;
;             PG8_LDB(B0, 1, 0); PG8_LDB(B1, 1, 1); PG8_SCHED; PG8_LDA(At, 1, 0); PG8_STAGE(PG8_SA(0, 1), a2 + hstep, voffA);
;             PG8_WAIT_V(8); PG8_WAIT_L(0); PG8_BAR; PG8_MMA(0, 0, At, B0); PG8_MMA(0, 1, At, B1); PG8_BAR; PG8_SCHED;
	v_mfma_f32_16x16x32_bf16 v[46:49], v[138:141], v[186:189], v[46:49]
	v_mfma_f32_16x16x32_bf16 v[42:45], v[154:157], v[186:189], v[42:45]
	v_mfma_f32_16x16x32_bf16 v[30:33], v[138:141], v[194:197], v[30:33]
	v_mfma_f32_16x16x32_bf16 v[26:29], v[154:157], v[194:197], v[26:29]
	v_mfma_f32_16x16x32_bf16 v[14:17], v[138:141], v[202:205], v[14:17]
	v_mfma_f32_16x16x32_bf16 v[10:13], v[154:157], v[202:205], v[10:13]
	v_mfma_f32_16x16x32_bf16 v[62:65], v[144:147], v[182:185], v[62:65]
	v_mfma_f32_16x16x32_bf16 v[58:61], v[158:161], v[182:185], v[58:61]
	v_mfma_f32_16x16x32_bf16 v[46:49], v[144:147], v[190:193], v[46:49]
	v_mfma_f32_16x16x32_bf16 v[42:45], v[158:161], v[190:193], v[42:45]
	v_mfma_f32_16x16x32_bf16 v[30:33], v[144:147], v[198:201], v[30:33]
	v_mfma_f32_16x16x32_bf16 v[26:29], v[158:161], v[198:201], v[26:29]
	v_mfma_f32_16x16x32_bf16 v[14:17], v[144:147], v[224:227], v[14:17]
	v_mfma_f32_16x16x32_bf16 v[10:13], v[158:161], v[224:227], v[10:13]
	v_mfma_f32_16x16x32_bf16 v[54:57], v[162:165], v[178:181], v[54:57]
	v_mfma_f32_16x16x32_bf16 v[50:53], v[170:173], v[178:181], v[50:53]
	v_mfma_f32_16x16x32_bf16 v[38:41], v[162:165], v[186:189], v[38:41]
	v_mfma_f32_16x16x32_bf16 v[34:37], v[170:173], v[186:189], v[34:37]
	v_mfma_f32_16x16x32_bf16 v[22:25], v[162:165], v[194:197], v[22:25]
	v_mfma_f32_16x16x32_bf16 v[18:21], v[170:173], v[194:197], v[18:21]
	v_mfma_f32_16x16x32_bf16 v[6:9], v[162:165], v[202:205], v[6:9]
	v_mfma_f32_16x16x32_bf16 v[2:5], v[170:173], v[202:205], v[2:5]
	v_mfma_f32_16x16x32_bf16 v[54:57], v[166:169], v[182:185], v[54:57]
	v_mfma_f32_16x16x32_bf16 v[50:53], v[174:177], v[182:185], v[50:53]
	v_mfma_f32_16x16x32_bf16 v[38:41], v[166:169], v[190:193], v[38:41]
	v_mfma_f32_16x16x32_bf16 v[34:37], v[174:177], v[190:193], v[34:37]
	v_mfma_f32_16x16x32_bf16 v[22:25], v[166:169], v[198:201], v[22:25]
	v_mfma_f32_16x16x32_bf16 v[18:21], v[174:177], v[198:201], v[18:21]
	v_mfma_f32_16x16x32_bf16 v[6:9], v[166:169], v[224:227], v[6:9]
	v_mfma_f32_16x16x32_bf16 v[2:5], v[174:177], v[224:227], v[2:5]
	s_barrier
	s_setprio 0
	s_add_i32 s46, 0, 0x18000
	s_add_i32 s47, 0, 0x1c000
	v_add_u32_e32 v158, s46, v151
	v_add_u32_e32 v174, s47, v151
	ds_read_b128 v[138:141], v158
	ds_read_b128 v[144:147], v158 offset:1024
	ds_read_b128 v[154:157], v158 offset:2048
	ds_read_b128 v[158:161], v158 offset:3072
	ds_read_b128 v[162:165], v174
	ds_read_b128 v[166:169], v174 offset:1024
	ds_read_b128 v[170:173], v174 offset:2048
	ds_read_b128 v[174:177], v174 offset:3072
	s_add_u32 s20, s20, 0x20000
	s_addc_u32 s21, s21, 0
	s_mov_b32 m0, s29
	v_lshl_add_u64 v[234:235], s[20:21], 0, v[130:131]
	ds_read_b128 v[178:181], v153 offset:32768
	ds_read_b128 v[182:185], v153 offset:33792
	ds_read_b128 v[186:189], v153 offset:34816
	ds_read_b128 v[190:193], v153 offset:35840
	ds_read_b128 v[194:197], v153 offset:36864
	ds_read_b128 v[198:201], v153 offset:37888
	ds_read_b128 v[202:205], v153 offset:38912
	ds_read_b128 v[224:227], v153 offset:39936
	global_load_lds_dwordx4 v[234:235], off
	v_lshl_add_u64 v[234:235], s[20:21], 0, v[132:133]
	s_mov_b32 m0, s30
	s_nop 0
	global_load_lds_dwordx4 v[234:235], off
	s_waitcnt vmcnt(8)
	s_waitcnt lgkmcnt(0)
	v_mfma_f32_16x16x32_bf16 v[126:129], v[138:141], v[178:181], v[126:129]
	v_mfma_f32_16x16x32_bf16 v[122:125], v[154:157], v[178:181], v[122:125]
	s_setprio 1
	s_barrier
	v_mfma_f32_16x16x32_bf16 v[110:113], v[138:141], v[186:189], v[110:113]
	v_mfma_f32_16x16x32_bf16 v[106:109], v[154:157], v[186:189], v[106:109]
	v_mfma_f32_16x16x32_bf16 v[94:97], v[138:141], v[194:197], v[94:97]
	v_mfma_f32_16x16x32_bf16 v[90:93], v[154:157], v[194:197], v[90:93]
	v_mfma_f32_16x16x32_bf16 v[78:81], v[138:141], v[202:205], v[78:81]
	v_mfma_f32_16x16x32_bf16 v[74:77], v[154:157], v[202:205], v[74:77]
	v_mfma_f32_16x16x32_bf16 v[126:129], v[144:147], v[182:185], v[126:129]
	v_mfma_f32_16x16x32_bf16 v[122:125], v[158:161], v[182:185], v[122:125]
	v_mfma_f32_16x16x32_bf16 v[110:113], v[144:147], v[190:193], v[110:113]
	v_mfma_f32_16x16x32_bf16 v[106:109], v[158:161], v[190:193], v[106:109]
	v_mfma_f32_16x16x32_bf16 v[94:97], v[144:147], v[198:201], v[94:97]
	v_mfma_f32_16x16x32_bf16 v[90:93], v[158:161], v[198:201], v[90:93]
	v_mfma_f32_16x16x32_bf16 v[78:81], v[144:147], v[224:227], v[78:81]
	v_mfma_f32_16x16x32_bf16 v[74:77], v[158:161], v[224:227], v[74:77]
	v_mfma_f32_16x16x32_bf16 v[118:121], v[162:165], v[178:181], v[118:121]
	v_mfma_f32_16x16x32_bf16 v[114:117], v[170:173], v[178:181], v[114:117]
	v_mfma_f32_16x16x32_bf16 v[102:105], v[162:165], v[186:189], v[102:105]
	v_mfma_f32_16x16x32_bf16 v[98:101], v[170:173], v[186:189], v[98:101]
	v_mfma_f32_16x16x32_bf16 v[86:89], v[162:165], v[194:197], v[86:89]
	v_mfma_f32_16x16x32_bf16 v[82:85], v[170:173], v[194:197], v[82:85]
	v_mfma_f32_16x16x32_bf16 v[70:73], v[162:165], v[202:205], v[70:73]
	v_mfma_f32_16x16x32_bf16 v[66:69], v[170:173], v[202:205], v[66:69]
	v_mfma_f32_16x16x32_bf16 v[118:121], v[166:169], v[182:185], v[118:121]
	v_mfma_f32_16x16x32_bf16 v[114:117], v[174:177], v[182:185], v[114:117]
	v_mfma_f32_16x16x32_bf16 v[102:105], v[166:169], v[190:193], v[102:105]
	v_mfma_f32_16x16x32_bf16 v[98:101], v[174:177], v[190:193], v[98:101]
	v_mfma_f32_16x16x32_bf16 v[86:89], v[166:169], v[198:201], v[86:89]
	v_mfma_f32_16x16x32_bf16 v[82:85], v[174:177], v[198:201], v[82:85]
	v_mfma_f32_16x16x32_bf16 v[70:73], v[166:169], v[224:227], v[70:73]
	v_mfma_f32_16x16x32_bf16 v[66:69], v[174:177], v[224:227], v[66:69]
	s_barrier
; #define PG8_STAGE(bufoff, gbase, voff) do { _Pragma("unroll") for (int _i = 0; _i < 2; ++_i) \
;         __builtin_amdgcn_global_load_lds((const unsigned*)((const char*)(gbase) + (voff)[_i]), (PG8_LAS unsigned*)(lds + (bufoff) + ldsw + _i * 8192), 16, 0, 0); } while (0)
; #define PG8_LDA(dst, b, h) do { _Pragma("unroll") for (int m = 0; m < 4; ++m) _Pragma("unroll") for (int k = 0; k < 2; ++k) dst[m][k] = *(const PG8_LAS bf16x8*)(lds + PG8_SA(b, h) + aoff + m * 2048 + k * 1024); } while (0)
; #define PG8_MMA(ai, bj, At, Bt) do { __builtin_amdgcn_s_setprio(1); _Pragma("unroll") for (int m = 0; m < 4; ++m) _Pragma("unroll") for (int n = 0; n < 2; ++n) _Pragma("unroll") for (int k = 0; k < 2; ++k) \
;         acc[ai][bj][m][n] = __builtin_amdgcn_mfma_f32_16x16x32_bf16(Bt[n][k], At[m][k], acc[ai][bj][m][n], 0, 0, 0); __builtin_amdgcn_s_setprio(0); } while (0)
; #define PG8_WAIT_V(n) asm volatile("s_waitcnt vmcnt(" #n ")" ::: "memory")
; #define PG8_WAIT_L(n) asm volatile("s_waitcnt lgkmcnt(" #n ")" ::: "memory")
; #define PG8_BAR __builtin_amdgcn_s_barrier()
; #define PG8_SCHED __builtin_amdgcn_sched_barrier(0)
; template <class Epi, class Sched, bool ALIGN_EPI = false, bool SP2 = false>
; __device__ __forceinline__ void gemm_phase(PG8_LAS unsigned char* lds, const Gemm g, const Sched& S, const Epi& E) {
;     ...
;             PG8_LDA(At, 1, 1); PG8_STAGE(PG8_SB(1, 0), b3, voffB); PG8_STAGE(PG8_SB(1, 1), b3 + hstep, voffB); PG8_STAGE(PG8_SA(1, 0), a3, voffA);
;             PG8_WAIT_V(8); PG8_WAIT_L(0); PG8_BAR; PG8_MMA(1, 0, At, B0); PG8_MMA(1, 1, At, B1); PG8_BAR; PG8_SCHED;
;     __device__ __forceinline__ void operator()(const f32x4 (&acc)[2][2][4][2], const Unit& u, int wr, int wc, int fr, int fq) const {
;         const int row0 = u.pm * 256 + wr * 64 + fr, col0 = u.pn * 256 + wc * 32 + 8 * fq;
; #pragma unroll
;         for (int ai = 0; ai < 2; ++ai)
; #pragma unroll
;             for (int m = 0; m < 4; ++m) {
;                 const int row = row0 + ai * 128 + m * 16;
; #pragma unroll
;                 for (int bj = 0; bj < 2; ++bj) {
;                     const int c = col0 + bj * 128;
;                     const u32x4 g = *(const u32x4*)(G + (size_t)row * P2W + c);
	s_setprio 0
	s_add_i32 s20, s46, s26
	v_lshl_add_u64 v[148:149], v[148:149], 0, s[86:87]
	s_mov_b32 m0, s20
	ds_read_b128 v[178:181], v153 offset:49152
	ds_read_b128 v[182:185], v153 offset:50176
	ds_read_b128 v[186:189], v153 offset:51200
	ds_read_b128 v[190:193], v153 offset:52224
	ds_read_b128 v[194:197], v153 offset:53248
	ds_read_b128 v[198:201], v153 offset:54272
	ds_read_b128 v[202:205], v153 offset:55296
	ds_read_b128 v[224:227], v153 offset:56320
	global_load_lds_dwordx4 v[148:149], off
	s_add_i32 m0, s20, 0x2000
	s_add_u32 s18, s18, 0x20080
	v_lshl_add_u64 v[148:149], v[228:229], 0, s[86:87]
	s_addc_u32 s19, s19, 0
	s_add_i32 s20, s47, s26
	global_load_lds_dwordx4 v[148:149], off
	v_lshl_add_u64 v[148:149], s[18:19], 0, v[0:1]
	s_mov_b32 m0, s20
	s_nop 0
	global_load_lds_dwordx4 v[148:149], off
	v_lshl_add_u64 v[148:149], s[18:19], 0, v[134:135]
	s_add_i32 m0, s20, 0x2000
	s_nop 0
	global_load_lds_dwordx4 v[148:149], off
	v_lshl_add_u64 v[148:149], v[230:231], 0, s[86:87]
	s_mov_b32 m0, s31
	s_nop 0
	global_load_lds_dwordx4 v[148:149], off
	v_lshl_add_u64 v[148:149], v[232:233], 0, s[86:87]
	s_mov_b32 m0, s38
	s_nop 0
	global_load_lds_dwordx4 v[148:149], off
	s_waitcnt vmcnt(8)
	s_waitcnt lgkmcnt(0)
	v_mfma_f32_16x16x32_bf16 v[62:65], v[138:141], v[178:181], v[62:65]
	v_mfma_f32_16x16x32_bf16 v[58:61], v[154:157], v[178:181], v[58:61]
	s_setprio 1
	s_barrier
	v_mfma_f32_16x16x32_bf16 v[46:49], v[138:141], v[186:189], v[46:49]
	v_mfma_f32_16x16x32_bf16 v[42:45], v[154:157], v[186:189], v[42:45]
	v_mfma_f32_16x16x32_bf16 v[30:33], v[138:141], v[194:197], v[30:33]
	v_mfma_f32_16x16x32_bf16 v[26:29], v[154:157], v[194:197], v[26:29]
	v_mfma_f32_16x16x32_bf16 v[14:17], v[138:141], v[202:205], v[14:17]
	v_mfma_f32_16x16x32_bf16 v[10:13], v[154:157], v[202:205], v[10:13]
	v_mfma_f32_16x16x32_bf16 v[62:65], v[144:147], v[182:185], v[62:65]
	v_mfma_f32_16x16x32_bf16 v[58:61], v[158:161], v[182:185], v[58:61]
	v_mfma_f32_16x16x32_bf16 v[46:49], v[144:147], v[190:193], v[46:49]
	v_mfma_f32_16x16x32_bf16 v[42:45], v[158:161], v[190:193], v[42:45]
	v_mfma_f32_16x16x32_bf16 v[30:33], v[144:147], v[198:201], v[30:33]
	v_mfma_f32_16x16x32_bf16 v[26:29], v[158:161], v[198:201], v[26:29]
	v_mfma_f32_16x16x32_bf16 v[14:17], v[144:147], v[224:227], v[14:17]
	v_mfma_f32_16x16x32_bf16 v[10:13], v[158:161], v[224:227], v[10:13]
	v_mfma_f32_16x16x32_bf16 v[54:57], v[162:165], v[178:181], v[54:57]
	v_mfma_f32_16x16x32_bf16 v[50:53], v[170:173], v[178:181], v[50:53]
	v_mfma_f32_16x16x32_bf16 v[38:41], v[162:165], v[186:189], v[38:41]
	v_mfma_f32_16x16x32_bf16 v[34:37], v[170:173], v[186:189], v[34:37]
	v_mfma_f32_16x16x32_bf16 v[22:25], v[162:165], v[194:197], v[22:25]
	v_mfma_f32_16x16x32_bf16 v[18:21], v[170:173], v[194:197], v[18:21]
	v_mfma_f32_16x16x32_bf16 v[6:9], v[162:165], v[202:205], v[6:9]
	v_mfma_f32_16x16x32_bf16 v[2:5], v[170:173], v[202:205], v[2:5]
	v_mfma_f32_16x16x32_bf16 v[54:57], v[166:169], v[182:185], v[54:57]
	v_mfma_f32_16x16x32_bf16 v[50:53], v[174:177], v[182:185], v[50:53]
	v_mfma_f32_16x16x32_bf16 v[38:41], v[166:169], v[190:193], v[38:41]
	v_mfma_f32_16x16x32_bf16 v[34:37], v[174:177], v[190:193], v[34:37]
	v_mfma_f32_16x16x32_bf16 v[22:25], v[166:169], v[198:201], v[22:25]
	v_mfma_f32_16x16x32_bf16 v[18:21], v[174:177], v[198:201], v[18:21]
	v_mfma_f32_16x16x32_bf16 v[6:9], v[166:169], v[224:227], v[6:9]
	v_mfma_f32_16x16x32_bf16 v[2:5], v[174:177], v[224:227], v[2:5]
	s_barrier
	s_setprio 0
	s_add_i32 s45, s45, 2
	s_add_u32 s16, s16, 0x100
	s_addc_u32 s17, s17, 0
	s_add_u32 s43, s43, 0x100
	s_addc_u32 s44, s44, 0
	s_cmp_gt_u32 s45, 5
	s_cbranch_scc0 .LBB0_891
	v_lshl_add_u32 v140, s14, 8, v150
	v_lshl_or_b32 v141, s15, 8, v152
	v_mul_lo_u32 v138, v140, s83
	v_lshlrev_b32_e32 v139, 11, v140
	v_lshl_add_u32 v138, v141, 1, v138
	v_lshl_add_u32 v139, v141, 1, v139
	global_load_dwordx4 v[144:147], v138, s[74:75]
	global_load_dwordx4 v[156:159], v138, s[74:75] offset:256
	v_add_u32_e32 v140, 0x1a000, v138
	global_load_dwordx4 v[160:163], v140, s[74:75]
	global_load_dwordx4 v[164:167], v140, s[74:75] offset:256
	v_add_u32_e32 v140, 0x34000, v138
	global_load_dwordx4 v[168:171], v140, s[74:75]
	global_load_dwordx4 v[172:175], v140, s[74:75] offset:256
	v_add_u32_e32 v140, 0x4e000, v138
	global_load_dwordx4 v[176:179], v140, s[74:75]
	global_load_dwordx4 v[180:183], v140, s[74:75] offset:256
	v_add_u32_e32 v140, 0xd0000, v138
	global_load_dwordx4 v[184:187], v140, s[74:75]
	global_load_dwordx4 v[188:191], v140, s[74:75] offset:256
	v_add_u32_e32 v140, 0xea000, v138
	global_load_dwordx4 v[192:195], v140, s[74:75]
	global_load_dwordx4 v[196:199], v140, s[74:75] offset:256
	v_add_u32_e32 v140, 0x104000, v138
	global_load_dwordx4 v[200:203], v140, s[74:75]
	global_load_dwordx4 v[224:227], v140, s[74:75] offset:256
	v_add_u32_e32 v140, 0x11e000, v138
	global_load_dwordx4 v[228:231], v140, s[74:75]
	global_load_dwordx4 v[232:235], v140, s[74:75] offset:256
	s_and_b64 vcc, exec, s[4:5]
	s_cbranch_vccz .LBB0_894
	s_barrier

; #define PG8_STAGE(bufoff, gbase, voff) do { _Pragma("unroll") for (int _i = 0; _i < 2; ++_i) \
;         __builtin_amdgcn_global_load_lds((const unsigned*)((const char*)(gbase) + (voff)[_i]), (PG8_LAS unsigned*)(lds + (bufoff) + ldsw + _i * 8192), 16, 0, 0); } while (0)
; #define PG8_LDA(dst, b, h) do { _Pragma("unroll") for (int m = 0; m < 4; ++m) _Pragma("unroll") for (int k = 0; k < 2; ++k) dst[m][k] = *(const PG8_LAS bf16x8*)(lds + PG8_SA(b, h) + aoff + m * 2048 + k * 1024); } while (0)
; #define PG8_LDB(dst, b, h) do { _Pragma("unroll") for (int n = 0; n < 2; ++n) _Pragma("unroll") for (int k = 0; k < 2; ++k) dst[n][k] = *(const PG8_LAS bf16x8*)(lds + PG8_SB(b, h) + boff + n * 2048 + k * 1024); } while (0)
; #define PG8_MMA(ai, bj, At, Bt) do { __builtin_amdgcn_s_setprio(1); _Pragma("unroll") for (int m = 0; m < 4; ++m) _Pragma("unroll") for (int n = 0; n < 2; ++n) _Pragma("unroll") for (int k = 0; k < 2; ++k) \
;         acc[ai][bj][m][n] = __builtin_amdgcn_mfma_f32_16x16x32_bf16(Bt[n][k], At[m][k], acc[ai][bj][m][n], 0, 0, 0); __builtin_amdgcn_s_setprio(0); } while (0)
; #define PG8_WAIT_V(n) asm volatile("s_waitcnt vmcnt(" #n ")" ::: "memory")
; #define PG8_WAIT_L(n) asm volatile("s_waitcnt lgkmcnt(" #n ")" ::: "memory")
; #define PG8_BAR __builtin_amdgcn_s_barrier()
; #define PG8_SCHED __builtin_amdgcn_sched_barrier(0)
; template <class Epi, class Sched, bool ALIGN_EPI = false, bool SP2 = false>
; __device__ __forceinline__ void gemm_phase(PG8_LAS unsigned char* lds, const Gemm g, const Sched& S, const Epi& E) {
;     ...
;             PG8_LDB(B0, 0, 0); PG8_LDB(B1, 0, 1); PG8_SCHED; PG8_LDA(At, 0, 0); PG8_STAGE(PG8_SA(1, 1), a1 + hstep, voffA);
;             PG8_WAIT_V(8); PG8_WAIT_L(0); PG8_BAR; PG8_MMA(0, 0, At, B0); PG8_MMA(0, 1, At, B1); PG8_BAR; PG8_SCHED;
;             PG8_LDA(At, 0, 1); PG8_STAGE(PG8_SB(0, 0), b2, voffB); PG8_STAGE(PG8_SB(0, 1), b2 + hstep, voffB); PG8_STAGE(PG8_SA(0, 0), a2, voffA);
;             PG8_WAIT_V(8); PG8_WAIT_L(0); PG8_BAR; PG8_MMA(1, 0, At, B0); PG8_MMA(1, 1, At, B1); PG8_BAR; PG8_SCHED;
.LBB0_919:
	s_add_u32 s12, s10, 0x100
	s_addc_u32 s13, s11, 0
	s_add_i32 s44, 0, 0x10000
	s_cmp_eq_u32 s43, 16
	s_cselect_b32 s17, s5, s13
	s_cselect_b32 s16, s4, s12
	v_add_u32_e32 v148, s44, v151
	s_cselect_b32 s15, s9, s42
	s_cselect_b32 s14, s8, s41
	s_add_i32 s45, 0, 0x14000
	ds_read_b128 v[138:141], v148
	ds_read_b128 v[144:147], v148 offset:1024
	ds_read_b128 v[154:157], v148 offset:2048
	ds_read_b128 v[158:161], v148 offset:3072
	v_add_u32_e32 v148, s45, v151
	ds_read_b128 v[162:165], v148
	ds_read_b128 v[166:169], v148 offset:1024
	ds_read_b128 v[170:173], v148 offset:2048
	ds_read_b128 v[174:177], v148 offset:3072
	v_lshl_add_u64 v[148:149], s[10:11], 0, v[136:137]
	s_add_i32 m0, s23, 0xc000
	ds_read_b128 v[178:181], v153
	ds_read_b128 v[182:185], v153 offset:1024
	ds_read_b128 v[186:189], v153 offset:2048
	ds_read_b128 v[190:193], v153 offset:3072
	ds_read_b128 v[194:197], v153 offset:4096
	ds_read_b128 v[198:201], v153 offset:5120
	ds_read_b128 v[202:205], v153 offset:6144
	ds_read_b128 v[224:227], v153 offset:7168
	global_load_lds_dwordx4 v[148:149], off
	v_lshl_add_u64 v[148:149], s[10:11], 0, v[142:143]
	s_add_i32 m0, s23, 0xe000
	s_nop 0
	global_load_lds_dwordx4 v[148:149], off
	s_waitcnt vmcnt(8)
	s_waitcnt lgkmcnt(0)
	v_mfma_f32_16x16x32_bf16 v[126:129], v[138:141], v[178:181], v[126:129]
	v_mfma_f32_16x16x32_bf16 v[122:125], v[154:157], v[178:181], v[122:125]
	s_setprio 1
	s_barrier
	v_mfma_f32_16x16x32_bf16 v[110:113], v[138:141], v[186:189], v[110:113]
	v_mfma_f32_16x16x32_bf16 v[106:109], v[154:157], v[186:189], v[106:109]
	v_mfma_f32_16x16x32_bf16 v[94:97], v[138:141], v[194:197], v[94:97]
	v_mfma_f32_16x16x32_bf16 v[90:93], v[154:157], v[194:197], v[90:93]
	v_mfma_f32_16x16x32_bf16 v[78:81], v[138:141], v[202:205], v[78:81]
	v_mfma_f32_16x16x32_bf16 v[74:77], v[154:157], v[202:205], v[74:77]
	v_mfma_f32_16x16x32_bf16 v[126:129], v[144:147], v[182:185], v[126:129]
	v_mfma_f32_16x16x32_bf16 v[122:125], v[158:161], v[182:185], v[122:125]
	v_mfma_f32_16x16x32_bf16 v[110:113], v[144:147], v[190:193], v[110:113]
	v_mfma_f32_16x16x32_bf16 v[106:109], v[158:161], v[190:193], v[106:109]
	v_mfma_f32_16x16x32_bf16 v[94:97], v[144:147], v[198:201], v[94:97]
	v_mfma_f32_16x16x32_bf16 v[90:93], v[158:161], v[198:201], v[90:93]
	v_mfma_f32_16x16x32_bf16 v[78:81], v[144:147], v[224:227], v[78:81]
	v_mfma_f32_16x16x32_bf16 v[74:77], v[158:161], v[224:227], v[74:77]
	v_mfma_f32_16x16x32_bf16 v[118:121], v[162:165], v[178:181], v[118:121]
	v_mfma_f32_16x16x32_bf16 v[114:117], v[170:173], v[178:181], v[114:117]
	v_mfma_f32_16x16x32_bf16 v[102:105], v[162:165], v[186:189], v[102:105]
	v_mfma_f32_16x16x32_bf16 v[98:101], v[170:173], v[186:189], v[98:101]
	v_mfma_f32_16x16x32_bf16 v[86:89], v[162:165], v[194:197], v[86:89]
	v_mfma_f32_16x16x32_bf16 v[82:85], v[170:173], v[194:197], v[82:85]
	v_mfma_f32_16x16x32_bf16 v[70:73], v[162:165], v[202:205], v[70:73]
	v_mfma_f32_16x16x32_bf16 v[66:69], v[170:173], v[202:205], v[66:69]
	v_mfma_f32_16x16x32_bf16 v[118:121], v[166:169], v[182:185], v[118:121]
	v_mfma_f32_16x16x32_bf16 v[114:117], v[174:177], v[182:185], v[114:117]
	v_mfma_f32_16x16x32_bf16 v[102:105], v[166:169], v[190:193], v[102:105]
	v_mfma_f32_16x16x32_bf16 v[98:101], v[174:177], v[190:193], v[98:101]
	v_mfma_f32_16x16x32_bf16 v[86:89], v[166:169], v[198:201], v[86:89]
	v_mfma_f32_16x16x32_bf16 v[82:85], v[174:177], v[198:201], v[82:85]
	v_mfma_f32_16x16x32_bf16 v[70:73], v[166:169], v[224:227], v[70:73]
	v_mfma_f32_16x16x32_bf16 v[66:69], v[174:177], v[224:227], v[66:69]
	s_barrier
	s_setprio 0
	s_add_i32 s10, s44, s20
	v_lshl_add_u64 v[148:149], s[14:15], 0, v[0:1]
	s_mov_b32 m0, s10
	ds_read_b128 v[178:181], v153 offset:16384
	ds_read_b128 v[182:185], v153 offset:17408
	ds_read_b128 v[186:189], v153 offset:18432
	ds_read_b128 v[190:193], v153 offset:19456
	ds_read_b128 v[194:197], v153 offset:20480
	ds_read_b128 v[198:201], v153 offset:21504
	ds_read_b128 v[202:205], v153 offset:22528
	ds_read_b128 v[224:227], v153 offset:23552
	global_load_lds_dwordx4 v[148:149], off
	s_add_i32 m0, s10, 0x2000
	s_add_u32 s10, s14, 0x50000
	v_lshl_add_u64 v[228:229], s[14:15], 0, v[134:135]
	s_addc_u32 s11, s15, 0
	s_add_i32 s44, s45, s20
	global_load_lds_dwordx4 v[228:229], off
	v_lshl_add_u64 v[230:231], s[10:11], 0, v[0:1]
	s_mov_b32 m0, s44
	v_lshl_add_u64 v[232:233], s[16:17], 0, v[132:133]
	global_load_lds_dwordx4 v[230:231], off
	v_lshl_add_u64 v[230:231], s[10:11], 0, v[134:135]
	s_add_i32 m0, s44, 0x2000
	s_nop 0
	global_load_lds_dwordx4 v[230:231], off
	v_lshl_add_u64 v[230:231], s[16:17], 0, v[130:131]
	s_mov_b32 m0, s23
	s_nop 0
	global_load_lds_dwordx4 v[230:231], off
	s_mov_b32 m0, s24
	s_nop 0
	global_load_lds_dwordx4 v[232:233], off
	s_waitcnt vmcnt(8)
	s_waitcnt lgkmcnt(0)
	v_mfma_f32_16x16x32_bf16 v[62:65], v[138:141], v[178:181], v[62:65]
	v_mfma_f32_16x16x32_bf16 v[58:61], v[154:157], v[178:181], v[58:61]
	s_setprio 1
	s_barrier
; #define PG8_STAGE(bufoff, gbase, voff) do { _Pragma("unroll") for (int _i = 0; _i < 2; ++_i) \
;         __builtin_amdgcn_global_load_lds((const unsigned*)((const char*)(gbase) + (voff)[_i]), (PG8_LAS unsigned*)(lds + (bufoff) + ldsw + _i * 8192), 16, 0, 0); } while (0)
; #define PG8_LDA(dst, b, h) do { _Pragma("unroll") for (int m = 0; m < 4; ++m) _Pragma("unroll") for (int k = 0; k < 2; ++k) dst[m][k] = *(const PG8_LAS bf16x8*)(lds + PG8_SA(b, h) + aoff + m * 2048 + k * 1024); } while (0)
; #define PG8_LDB(dst, b, h) do { _Pragma("unroll") for (int n = 0; n < 2; ++n) _Pragma("unroll") for (int k = 0; k < 2; ++k) dst[n][k] = *(const PG8_LAS bf16x8*)(lds + PG8_SB(b, h) + boff + n * 2048 + k * 1024); } while (0)
; #define PG8_MMA(ai, bj, At, Bt) do { __builtin_amdgcn_s_setprio(1); _Pragma("unroll") for (int m = 0; m < 4; ++m) _Pragma("unroll") for (int n = 0; n < 2; ++n) _Pragma("unroll") for (int k = 0; k < 2; ++k) \
;         acc[ai][bj][m][n] = __builtin_amdgcn_mfma_f32_16x16x32_bf16(Bt[n][k], At[m][k], acc[ai][bj][m][n], 0, 0, 0); __builtin_amdgcn_s_setprio(0); } while (0)
; #define PG8_WAIT_V(n) asm volatile("s_waitcnt vmcnt(" #n ")" ::: "memory")
; #define PG8_WAIT_L(n) asm volatile("s_waitcnt lgkmcnt(" #n ")" ::: "memory")
; #define PG8_BAR __builtin_amdgcn_s_barrier()
; #define PG8_SCHED __builtin_amdgcn_sched_barrier(0)
; template <class Epi, class Sched, bool ALIGN_EPI = false, bool SP2 = false>
; __device__ __forceinline__ void gemm_phase(PG8_LAS unsigned char* lds, const Gemm g, const Sched& S, const Epi& E) {
;     ...
;             PG8_WAIT_V(8); PG8_WAIT_L(0); PG8_BAR; PG8_MMA(1, 0, At, B0); PG8_MMA(1, 1, At, B1); PG8_BAR; PG8_SCHED;
;             PG8_LDB(B0, 1, 0); PG8_LDB(B1, 1, 1); PG8_SCHED; PG8_LDA(At, 1, 0); PG8_STAGE(PG8_SA(0, 1), a2 + hstep, voffA);
;             PG8_WAIT_V(8); PG8_WAIT_L(0); PG8_BAR; PG8_MMA(0, 0, At, B0); PG8_MMA(0, 1, At, B1); PG8_BAR; PG8_SCHED;
	v_mfma_f32_16x16x32_bf16 v[46:49], v[138:141], v[186:189], v[46:49]
	v_mfma_f32_16x16x32_bf16 v[42:45], v[154:157], v[186:189], v[42:45]
	v_mfma_f32_16x16x32_bf16 v[30:33], v[138:141], v[194:197], v[30:33]
	v_mfma_f32_16x16x32_bf16 v[26:29], v[154:157], v[194:197], v[26:29]
	v_mfma_f32_16x16x32_bf16 v[14:17], v[138:141], v[202:205], v[14:17]
	v_mfma_f32_16x16x32_bf16 v[10:13], v[154:157], v[202:205], v[10:13]
	v_mfma_f32_16x16x32_bf16 v[62:65], v[144:147], v[182:185], v[62:65]
	v_mfma_f32_16x16x32_bf16 v[58:61], v[158:161], v[182:185], v[58:61]
	v_mfma_f32_16x16x32_bf16 v[46:49], v[144:147], v[190:193], v[46:49]
	v_mfma_f32_16x16x32_bf16 v[42:45], v[158:161], v[190:193], v[42:45]
	v_mfma_f32_16x16x32_bf16 v[30:33], v[144:147], v[198:201], v[30:33]
	v_mfma_f32_16x16x32_bf16 v[26:29], v[158:161], v[198:201], v[26:29]
	v_mfma_f32_16x16x32_bf16 v[14:17], v[144:147], v[224:227], v[14:17]
	v_mfma_f32_16x16x32_bf16 v[10:13], v[158:161], v[224:227], v[10:13]
	v_mfma_f32_16x16x32_bf16 v[54:57], v[162:165], v[178:181], v[54:57]
	v_mfma_f32_16x16x32_bf16 v[50:53], v[170:173], v[178:181], v[50:53]
	v_mfma_f32_16x16x32_bf16 v[38:41], v[162:165], v[186:189], v[38:41]
	v_mfma_f32_16x16x32_bf16 v[34:37], v[170:173], v[186:189], v[34:37]
	v_mfma_f32_16x16x32_bf16 v[22:25], v[162:165], v[194:197], v[22:25]
	v_mfma_f32_16x16x32_bf16 v[18:21], v[170:173], v[194:197], v[18:21]
	v_mfma_f32_16x16x32_bf16 v[6:9], v[162:165], v[202:205], v[6:9]
	v_mfma_f32_16x16x32_bf16 v[2:5], v[170:173], v[202:205], v[2:5]
	v_mfma_f32_16x16x32_bf16 v[54:57], v[166:169], v[182:185], v[54:57]
	v_mfma_f32_16x16x32_bf16 v[50:53], v[174:177], v[182:185], v[50:53]
	v_mfma_f32_16x16x32_bf16 v[38:41], v[166:169], v[190:193], v[38:41]
	v_mfma_f32_16x16x32_bf16 v[34:37], v[174:177], v[190:193], v[34:37]
	v_mfma_f32_16x16x32_bf16 v[22:25], v[166:169], v[198:201], v[22:25]
	v_mfma_f32_16x16x32_bf16 v[18:21], v[174:177], v[198:201], v[18:21]
	v_mfma_f32_16x16x32_bf16 v[6:9], v[166:169], v[224:227], v[6:9]
	v_mfma_f32_16x16x32_bf16 v[2:5], v[174:177], v[224:227], v[2:5]
	s_barrier
	s_setprio 0
	s_add_i32 s44, 0, 0x18000
	s_add_i32 s45, 0, 0x1c000
	v_add_u32_e32 v158, s44, v151
	v_add_u32_e32 v174, s45, v151
	ds_read_b128 v[138:141], v158
	ds_read_b128 v[144:147], v158 offset:1024
	ds_read_b128 v[154:157], v158 offset:2048
	ds_read_b128 v[158:161], v158 offset:3072
	ds_read_b128 v[162:165], v174
	ds_read_b128 v[166:169], v174 offset:1024
	ds_read_b128 v[170:173], v174 offset:2048
	ds_read_b128 v[174:177], v174 offset:3072
	s_add_u32 s10, s16, 0x50000
	s_addc_u32 s11, s17, 0
	s_mov_b32 m0, s25
	v_lshl_add_u64 v[234:235], s[10:11], 0, v[130:131]
	ds_read_b128 v[178:181], v153 offset:32768
	ds_read_b128 v[182:185], v153 offset:33792
	ds_read_b128 v[186:189], v153 offset:34816
	ds_read_b128 v[190:193], v153 offset:35840
	ds_read_b128 v[194:197], v153 offset:36864
	ds_read_b128 v[198:201], v153 offset:37888
	ds_read_b128 v[202:205], v153 offset:38912
	ds_read_b128 v[224:227], v153 offset:39936
	global_load_lds_dwordx4 v[234:235], off
	v_lshl_add_u64 v[234:235], s[10:11], 0, v[132:133]
	s_mov_b32 m0, s26
	s_nop 0
	global_load_lds_dwordx4 v[234:235], off
	s_waitcnt vmcnt(8)
	s_waitcnt lgkmcnt(0)
	v_mfma_f32_16x16x32_bf16 v[126:129], v[138:141], v[178:181], v[126:129]
	v_mfma_f32_16x16x32_bf16 v[122:125], v[154:157], v[178:181], v[122:125]
	s_setprio 1
	s_barrier
	v_mfma_f32_16x16x32_bf16 v[110:113], v[138:141], v[186:189], v[110:113]
	v_mfma_f32_16x16x32_bf16 v[106:109], v[154:157], v[186:189], v[106:109]
	v_mfma_f32_16x16x32_bf16 v[94:97], v[138:141], v[194:197], v[94:97]
	v_mfma_f32_16x16x32_bf16 v[90:93], v[154:157], v[194:197], v[90:93]
	v_mfma_f32_16x16x32_bf16 v[78:81], v[138:141], v[202:205], v[78:81]
	v_mfma_f32_16x16x32_bf16 v[74:77], v[154:157], v[202:205], v[74:77]
	v_mfma_f32_16x16x32_bf16 v[126:129], v[144:147], v[182:185], v[126:129]
	v_mfma_f32_16x16x32_bf16 v[122:125], v[158:161], v[182:185], v[122:125]
	v_mfma_f32_16x16x32_bf16 v[110:113], v[144:147], v[190:193], v[110:113]
	v_mfma_f32_16x16x32_bf16 v[106:109], v[158:161], v[190:193], v[106:109]
	v_mfma_f32_16x16x32_bf16 v[94:97], v[144:147], v[198:201], v[94:97]
	v_mfma_f32_16x16x32_bf16 v[90:93], v[158:161], v[198:201], v[90:93]
	v_mfma_f32_16x16x32_bf16 v[78:81], v[144:147], v[224:227], v[78:81]
	v_mfma_f32_16x16x32_bf16 v[74:77], v[158:161], v[224:227], v[74:77]
	v_mfma_f32_16x16x32_bf16 v[118:121], v[162:165], v[178:181], v[118:121]
	v_mfma_f32_16x16x32_bf16 v[114:117], v[170:173], v[178:181], v[114:117]
	v_mfma_f32_16x16x32_bf16 v[102:105], v[162:165], v[186:189], v[102:105]
	v_mfma_f32_16x16x32_bf16 v[98:101], v[170:173], v[186:189], v[98:101]
	v_mfma_f32_16x16x32_bf16 v[86:89], v[162:165], v[194:197], v[86:89]
	v_mfma_f32_16x16x32_bf16 v[82:85], v[170:173], v[194:197], v[82:85]
	v_mfma_f32_16x16x32_bf16 v[70:73], v[162:165], v[202:205], v[70:73]
	v_mfma_f32_16x16x32_bf16 v[66:69], v[170:173], v[202:205], v[66:69]
	v_mfma_f32_16x16x32_bf16 v[118:121], v[166:169], v[182:185], v[118:121]
	v_mfma_f32_16x16x32_bf16 v[114:117], v[174:177], v[182:185], v[114:117]
	v_mfma_f32_16x16x32_bf16 v[102:105], v[166:169], v[190:193], v[102:105]
	v_mfma_f32_16x16x32_bf16 v[98:101], v[174:177], v[190:193], v[98:101]
	v_mfma_f32_16x16x32_bf16 v[86:89], v[166:169], v[198:201], v[86:89]
	v_mfma_f32_16x16x32_bf16 v[82:85], v[174:177], v[198:201], v[82:85]
	v_mfma_f32_16x16x32_bf16 v[70:73], v[166:169], v[224:227], v[70:73]
	v_mfma_f32_16x16x32_bf16 v[66:69], v[174:177], v[224:227], v[66:69]
	s_barrier
; #define PG8_STAGE(bufoff, gbase, voff) do { _Pragma("unroll") for (int _i = 0; _i < 2; ++_i) \
;         __builtin_amdgcn_global_load_lds((const unsigned*)((const char*)(gbase) + (voff)[_i]), (PG8_LAS unsigned*)(lds + (bufoff) + ldsw + _i * 8192), 16, 0, 0); } while (0)
; #define PG8_LDA(dst, b, h) do { _Pragma("unroll") for (int m = 0; m < 4; ++m) _Pragma("unroll") for (int k = 0; k < 2; ++k) dst[m][k] = *(const PG8_LAS bf16x8*)(lds + PG8_SA(b, h) + aoff + m * 2048 + k * 1024); } while (0)
; #define PG8_MMA(ai, bj, At, Bt) do { __builtin_amdgcn_s_setprio(1); _Pragma("unroll") for (int m = 0; m < 4; ++m) _Pragma("unroll") for (int n = 0; n < 2; ++n) _Pragma("unroll") for (int k = 0; k < 2; ++k) \
;         acc[ai][bj][m][n] = __builtin_amdgcn_mfma_f32_16x16x32_bf16(Bt[n][k], At[m][k], acc[ai][bj][m][n], 0, 0, 0); __builtin_amdgcn_s_setprio(0); } while (0)
; #define PG8_WAIT_V(n) asm volatile("s_waitcnt vmcnt(" #n ")" ::: "memory")
; #define PG8_WAIT_L(n) asm volatile("s_waitcnt lgkmcnt(" #n ")" ::: "memory")
; #define PG8_BAR __builtin_amdgcn_s_barrier()
; #define PG8_SCHED __builtin_amdgcn_sched_barrier(0)
; template <class Epi, class Sched, bool ALIGN_EPI = false, bool SP2 = false>
; __device__ __forceinline__ void gemm_phase(PG8_LAS unsigned char* lds, const Gemm g, const Sched& S, const Epi& E) {
;     ...
;             PG8_LDA(At, 1, 1); PG8_STAGE(PG8_SB(1, 0), b3, voffB); PG8_STAGE(PG8_SB(1, 1), b3 + hstep, voffB); PG8_STAGE(PG8_SA(1, 0), a3, voffA);
;             PG8_WAIT_V(8); PG8_WAIT_L(0); PG8_BAR; PG8_MMA(1, 0, At, B0); PG8_MMA(1, 1, At, B1); PG8_BAR; PG8_SCHED;
;     __device__ __forceinline__ void operator()(const f32x4 (&acc)[2][2][4][2], const Unit& u, int wr, int wc, int fr, int fq) const {
;         const int row0 = u.pm * 256 + wr * 64 + fr, col0 = u.pn * 256 + wc * 32 + 8 * fq;
; #pragma unroll
;         for (int ai = 0; ai < 2; ++ai)
; #pragma unroll
;             for (int m = 0; m < 4; ++m) {
;                 const int row = row0 + ai * 128 + m * 16;
; #pragma unroll
;                 for (int bj = 0; bj < 2; ++bj) {
;                     const int c = col0 + bj * 128;
;                     const u32x4 g = *(const u32x4*)(G + (size_t)row * P2W + c);
;                     const u32x4 t = *(const u32x4*)(T + (size_t)row * D + c);
	s_setprio 0
	s_add_i32 s10, s44, s20
	v_lshl_add_u64 v[148:149], v[148:149], 0, s[86:87]
	s_mov_b32 m0, s10
	ds_read_b128 v[178:181], v153 offset:49152
	ds_read_b128 v[182:185], v153 offset:50176
	ds_read_b128 v[186:189], v153 offset:51200
	ds_read_b128 v[190:193], v153 offset:52224
	ds_read_b128 v[194:197], v153 offset:53248
	ds_read_b128 v[198:201], v153 offset:54272
	ds_read_b128 v[202:205], v153 offset:55296
	ds_read_b128 v[224:227], v153 offset:56320
	global_load_lds_dwordx4 v[148:149], off
	s_add_i32 m0, s10, 0x2000
	s_add_u32 s10, s14, 0x50080
	v_lshl_add_u64 v[148:149], v[228:229], 0, s[86:87]
	s_addc_u32 s11, s15, 0
	s_add_i32 s14, s45, s20
	global_load_lds_dwordx4 v[148:149], off
	v_lshl_add_u64 v[148:149], s[10:11], 0, v[0:1]
	s_mov_b32 m0, s14
	s_nop 0
	global_load_lds_dwordx4 v[148:149], off
	v_lshl_add_u64 v[148:149], s[10:11], 0, v[134:135]
	s_add_i32 m0, s14, 0x2000
	s_nop 0
	global_load_lds_dwordx4 v[148:149], off
	v_lshl_add_u64 v[148:149], v[230:231], 0, s[86:87]
	s_mov_b32 m0, s27
	s_nop 0
	global_load_lds_dwordx4 v[148:149], off
	v_lshl_add_u64 v[148:149], v[232:233], 0, s[86:87]
	s_mov_b32 m0, s28
	s_nop 0
	global_load_lds_dwordx4 v[148:149], off
	s_waitcnt vmcnt(8)
	s_waitcnt lgkmcnt(0)
	v_mfma_f32_16x16x32_bf16 v[62:65], v[138:141], v[178:181], v[62:65]
	v_mfma_f32_16x16x32_bf16 v[58:61], v[154:157], v[178:181], v[58:61]
	s_setprio 1
	s_barrier
	v_mfma_f32_16x16x32_bf16 v[46:49], v[138:141], v[186:189], v[46:49]
	v_mfma_f32_16x16x32_bf16 v[42:45], v[154:157], v[186:189], v[42:45]
	v_mfma_f32_16x16x32_bf16 v[30:33], v[138:141], v[194:197], v[30:33]
	v_mfma_f32_16x16x32_bf16 v[26:29], v[154:157], v[194:197], v[26:29]
	v_mfma_f32_16x16x32_bf16 v[14:17], v[138:141], v[202:205], v[14:17]
	v_mfma_f32_16x16x32_bf16 v[10:13], v[154:157], v[202:205], v[10:13]
	v_mfma_f32_16x16x32_bf16 v[62:65], v[144:147], v[182:185], v[62:65]
	v_mfma_f32_16x16x32_bf16 v[58:61], v[158:161], v[182:185], v[58:61]
	v_mfma_f32_16x16x32_bf16 v[46:49], v[144:147], v[190:193], v[46:49]
	v_mfma_f32_16x16x32_bf16 v[42:45], v[158:161], v[190:193], v[42:45]
	v_mfma_f32_16x16x32_bf16 v[30:33], v[144:147], v[198:201], v[30:33]
	v_mfma_f32_16x16x32_bf16 v[26:29], v[158:161], v[198:201], v[26:29]
	v_mfma_f32_16x16x32_bf16 v[14:17], v[144:147], v[224:227], v[14:17]
	v_mfma_f32_16x16x32_bf16 v[10:13], v[158:161], v[224:227], v[10:13]
	v_mfma_f32_16x16x32_bf16 v[54:57], v[162:165], v[178:181], v[54:57]
	v_mfma_f32_16x16x32_bf16 v[50:53], v[170:173], v[178:181], v[50:53]
	v_mfma_f32_16x16x32_bf16 v[38:41], v[162:165], v[186:189], v[38:41]
	v_mfma_f32_16x16x32_bf16 v[34:37], v[170:173], v[186:189], v[34:37]
	v_mfma_f32_16x16x32_bf16 v[22:25], v[162:165], v[194:197], v[22:25]
	v_mfma_f32_16x16x32_bf16 v[18:21], v[170:173], v[194:197], v[18:21]
	v_mfma_f32_16x16x32_bf16 v[6:9], v[162:165], v[202:205], v[6:9]
	v_mfma_f32_16x16x32_bf16 v[2:5], v[170:173], v[202:205], v[2:5]
	v_mfma_f32_16x16x32_bf16 v[54:57], v[166:169], v[182:185], v[54:57]
	v_mfma_f32_16x16x32_bf16 v[50:53], v[174:177], v[182:185], v[50:53]
	v_mfma_f32_16x16x32_bf16 v[38:41], v[166:169], v[190:193], v[38:41]
	v_mfma_f32_16x16x32_bf16 v[34:37], v[174:177], v[190:193], v[34:37]
	v_mfma_f32_16x16x32_bf16 v[22:25], v[166:169], v[198:201], v[22:25]
	v_mfma_f32_16x16x32_bf16 v[18:21], v[174:177], v[198:201], v[18:21]
	v_mfma_f32_16x16x32_bf16 v[6:9], v[166:169], v[224:227], v[6:9]
	v_mfma_f32_16x16x32_bf16 v[2:5], v[174:177], v[224:227], v[2:5]
	s_barrier
	s_setprio 0
	s_add_i32 s43, s43, 2
	s_add_u32 s41, s41, 0x100
	s_addc_u32 s42, s42, 0
	s_cmp_gt_u32 s43, 17
	s_mov_b64 s[10:11], s[12:13]
	s_cbranch_scc0 .LBB0_919
	v_lshl_add_u32 v140, s38, 8, v150
	v_lshl_or_b32 v141, s39, 8, v152
	v_mul_lo_u32 v138, v140, s83
	v_lshlrev_b32_e32 v139, 11, v140
	v_lshl_add_u32 v138, v141, 1, v138
	v_lshl_add_u32 v139, v141, 1, v139
	global_load_dwordx4 v[144:147], v138, s[72:73]
	global_load_dwordx4 v[156:159], v139, s[36:37]
	global_load_dwordx4 v[160:163], v138, s[72:73] offset:256
	global_load_dwordx4 v[164:167], v139, s[36:37] offset:256
	v_add_u32_e32 v140, 0x1a000, v138
	v_add_u32_e32 v141, 0x8000, v139
	global_load_dwordx4 v[168:171], v140, s[72:73]
	global_load_dwordx4 v[172:175], v141, s[36:37]
	global_load_dwordx4 v[176:179], v140, s[72:73] offset:256
	global_load_dwordx4 v[180:183], v141, s[36:37] offset:256
	v_add_u32_e32 v140, 0x34000, v138
	v_add_u32_e32 v141, 0x10000, v139
	global_load_dwordx4 v[184:187], v140, s[72:73]
	global_load_dwordx4 v[188:191], v141, s[36:37]
	global_load_dwordx4 v[192:195], v140, s[72:73] offset:256
	global_load_dwordx4 v[196:199], v141, s[36:37] offset:256
	v_add_u32_e32 v140, 0x4e000, v138
	v_add_u32_e32 v141, 0x18000, v139
	global_load_dwordx4 v[200:203], v140, s[72:73]
	global_load_dwordx4 v[224:227], v141, s[36:37]
	global_load_dwordx4 v[228:231], v140, s[72:73] offset:256
	global_load_dwordx4 v[232:235], v141, s[36:37] offset:256
	s_and_b64 vcc, exec, s[6:7]
	s_cbranch_vccz .LBB0_922
	s_barrier

; #define PG8_STAGE(bufoff, gbase, voff) do { _Pragma("unroll") for (int _i = 0; _i < 2; ++_i) \
;         __builtin_amdgcn_global_load_lds((const unsigned*)((const char*)(gbase) + (voff)[_i]), (PG8_LAS unsigned*)(lds + (bufoff) + ldsw + _i * 8192), 16, 0, 0); } while (0)
; #define PG8_LDA(dst, b, h) do { _Pragma("unroll") for (int m = 0; m < 4; ++m) _Pragma("unroll") for (int k = 0; k < 2; ++k) dst[m][k] = *(const PG8_LAS bf16x8*)(lds + PG8_SA(b, h) + aoff + m * 2048 + k * 1024); } while (0)
; #define PG8_LDB(dst, b, h) do { _Pragma("unroll") for (int n = 0; n < 2; ++n) _Pragma("unroll") for (int k = 0; k < 2; ++k) dst[n][k] = *(const PG8_LAS bf16x8*)(lds + PG8_SB(b, h) + boff + n * 2048 + k * 1024); } while (0)
; #define PG8_MMA(ai, bj, At, Bt) do { __builtin_amdgcn_s_setprio(1); _Pragma("unroll") for (int m = 0; m < 4; ++m) _Pragma("unroll") for (int n = 0; n < 2; ++n) _Pragma("unroll") for (int k = 0; k < 2; ++k) \
;         acc[ai][bj][m][n] = __builtin_amdgcn_mfma_f32_16x16x32_bf16(Bt[n][k], At[m][k], acc[ai][bj][m][n], 0, 0, 0); __builtin_amdgcn_s_setprio(0); } while (0)
; #define PG8_WAIT_V(n) asm volatile("s_waitcnt vmcnt(" #n ")" ::: "memory")
; #define PG8_WAIT_L(n) asm volatile("s_waitcnt lgkmcnt(" #n ")" ::: "memory")
; #define PG8_BAR __builtin_amdgcn_s_barrier()
; #define PG8_SCHED __builtin_amdgcn_sched_barrier(0)
; template <class Epi, class Sched, bool ALIGN_EPI = false, bool SP2 = false>
; __device__ __forceinline__ void gemm_phase(PG8_LAS unsigned char* lds, const Gemm g, const Sched& S, const Epi& E) {
;     ...
;             PG8_LDB(B0, 0, 0); PG8_LDB(B1, 0, 1); PG8_SCHED; PG8_LDA(At, 0, 0); PG8_STAGE(PG8_SA(1, 1), a1 + hstep, voffA);
;             PG8_WAIT_V(8); PG8_WAIT_L(0); PG8_BAR; PG8_MMA(0, 0, At, B0); PG8_MMA(0, 1, At, B1); PG8_BAR; PG8_SCHED;
;             PG8_LDA(At, 0, 1); PG8_STAGE(PG8_SB(0, 0), b2, voffB); PG8_STAGE(PG8_SB(0, 1), b2 + hstep, voffB); PG8_STAGE(PG8_SA(0, 0), a2, voffA);
;             PG8_WAIT_V(8); PG8_WAIT_L(0); PG8_BAR; PG8_MMA(1, 0, At, B0); PG8_MMA(1, 1, At, B1); PG8_BAR; PG8_SCHED;
.LBB0_1050:
	s_add_u32 s24, s22, 0xfffc0080
	s_addc_u32 s25, s23, -1
	s_add_i32 s51, 0, 0x10000
	s_cmp_eq_u32 s50, 12
	s_cselect_b32 s27, s13, s25
	s_cselect_b32 s26, s19, s24
	s_cselect_b32 s25, s11, s49
	s_cselect_b32 s24, s21, s48
	s_add_i32 s55, 0, 0x14000
	v_add_u32_e32 v156, s51, v149
	v_add_u32_e32 v172, s55, v149
	ds_read_b128 v[138:141], v156
	ds_read_b128 v[144:147], v156 offset:1024
	ds_read_b128 v[152:155], v156 offset:2048
	ds_read_b128 v[156:159], v156 offset:3072
	ds_read_b128 v[160:163], v172
	ds_read_b128 v[164:167], v172 offset:1024
	ds_read_b128 v[168:171], v172 offset:2048
	ds_read_b128 v[172:175], v172 offset:3072
	v_lshl_add_u64 v[204:205], s[22:23], 0, v[136:137]
	s_add_i32 m0, s38, 0xc000
	ds_read_b128 v[176:179], v151
	ds_read_b128 v[180:183], v151 offset:1024
	ds_read_b128 v[184:187], v151 offset:2048
	ds_read_b128 v[188:191], v151 offset:3072
	ds_read_b128 v[192:195], v151 offset:4096
	ds_read_b128 v[196:199], v151 offset:5120
	ds_read_b128 v[200:203], v151 offset:6144
	ds_read_b128 v[224:227], v151 offset:7168
	global_load_lds_dwordx4 v[204:205], off
	v_lshl_add_u64 v[204:205], s[22:23], 0, v[142:143]
	s_add_i32 m0, s38, 0xe000
	s_nop 0
	global_load_lds_dwordx4 v[204:205], off
	s_waitcnt vmcnt(8)
	s_waitcnt lgkmcnt(0)
	v_mfma_f32_16x16x32_bf16 v[126:129], v[138:141], v[176:179], v[126:129]
	v_mfma_f32_16x16x32_bf16 v[122:125], v[152:155], v[176:179], v[122:125]
	s_setprio 1
	s_barrier
	v_mfma_f32_16x16x32_bf16 v[110:113], v[138:141], v[184:187], v[110:113]
	v_mfma_f32_16x16x32_bf16 v[106:109], v[152:155], v[184:187], v[106:109]
	v_mfma_f32_16x16x32_bf16 v[94:97], v[138:141], v[192:195], v[94:97]
	v_mfma_f32_16x16x32_bf16 v[90:93], v[152:155], v[192:195], v[90:93]
	v_mfma_f32_16x16x32_bf16 v[78:81], v[138:141], v[200:203], v[78:81]
	v_mfma_f32_16x16x32_bf16 v[74:77], v[152:155], v[200:203], v[74:77]
	v_mfma_f32_16x16x32_bf16 v[126:129], v[144:147], v[180:183], v[126:129]
	v_mfma_f32_16x16x32_bf16 v[122:125], v[156:159], v[180:183], v[122:125]
	v_mfma_f32_16x16x32_bf16 v[110:113], v[144:147], v[188:191], v[110:113]
	v_mfma_f32_16x16x32_bf16 v[106:109], v[156:159], v[188:191], v[106:109]
	v_mfma_f32_16x16x32_bf16 v[94:97], v[144:147], v[196:199], v[94:97]
	v_mfma_f32_16x16x32_bf16 v[90:93], v[156:159], v[196:199], v[90:93]
	v_mfma_f32_16x16x32_bf16 v[78:81], v[144:147], v[224:227], v[78:81]
	v_mfma_f32_16x16x32_bf16 v[74:77], v[156:159], v[224:227], v[74:77]
	v_mfma_f32_16x16x32_bf16 v[118:121], v[160:163], v[176:179], v[118:121]
	v_mfma_f32_16x16x32_bf16 v[114:117], v[168:171], v[176:179], v[114:117]
	v_mfma_f32_16x16x32_bf16 v[102:105], v[160:163], v[184:187], v[102:105]
	v_mfma_f32_16x16x32_bf16 v[98:101], v[168:171], v[184:187], v[98:101]
	v_mfma_f32_16x16x32_bf16 v[86:89], v[160:163], v[192:195], v[86:89]
	v_mfma_f32_16x16x32_bf16 v[82:85], v[168:171], v[192:195], v[82:85]
	v_mfma_f32_16x16x32_bf16 v[70:73], v[160:163], v[200:203], v[70:73]
	v_mfma_f32_16x16x32_bf16 v[66:69], v[168:171], v[200:203], v[66:69]
	v_mfma_f32_16x16x32_bf16 v[118:121], v[164:167], v[180:183], v[118:121]
	v_mfma_f32_16x16x32_bf16 v[114:117], v[172:175], v[180:183], v[114:117]
	v_mfma_f32_16x16x32_bf16 v[102:105], v[164:167], v[188:191], v[102:105]
	v_mfma_f32_16x16x32_bf16 v[98:101], v[172:175], v[188:191], v[98:101]
	v_mfma_f32_16x16x32_bf16 v[86:89], v[164:167], v[196:199], v[86:89]
	v_mfma_f32_16x16x32_bf16 v[82:85], v[172:175], v[196:199], v[82:85]
	v_mfma_f32_16x16x32_bf16 v[70:73], v[164:167], v[224:227], v[70:73]
	v_mfma_f32_16x16x32_bf16 v[66:69], v[172:175], v[224:227], v[66:69]
	s_barrier
	s_setprio 0
	s_add_i32 s51, s51, s31
	v_lshl_add_u64 v[204:205], s[24:25], 0, v[0:1]
	s_mov_b32 m0, s51
	ds_read_b128 v[176:179], v151 offset:16384
	ds_read_b128 v[180:183], v151 offset:17408
	ds_read_b128 v[184:187], v151 offset:18432
	ds_read_b128 v[188:191], v151 offset:19456
	ds_read_b128 v[192:195], v151 offset:20480
	ds_read_b128 v[196:199], v151 offset:21504
	ds_read_b128 v[200:203], v151 offset:22528
	ds_read_b128 v[224:227], v151 offset:23552
	global_load_lds_dwordx4 v[204:205], off
	s_add_i32 m0, s51, 0x2000
	s_add_u32 s52, s24, 0x40000
	v_lshl_add_u64 v[228:229], s[24:25], 0, v[134:135]
	s_addc_u32 s53, s25, 0
	s_add_i32 s51, s55, s31
	global_load_lds_dwordx4 v[228:229], off
	v_lshl_add_u64 v[230:231], s[52:53], 0, v[0:1]
	s_mov_b32 m0, s51
	v_lshl_add_u64 v[232:233], s[26:27], 0, v[132:133]
	global_load_lds_dwordx4 v[230:231], off
	v_lshl_add_u64 v[230:231], s[52:53], 0, v[134:135]
	s_add_i32 m0, s51, 0x2000
	s_nop 0
	global_load_lds_dwordx4 v[230:231], off
	v_lshl_add_u64 v[230:231], s[26:27], 0, v[130:131]
	s_mov_b32 m0, s38
	s_nop 0
	global_load_lds_dwordx4 v[230:231], off
	s_mov_b32 m0, s39
	s_nop 0
	global_load_lds_dwordx4 v[232:233], off
	s_waitcnt vmcnt(8)
	s_waitcnt lgkmcnt(0)
	v_mfma_f32_16x16x32_bf16 v[62:65], v[138:141], v[176:179], v[62:65]
	v_mfma_f32_16x16x32_bf16 v[58:61], v[152:155], v[176:179], v[58:61]
	s_setprio 1
	s_barrier
; #define PG8_STAGE(bufoff, gbase, voff) do { _Pragma("unroll") for (int _i = 0; _i < 2; ++_i) \
;         __builtin_amdgcn_global_load_lds((const unsigned*)((const char*)(gbase) + (voff)[_i]), (PG8_LAS unsigned*)(lds + (bufoff) + ldsw + _i * 8192), 16, 0, 0); } while (0)
; #define PG8_LDA(dst, b, h) do { _Pragma("unroll") for (int m = 0; m < 4; ++m) _Pragma("unroll") for (int k = 0; k < 2; ++k) dst[m][k] = *(const PG8_LAS bf16x8*)(lds + PG8_SA(b, h) + aoff + m * 2048 + k * 1024); } while (0)
; #define PG8_LDB(dst, b, h) do { _Pragma("unroll") for (int n = 0; n < 2; ++n) _Pragma("unroll") for (int k = 0; k < 2; ++k) dst[n][k] = *(const PG8_LAS bf16x8*)(lds + PG8_SB(b, h) + boff + n * 2048 + k * 1024); } while (0)
; #define PG8_MMA(ai, bj, At, Bt) do { __builtin_amdgcn_s_setprio(1); _Pragma("unroll") for (int m = 0; m < 4; ++m) _Pragma("unroll") for (int n = 0; n < 2; ++n) _Pragma("unroll") for (int k = 0; k < 2; ++k) \
;         acc[ai][bj][m][n] = __builtin_amdgcn_mfma_f32_16x16x32_bf16(Bt[n][k], At[m][k], acc[ai][bj][m][n], 0, 0, 0); __builtin_amdgcn_s_setprio(0); } while (0)
; #define PG8_WAIT_V(n) asm volatile("s_waitcnt vmcnt(" #n ")" ::: "memory")
; #define PG8_WAIT_L(n) asm volatile("s_waitcnt lgkmcnt(" #n ")" ::: "memory")
; #define PG8_BAR __builtin_amdgcn_s_barrier()
; #define PG8_SCHED __builtin_amdgcn_sched_barrier(0)
; template <class Epi, class Sched, bool ALIGN_EPI = false, bool SP2 = false>
; __device__ __forceinline__ void gemm_phase(PG8_LAS unsigned char* lds, const Gemm g, const Sched& S, const Epi& E) {
;     ...
;             PG8_WAIT_V(8); PG8_WAIT_L(0); PG8_BAR; PG8_MMA(1, 0, At, B0); PG8_MMA(1, 1, At, B1); PG8_BAR; PG8_SCHED;
;             PG8_LDB(B0, 1, 0); PG8_LDB(B1, 1, 1); PG8_SCHED; PG8_LDA(At, 1, 0); PG8_STAGE(PG8_SA(0, 1), a2 + hstep, voffA);
;             PG8_WAIT_V(8); PG8_WAIT_L(0); PG8_BAR; PG8_MMA(0, 0, At, B0); PG8_MMA(0, 1, At, B1); PG8_BAR; PG8_SCHED;
	v_mfma_f32_16x16x32_bf16 v[46:49], v[138:141], v[184:187], v[46:49]
	v_mfma_f32_16x16x32_bf16 v[42:45], v[152:155], v[184:187], v[42:45]
	v_mfma_f32_16x16x32_bf16 v[30:33], v[138:141], v[192:195], v[30:33]
	v_mfma_f32_16x16x32_bf16 v[26:29], v[152:155], v[192:195], v[26:29]
	v_mfma_f32_16x16x32_bf16 v[14:17], v[138:141], v[200:203], v[14:17]
	v_mfma_f32_16x16x32_bf16 v[10:13], v[152:155], v[200:203], v[10:13]
	v_mfma_f32_16x16x32_bf16 v[62:65], v[144:147], v[180:183], v[62:65]
	v_mfma_f32_16x16x32_bf16 v[58:61], v[156:159], v[180:183], v[58:61]
	v_mfma_f32_16x16x32_bf16 v[46:49], v[144:147], v[188:191], v[46:49]
	v_mfma_f32_16x16x32_bf16 v[42:45], v[156:159], v[188:191], v[42:45]
	v_mfma_f32_16x16x32_bf16 v[30:33], v[144:147], v[196:199], v[30:33]
	v_mfma_f32_16x16x32_bf16 v[26:29], v[156:159], v[196:199], v[26:29]
	v_mfma_f32_16x16x32_bf16 v[14:17], v[144:147], v[224:227], v[14:17]
	v_mfma_f32_16x16x32_bf16 v[10:13], v[156:159], v[224:227], v[10:13]
	v_mfma_f32_16x16x32_bf16 v[54:57], v[160:163], v[176:179], v[54:57]
	v_mfma_f32_16x16x32_bf16 v[50:53], v[168:171], v[176:179], v[50:53]
	v_mfma_f32_16x16x32_bf16 v[38:41], v[160:163], v[184:187], v[38:41]
	v_mfma_f32_16x16x32_bf16 v[34:37], v[168:171], v[184:187], v[34:37]
	v_mfma_f32_16x16x32_bf16 v[22:25], v[160:163], v[192:195], v[22:25]
	v_mfma_f32_16x16x32_bf16 v[18:21], v[168:171], v[192:195], v[18:21]
	v_mfma_f32_16x16x32_bf16 v[6:9], v[160:163], v[200:203], v[6:9]
	v_mfma_f32_16x16x32_bf16 v[2:5], v[168:171], v[200:203], v[2:5]
	v_mfma_f32_16x16x32_bf16 v[54:57], v[164:167], v[180:183], v[54:57]
	v_mfma_f32_16x16x32_bf16 v[50:53], v[172:175], v[180:183], v[50:53]
	v_mfma_f32_16x16x32_bf16 v[38:41], v[164:167], v[188:191], v[38:41]
	v_mfma_f32_16x16x32_bf16 v[34:37], v[172:175], v[188:191], v[34:37]
	v_mfma_f32_16x16x32_bf16 v[22:25], v[164:167], v[196:199], v[22:25]
	v_mfma_f32_16x16x32_bf16 v[18:21], v[172:175], v[196:199], v[18:21]
	v_mfma_f32_16x16x32_bf16 v[6:9], v[164:167], v[224:227], v[6:9]
	v_mfma_f32_16x16x32_bf16 v[2:5], v[172:175], v[224:227], v[2:5]
	s_barrier
	s_setprio 0
	s_add_i32 s51, 0, 0x18000
	s_add_i32 s52, 0, 0x1c000
	v_add_u32_e32 v156, s51, v149
	v_add_u32_e32 v172, s52, v149
	ds_read_b128 v[138:141], v156
	ds_read_b128 v[144:147], v156 offset:1024
	ds_read_b128 v[152:155], v156 offset:2048
	ds_read_b128 v[156:159], v156 offset:3072
	ds_read_b128 v[160:163], v172
	ds_read_b128 v[164:167], v172 offset:1024
	ds_read_b128 v[168:171], v172 offset:2048
	ds_read_b128 v[172:175], v172 offset:3072
	s_add_u32 s26, s26, 0x40000
	s_addc_u32 s27, s27, 0
	s_mov_b32 m0, s41
	v_lshl_add_u64 v[234:235], s[26:27], 0, v[130:131]
	ds_read_b128 v[176:179], v151 offset:32768
	ds_read_b128 v[180:183], v151 offset:33792
	ds_read_b128 v[184:187], v151 offset:34816
	ds_read_b128 v[188:191], v151 offset:35840
	ds_read_b128 v[192:195], v151 offset:36864
	ds_read_b128 v[196:199], v151 offset:37888
	ds_read_b128 v[200:203], v151 offset:38912
	ds_read_b128 v[224:227], v151 offset:39936
	global_load_lds_dwordx4 v[234:235], off
	v_lshl_add_u64 v[234:235], s[26:27], 0, v[132:133]
	s_mov_b32 m0, s42
	s_nop 0
	global_load_lds_dwordx4 v[234:235], off
	s_waitcnt vmcnt(8)
	s_waitcnt lgkmcnt(0)
	v_mfma_f32_16x16x32_bf16 v[126:129], v[138:141], v[176:179], v[126:129]
	v_mfma_f32_16x16x32_bf16 v[122:125], v[152:155], v[176:179], v[122:125]
	s_setprio 1
	s_barrier
	v_mfma_f32_16x16x32_bf16 v[110:113], v[138:141], v[184:187], v[110:113]
	v_mfma_f32_16x16x32_bf16 v[106:109], v[152:155], v[184:187], v[106:109]
	v_mfma_f32_16x16x32_bf16 v[94:97], v[138:141], v[192:195], v[94:97]
	v_mfma_f32_16x16x32_bf16 v[90:93], v[152:155], v[192:195], v[90:93]
	v_mfma_f32_16x16x32_bf16 v[78:81], v[138:141], v[200:203], v[78:81]
	v_mfma_f32_16x16x32_bf16 v[74:77], v[152:155], v[200:203], v[74:77]
	v_mfma_f32_16x16x32_bf16 v[126:129], v[144:147], v[180:183], v[126:129]
	v_mfma_f32_16x16x32_bf16 v[122:125], v[156:159], v[180:183], v[122:125]
	v_mfma_f32_16x16x32_bf16 v[110:113], v[144:147], v[188:191], v[110:113]
	v_mfma_f32_16x16x32_bf16 v[106:109], v[156:159], v[188:191], v[106:109]
	v_mfma_f32_16x16x32_bf16 v[94:97], v[144:147], v[196:199], v[94:97]
	v_mfma_f32_16x16x32_bf16 v[90:93], v[156:159], v[196:199], v[90:93]
	v_mfma_f32_16x16x32_bf16 v[78:81], v[144:147], v[224:227], v[78:81]
	v_mfma_f32_16x16x32_bf16 v[74:77], v[156:159], v[224:227], v[74:77]
	v_mfma_f32_16x16x32_bf16 v[118:121], v[160:163], v[176:179], v[118:121]
	v_mfma_f32_16x16x32_bf16 v[114:117], v[168:171], v[176:179], v[114:117]
	v_mfma_f32_16x16x32_bf16 v[102:105], v[160:163], v[184:187], v[102:105]
	v_mfma_f32_16x16x32_bf16 v[98:101], v[168:171], v[184:187], v[98:101]
	v_mfma_f32_16x16x32_bf16 v[86:89], v[160:163], v[192:195], v[86:89]
	v_mfma_f32_16x16x32_bf16 v[82:85], v[168:171], v[192:195], v[82:85]
	v_mfma_f32_16x16x32_bf16 v[70:73], v[160:163], v[200:203], v[70:73]
	v_mfma_f32_16x16x32_bf16 v[66:69], v[168:171], v[200:203], v[66:69]
	v_mfma_f32_16x16x32_bf16 v[118:121], v[164:167], v[180:183], v[118:121]
	v_mfma_f32_16x16x32_bf16 v[114:117], v[172:175], v[180:183], v[114:117]
	v_mfma_f32_16x16x32_bf16 v[102:105], v[164:167], v[188:191], v[102:105]
	v_mfma_f32_16x16x32_bf16 v[98:101], v[172:175], v[188:191], v[98:101]
	v_mfma_f32_16x16x32_bf16 v[86:89], v[164:167], v[196:199], v[86:89]
	v_mfma_f32_16x16x32_bf16 v[82:85], v[172:175], v[196:199], v[82:85]
	v_mfma_f32_16x16x32_bf16 v[70:73], v[164:167], v[224:227], v[70:73]
	v_mfma_f32_16x16x32_bf16 v[66:69], v[172:175], v[224:227], v[66:69]
	s_barrier
; #define PG8_STAGE(bufoff, gbase, voff) do { _Pragma("unroll") for (int _i = 0; _i < 2; ++_i) \
;         __builtin_amdgcn_global_load_lds((const unsigned*)((const char*)(gbase) + (voff)[_i]), (PG8_LAS unsigned*)(lds + (bufoff) + ldsw + _i * 8192), 16, 0, 0); } while (0)
; #define PG8_LDA(dst, b, h) do { _Pragma("unroll") for (int m = 0; m < 4; ++m) _Pragma("unroll") for (int k = 0; k < 2; ++k) dst[m][k] = *(const PG8_LAS bf16x8*)(lds + PG8_SA(b, h) + aoff + m * 2048 + k * 1024); } while (0)
; #define PG8_MMA(ai, bj, At, Bt) do { __builtin_amdgcn_s_setprio(1); _Pragma("unroll") for (int m = 0; m < 4; ++m) _Pragma("unroll") for (int n = 0; n < 2; ++n) _Pragma("unroll") for (int k = 0; k < 2; ++k) \
;         acc[ai][bj][m][n] = __builtin_amdgcn_mfma_f32_16x16x32_bf16(Bt[n][k], At[m][k], acc[ai][bj][m][n], 0, 0, 0); __builtin_amdgcn_s_setprio(0); } while (0)
; #define PG8_WAIT_V(n) asm volatile("s_waitcnt vmcnt(" #n ")" ::: "memory")
; #define PG8_WAIT_L(n) asm volatile("s_waitcnt lgkmcnt(" #n ")" ::: "memory")
; #define PG8_BAR __builtin_amdgcn_s_barrier()
; #define PG8_SCHED __builtin_amdgcn_sched_barrier(0)
; template <class Epi, class Sched, bool ALIGN_EPI = false, bool SP2 = false>
; __device__ __forceinline__ void gemm_phase(PG8_LAS unsigned char* lds, const Gemm g, const Sched& S, const Epi& E) {
;     ...
;             PG8_LDA(At, 1, 1); PG8_STAGE(PG8_SB(1, 0), b3, voffB); PG8_STAGE(PG8_SB(1, 1), b3 + hstep, voffB); PG8_STAGE(PG8_SA(1, 0), a3, voffA);
;             PG8_WAIT_V(8); PG8_WAIT_L(0); PG8_BAR; PG8_MMA(1, 0, At, B0); PG8_MMA(1, 1, At, B1); PG8_BAR; PG8_SCHED;
;     __device__ __forceinline__ void operator()(const f32x4 (&acc)[2][2][4][2], const Unit& u, int wr, int wc, int fr, int fq) const {
;         const int row0 = u.pm * 256 + wr * 64 + fr, col0 = u.pn * 256 + wc * 32 + 8 * fq;
; #pragma unroll
;         for (int ai = 0; ai < 2; ++ai)
; #pragma unroll
;             for (int m = 0; m < 4; ++m) {
;                 const int row = row0 + ai * 128 + m * 16; float p = 0.f;
; #pragma unroll
;                 for (int bj = 0; bj < 2; ++bj) {
;                     const size_t off = (size_t)row * D + col0 + bj * 128;
;                     const u32x4 xx = *(const u32x4*)(xb + off);
	s_setprio 0
	s_add_i32 s26, s51, s31
	v_lshl_add_u64 v[204:205], v[204:205], 0, s[86:87]
	s_mov_b32 m0, s26
	ds_read_b128 v[176:179], v151 offset:49152
	ds_read_b128 v[180:183], v151 offset:50176
	ds_read_b128 v[184:187], v151 offset:51200
	ds_read_b128 v[188:191], v151 offset:52224
	ds_read_b128 v[192:195], v151 offset:53248
	ds_read_b128 v[196:199], v151 offset:54272
	ds_read_b128 v[200:203], v151 offset:55296
	ds_read_b128 v[224:227], v151 offset:56320
	global_load_lds_dwordx4 v[204:205], off
	s_add_i32 m0, s26, 0x2000
	s_add_u32 s24, s24, 0x40080
	v_lshl_add_u64 v[204:205], v[228:229], 0, s[86:87]
	s_addc_u32 s25, s25, 0
	s_add_i32 s26, s52, s31
	global_load_lds_dwordx4 v[204:205], off
	v_lshl_add_u64 v[204:205], s[24:25], 0, v[0:1]
	s_mov_b32 m0, s26
	s_nop 0
	global_load_lds_dwordx4 v[204:205], off
	v_lshl_add_u64 v[204:205], s[24:25], 0, v[134:135]
	s_add_i32 m0, s26, 0x2000
	s_nop 0
	global_load_lds_dwordx4 v[204:205], off
	v_lshl_add_u64 v[204:205], v[230:231], 0, s[86:87]
	s_mov_b32 m0, s44
	s_nop 0
	global_load_lds_dwordx4 v[204:205], off
	v_lshl_add_u64 v[204:205], v[232:233], 0, s[86:87]
	s_mov_b32 m0, s45
	s_nop 0
	global_load_lds_dwordx4 v[204:205], off
	s_waitcnt vmcnt(8)
	s_waitcnt lgkmcnt(0)
	v_mfma_f32_16x16x32_bf16 v[62:65], v[138:141], v[176:179], v[62:65]
	v_mfma_f32_16x16x32_bf16 v[58:61], v[152:155], v[176:179], v[58:61]
	s_setprio 1
	s_barrier
	v_mfma_f32_16x16x32_bf16 v[46:49], v[138:141], v[184:187], v[46:49]
	v_mfma_f32_16x16x32_bf16 v[42:45], v[152:155], v[184:187], v[42:45]
	v_mfma_f32_16x16x32_bf16 v[30:33], v[138:141], v[192:195], v[30:33]
	v_mfma_f32_16x16x32_bf16 v[26:29], v[152:155], v[192:195], v[26:29]
	v_mfma_f32_16x16x32_bf16 v[14:17], v[138:141], v[200:203], v[14:17]
	v_mfma_f32_16x16x32_bf16 v[10:13], v[152:155], v[200:203], v[10:13]
	v_mfma_f32_16x16x32_bf16 v[62:65], v[144:147], v[180:183], v[62:65]
	v_mfma_f32_16x16x32_bf16 v[58:61], v[156:159], v[180:183], v[58:61]
	v_mfma_f32_16x16x32_bf16 v[46:49], v[144:147], v[188:191], v[46:49]
	v_mfma_f32_16x16x32_bf16 v[42:45], v[156:159], v[188:191], v[42:45]
	v_mfma_f32_16x16x32_bf16 v[30:33], v[144:147], v[196:199], v[30:33]
	v_mfma_f32_16x16x32_bf16 v[26:29], v[156:159], v[196:199], v[26:29]
	v_mfma_f32_16x16x32_bf16 v[14:17], v[144:147], v[224:227], v[14:17]
	v_mfma_f32_16x16x32_bf16 v[10:13], v[156:159], v[224:227], v[10:13]
	v_mfma_f32_16x16x32_bf16 v[54:57], v[160:163], v[176:179], v[54:57]
	v_mfma_f32_16x16x32_bf16 v[50:53], v[168:171], v[176:179], v[50:53]
	v_mfma_f32_16x16x32_bf16 v[38:41], v[160:163], v[184:187], v[38:41]
	v_mfma_f32_16x16x32_bf16 v[34:37], v[168:171], v[184:187], v[34:37]
	v_mfma_f32_16x16x32_bf16 v[22:25], v[160:163], v[192:195], v[22:25]
	v_mfma_f32_16x16x32_bf16 v[18:21], v[168:171], v[192:195], v[18:21]
	v_mfma_f32_16x16x32_bf16 v[6:9], v[160:163], v[200:203], v[6:9]
	v_mfma_f32_16x16x32_bf16 v[2:5], v[168:171], v[200:203], v[2:5]
	v_mfma_f32_16x16x32_bf16 v[54:57], v[164:167], v[180:183], v[54:57]
	v_mfma_f32_16x16x32_bf16 v[50:53], v[172:175], v[180:183], v[50:53]
	v_mfma_f32_16x16x32_bf16 v[38:41], v[164:167], v[188:191], v[38:41]
	v_mfma_f32_16x16x32_bf16 v[34:37], v[172:175], v[188:191], v[34:37]
	v_mfma_f32_16x16x32_bf16 v[22:25], v[164:167], v[196:199], v[22:25]
	v_mfma_f32_16x16x32_bf16 v[18:21], v[172:175], v[196:199], v[18:21]
	v_mfma_f32_16x16x32_bf16 v[6:9], v[164:167], v[224:227], v[6:9]
	v_mfma_f32_16x16x32_bf16 v[2:5], v[172:175], v[224:227], v[2:5]
	s_barrier
	s_setprio 0
	s_add_i32 s50, s50, 2
	s_add_u32 s22, s22, 0x100
	s_addc_u32 s23, s23, 0
	s_add_u32 s48, s48, 0x100
	s_addc_u32 s49, s49, 0
	s_cmp_gt_u32 s50, 13
	s_cbranch_scc0 .LBB0_1050
	v_lshl_add_u32 v138, s20, 8, v148
	v_lshl_or_b32 v139, s18, 8, v150
	v_lshlrev_b32_e32 v138, 11, v138
	v_lshl_add_u32 v138, v139, 1, v138
	global_load_dwordx4 v[152:155], v138, s[34:35]
	global_load_dwordx4 v[156:159], v138, s[34:35] offset:256
	v_add_u32_e32 v139, 0x8000, v138
	global_load_dwordx4 v[160:163], v139, s[34:35]
	global_load_dwordx4 v[164:167], v139, s[34:35] offset:256
	v_add_u32_e32 v139, 0x10000, v138
	global_load_dwordx4 v[168:171], v139, s[34:35]
	global_load_dwordx4 v[172:175], v139, s[34:35] offset:256
	v_add_u32_e32 v139, 0x18000, v138
	global_load_dwordx4 v[176:179], v139, s[34:35]
	global_load_dwordx4 v[180:183], v139, s[34:35] offset:256
	v_add_u32_e32 v139, 0x40000, v138
	global_load_dwordx4 v[184:187], v139, s[34:35]
	global_load_dwordx4 v[188:191], v139, s[34:35] offset:256
	v_add_u32_e32 v139, 0x48000, v138
	global_load_dwordx4 v[192:195], v139, s[34:35]
	global_load_dwordx4 v[196:199], v139, s[34:35] offset:256
	v_add_u32_e32 v139, 0x50000, v138
	global_load_dwordx4 v[200:203], v139, s[34:35]
	global_load_dwordx4 v[224:227], v139, s[34:35] offset:256
	v_add_u32_e32 v139, 0x58000, v138
	global_load_dwordx4 v[228:231], v139, s[34:35]
	global_load_dwordx4 v[232:235], v139, s[34:35] offset:256
	s_and_b64 vcc, exec, s[8:9]
	s_cbranch_vccz .LBB0_1053
	s_barrier
